# redundant s_waitcnt lgkmcnt(0) at the head of each 32-MFMA segment (right after the barrier, counter already 0) deleted in all GEMM K-loops
# speedup vs baseline: 1.0086x; 1.0086x over previous
; #define PG8_STAGE(bufoff, gbase, voff) do { _Pragma("unroll") for (int _i = 0; _i < 2; ++_i) \
;         __builtin_amdgcn_global_load_lds((const unsigned*)((const char*)(gbase) + (voff)[_i]), (PG8_LAS unsigned*)(lds + (bufoff) + ldsw + _i * 8192), 16, 0, 0); } while (0)
; #define PG8_LDA(dst, b, h) do { _Pragma("unroll") for (int m = 0; m < 4; ++m) _Pragma("unroll") for (int k = 0; k < 2; ++k) dst[m][k] = *(const PG8_LAS bf16x8*)(lds + PG8_SA(b, h) + aoff + m * 2048 + k * 1024); } while (0)
; #define PG8_LDB(dst, b, h) do { _Pragma("unroll") for (int n = 0; n < 2; ++n) _Pragma("unroll") for (int k = 0; k < 2; ++k) dst[n][k] = *(const PG8_LAS bf16x8*)(lds + PG8_SB(b, h) + boff + n * 2048 + k * 1024); } while (0)
; #define PG8_WAIT_V(n) asm volatile("s_waitcnt vmcnt(" #n ")" ::: "memory")
; #define PG8_WAIT_L(n) asm volatile("s_waitcnt lgkmcnt(" #n ")" ::: "memory")
; #define PG8_BAR __builtin_amdgcn_s_barrier()
; #define PG8_SCHED __builtin_amdgcn_sched_barrier(0)
; template <class Epi, class Sched, bool ALIGN_EPI = false, bool SP2 = false>
; __device__ __forceinline__ void gemm_phase(PG8_LAS unsigned char* lds, const Gemm g, const Sched& S, const Epi& E) {
;     ...
;         const bool has_next = S.next(ui + 1, nxt);
;         const char* nA = has_next ? (const char*)g.A + (size_t)nxt.pm * tstep : cA; const char* nB = has_next ? (const char*)g.Bt + (size_t)nxt.pn * tstep : cB;
;         for (int t = 0; t < nt; t += 2) {
;             const bool last = (t == nt - 2);
;             const char* a1 = cA + (size_t)(t + 1) * kstep;
;             const char* a2 = last ? nA : cA + (size_t)(t + 2) * kstep; const char* b2 = last ? nB : cB + (size_t)(t + 2) * kstep;
;             const char* a3 = a2 + kstep; const char* b3 = b2 + kstep;
;             if (last && has_next) S.a_ready(nxt);
;             if constexpr (SP2) {
;             PG8_LDB(B0, 0, 0); PG8_LDB(B1, 0, 1); PG8_SCHED; PG8_LDA(At, 0, 0); PG8_STAGE(PG8_SA(1, 1), a1 + hstep, voffA);
;             PG8_WAIT_V(8); PG8_WAIT_L(0); PG8_BAR; PG8_MMA(0, 0, At, B0); PG8_MMA(0, 1, At, B1); PG8_BAR; PG8_SCHED;
;             PG8_LDA(At, 0, 1); PG8_STAGE(PG8_SB(0, 0), b2, voffB); PG8_STAGE(PG8_SB(0, 1), b2 + hstep, voffB); PG8_STAGE(PG8_SA(0, 0), a2, voffA);
;             PG8_WAIT_V(8); PG8_WAIT_L(0); PG8_BAR; PG8_MMA(1, 0, At, B0); PG8_MMA(1, 1, At, B1); PG8_BAR; PG8_SCHED;
.LBB0_43:
	s_ashr_i32 s47, s46, 31
	s_lshl_b64 s[24:25], s[46:47], 19
	s_add_u32 s48, s26, s24
	s_addc_u32 s49, s27, s25
	s_and_b64 s[24:25], s[40:41], exec
	s_cselect_b32 s1, s49, s61
	s_cselect_b32 s12, s48, s60
	s_ashr_i32 s3, s2, 31
	s_lshl_b64 s[24:25], s[2:3], 19
	s_add_u32 s56, s23, s24
	s_addc_u32 s57, s29, s25
	s_and_b64 s[24:25], s[40:41], exec
	s_cselect_b32 s3, s57, s63
	s_cselect_b32 s22, s56, s62
	s_add_u32 s60, s60, 0x40080
	s_addc_u32 s61, s61, 0
	s_add_u32 s33, s62, 0x100
	s_addc_u32 s44, s63, 0
	s_mov_b32 s45, -2
	s_add_u32 s24, s60, 0xfffc0080
	s_addc_u32 s25, s61, -1
	s_add_i32 s47, 0, 0x10000
	s_cmp_eq_u32 s45, 12
	s_cselect_b32 s65, s1, s25
	s_cselect_b32 s64, s12, s24
	v_add_u32_e32 v150, s47, v153
	s_cselect_b32 s63, s3, s44
	s_cselect_b32 s62, s22, s33
	s_add_i32 s50, 0, 0x14000
	ds_read_b128 v[146:149], v150
	ds_read_b128 v[156:159], v150 offset:1024
	ds_read_b128 v[160:163], v150 offset:2048
	ds_read_b128 v[164:167], v150 offset:3072
	v_add_u32_e32 v150, s50, v153
	ds_read_b128 v[168:171], v150
	ds_read_b128 v[192:195], v150 offset:1024
	ds_read_b128 v[196:199], v150 offset:2048
	ds_read_b128 v[200:203], v150 offset:3072
	v_lshl_add_u64 v[150:151], s[60:61], 0, v[142:143]
	s_add_i32 m0, s68, 0xc000
	ds_read_b128 v[204:207], v155
	ds_read_b128 v[208:211], v155 offset:1024
	ds_read_b128 v[212:215], v155 offset:2048
	ds_read_b128 v[216:219], v155 offset:3072
	ds_read_b128 v[220:223], v155 offset:4096
	ds_read_b128 v[224:227], v155 offset:5120
	ds_read_b128 v[228:231], v155 offset:6144
	ds_read_b128 v[232:235], v155 offset:7168
	global_load_lds_dwordx4 v[150:151], off
	v_lshl_add_u64 v[150:151], s[60:61], 0, v[144:145]
	s_add_i32 m0, s68, 0xe000
	s_nop 0
	global_load_lds_dwordx4 v[150:151], off
	s_waitcnt vmcnt(10)
	s_waitcnt lgkmcnt(0)
	s_barrier
	s_setprio 1
	v_mfma_f32_16x16x32_bf16 v[124:127], v[146:149], v[204:207], 0
	v_mfma_f32_16x16x32_bf16 v[120:123], v[160:163], v[204:207], 0
	v_mfma_f32_16x16x32_bf16 v[108:111], v[146:149], v[212:215], 0
	v_mfma_f32_16x16x32_bf16 v[104:107], v[160:163], v[212:215], 0
	v_mfma_f32_16x16x32_bf16 v[92:95], v[146:149], v[220:223], 0
	v_mfma_f32_16x16x32_bf16 v[88:91], v[160:163], v[220:223], 0
	v_mfma_f32_16x16x32_bf16 v[76:79], v[146:149], v[228:231], 0
	v_mfma_f32_16x16x32_bf16 v[72:75], v[160:163], v[228:231], 0
	v_mfma_f32_16x16x32_bf16 v[124:127], v[156:159], v[208:211], v[124:127]
	v_mfma_f32_16x16x32_bf16 v[120:123], v[164:167], v[208:211], v[120:123]
	v_mfma_f32_16x16x32_bf16 v[108:111], v[156:159], v[216:219], v[108:111]
	v_mfma_f32_16x16x32_bf16 v[104:107], v[164:167], v[216:219], v[104:107]
	v_mfma_f32_16x16x32_bf16 v[92:95], v[156:159], v[224:227], v[92:95]
	v_mfma_f32_16x16x32_bf16 v[88:91], v[164:167], v[224:227], v[88:91]
	v_mfma_f32_16x16x32_bf16 v[76:79], v[156:159], v[232:235], v[76:79]
	v_mfma_f32_16x16x32_bf16 v[72:75], v[164:167], v[232:235], v[72:75]
	v_mfma_f32_16x16x32_bf16 v[116:119], v[168:171], v[204:207], 0
	v_mfma_f32_16x16x32_bf16 v[112:115], v[196:199], v[204:207], 0
	v_mfma_f32_16x16x32_bf16 v[100:103], v[168:171], v[212:215], 0
	v_mfma_f32_16x16x32_bf16 v[96:99], v[196:199], v[212:215], 0
	v_mfma_f32_16x16x32_bf16 v[84:87], v[168:171], v[220:223], 0
	v_mfma_f32_16x16x32_bf16 v[80:83], v[196:199], v[220:223], 0
	v_mfma_f32_16x16x32_bf16 v[68:71], v[168:171], v[228:231], 0
	v_mfma_f32_16x16x32_bf16 v[64:67], v[196:199], v[228:231], 0
	v_mfma_f32_16x16x32_bf16 v[116:119], v[192:195], v[208:211], v[116:119]
	v_mfma_f32_16x16x32_bf16 v[112:115], v[200:203], v[208:211], v[112:115]
	v_mfma_f32_16x16x32_bf16 v[100:103], v[192:195], v[216:219], v[100:103]
	v_mfma_f32_16x16x32_bf16 v[96:99], v[200:203], v[216:219], v[96:99]
	v_mfma_f32_16x16x32_bf16 v[84:87], v[192:195], v[224:227], v[84:87]
	v_mfma_f32_16x16x32_bf16 v[80:83], v[200:203], v[224:227], v[80:83]
	v_mfma_f32_16x16x32_bf16 v[68:71], v[192:195], v[232:235], v[68:71]
	v_mfma_f32_16x16x32_bf16 v[64:67], v[200:203], v[232:235], v[64:67]
	s_setprio 0
	s_barrier
	s_add_i32 s24, s47, s66
	v_lshl_add_u64 v[150:151], s[62:63], 0, v[132:133]
	s_mov_b32 m0, s24
	ds_read_b128 v[204:207], v155 offset:16384
	ds_read_b128 v[208:211], v155 offset:17408
	ds_read_b128 v[212:215], v155 offset:18432
	ds_read_b128 v[216:219], v155 offset:19456
	ds_read_b128 v[220:223], v155 offset:20480
	ds_read_b128 v[224:227], v155 offset:21504
	ds_read_b128 v[228:231], v155 offset:22528
	ds_read_b128 v[232:235], v155 offset:23552
	global_load_lds_dwordx4 v[150:151], off
	s_add_i32 m0, s24, 0x2000
	s_add_u32 s24, s62, 0x40000
	v_lshl_add_u64 v[236:237], s[62:63], 0, v[128:129]
	s_addc_u32 s25, s63, 0
	s_add_i32 s47, s50, s66
	global_load_lds_dwordx4 v[236:237], off
	v_lshl_add_u64 v[238:239], s[24:25], 0, v[132:133]
	s_mov_b32 m0, s47
	v_lshl_add_u64 v[240:241], s[64:65], 0, v[130:131]
	global_load_lds_dwordx4 v[238:239], off
	v_lshl_add_u64 v[238:239], s[24:25], 0, v[128:129]
	s_add_i32 m0, s47, 0x2000
	s_nop 0
	global_load_lds_dwordx4 v[238:239], off
	v_lshl_add_u64 v[238:239], s[64:65], 0, v[140:141]
	s_mov_b32 m0, s68
	s_nop 0
	global_load_lds_dwordx4 v[238:239], off
	s_mov_b32 m0, s69
	s_nop 0
	global_load_lds_dwordx4 v[240:241], off
	s_waitcnt vmcnt(16)
	s_waitcnt lgkmcnt(0)
	s_barrier
; #define PG8_STAGE(bufoff, gbase, voff) do { _Pragma("unroll") for (int _i = 0; _i < 2; ++_i) \
;         __builtin_amdgcn_global_load_lds((const unsigned*)((const char*)(gbase) + (voff)[_i]), (PG8_LAS unsigned*)(lds + (bufoff) + ldsw + _i * 8192), 16, 0, 0); } while (0)
; #define PG8_LDA(dst, b, h) do { _Pragma("unroll") for (int m = 0; m < 4; ++m) _Pragma("unroll") for (int k = 0; k < 2; ++k) dst[m][k] = *(const PG8_LAS bf16x8*)(lds + PG8_SA(b, h) + aoff + m * 2048 + k * 1024); } while (0)
; #define PG8_LDB(dst, b, h) do { _Pragma("unroll") for (int n = 0; n < 2; ++n) _Pragma("unroll") for (int k = 0; k < 2; ++k) dst[n][k] = *(const PG8_LAS bf16x8*)(lds + PG8_SB(b, h) + boff + n * 2048 + k * 1024); } while (0)
; #define PG8_MMA(ai, bj, At, Bt) do { __builtin_amdgcn_s_setprio(1); _Pragma("unroll") for (int m = 0; m < 4; ++m) _Pragma("unroll") for (int n = 0; n < 2; ++n) _Pragma("unroll") for (int k = 0; k < 2; ++k) \
;         acc[ai][bj][m][n] = __builtin_amdgcn_mfma_f32_16x16x32_bf16(Bt[n][k], At[m][k], acc[ai][bj][m][n], 0, 0, 0); __builtin_amdgcn_s_setprio(0); } while (0)
; #define PG8_WAIT_V(n) asm volatile("s_waitcnt vmcnt(" #n ")" ::: "memory")
; #define PG8_WAIT_L(n) asm volatile("s_waitcnt lgkmcnt(" #n ")" ::: "memory")
; #define PG8_BAR __builtin_amdgcn_s_barrier()
; #define PG8_SCHED __builtin_amdgcn_sched_barrier(0)
; template <class Epi, class Sched, bool ALIGN_EPI = false, bool SP2 = false>
; __device__ __forceinline__ void gemm_phase(PG8_LAS unsigned char* lds, const Gemm g, const Sched& S, const Epi& E) {
;     ...
;             PG8_WAIT_V(8); PG8_WAIT_L(0); PG8_BAR; PG8_MMA(1, 0, At, B0); PG8_MMA(1, 1, At, B1); PG8_BAR; PG8_SCHED;
;             PG8_LDB(B0, 1, 0); PG8_LDB(B1, 1, 1); PG8_SCHED; PG8_LDA(At, 1, 0); PG8_STAGE(PG8_SA(0, 1), a2 + hstep, voffA);
;             PG8_WAIT_V(8); PG8_WAIT_L(0); PG8_BAR; PG8_MMA(0, 0, At, B0); PG8_MMA(0, 1, At, B1); PG8_BAR; PG8_SCHED;
	s_setprio 1
	v_mfma_f32_16x16x32_bf16 v[60:63], v[146:149], v[204:207], 0
	v_mfma_f32_16x16x32_bf16 v[56:59], v[160:163], v[204:207], 0
	v_mfma_f32_16x16x32_bf16 v[44:47], v[146:149], v[212:215], 0
	v_mfma_f32_16x16x32_bf16 v[40:43], v[160:163], v[212:215], 0
	v_mfma_f32_16x16x32_bf16 v[28:31], v[146:149], v[220:223], 0
	v_mfma_f32_16x16x32_bf16 v[24:27], v[160:163], v[220:223], 0
	v_mfma_f32_16x16x32_bf16 v[12:15], v[146:149], v[228:231], 0
	v_mfma_f32_16x16x32_bf16 v[8:11], v[160:163], v[228:231], 0
	v_mfma_f32_16x16x32_bf16 v[60:63], v[156:159], v[208:211], v[60:63]
	v_mfma_f32_16x16x32_bf16 v[56:59], v[164:167], v[208:211], v[56:59]
	v_mfma_f32_16x16x32_bf16 v[44:47], v[156:159], v[216:219], v[44:47]
	v_mfma_f32_16x16x32_bf16 v[40:43], v[164:167], v[216:219], v[40:43]
	v_mfma_f32_16x16x32_bf16 v[28:31], v[156:159], v[224:227], v[28:31]
	v_mfma_f32_16x16x32_bf16 v[24:27], v[164:167], v[224:227], v[24:27]
	v_mfma_f32_16x16x32_bf16 v[12:15], v[156:159], v[232:235], v[12:15]
	v_mfma_f32_16x16x32_bf16 v[8:11], v[164:167], v[232:235], v[8:11]
	v_mfma_f32_16x16x32_bf16 v[52:55], v[168:171], v[204:207], 0
	v_mfma_f32_16x16x32_bf16 v[48:51], v[196:199], v[204:207], 0
	v_mfma_f32_16x16x32_bf16 v[36:39], v[168:171], v[212:215], 0
	v_mfma_f32_16x16x32_bf16 v[32:35], v[196:199], v[212:215], 0
	v_mfma_f32_16x16x32_bf16 v[20:23], v[168:171], v[220:223], 0
	v_mfma_f32_16x16x32_bf16 v[16:19], v[196:199], v[220:223], 0
	v_mfma_f32_16x16x32_bf16 v[4:7], v[168:171], v[228:231], 0
	v_mfma_f32_16x16x32_bf16 v[0:3], v[196:199], v[228:231], 0
	v_mfma_f32_16x16x32_bf16 v[52:55], v[192:195], v[208:211], v[52:55]
	v_mfma_f32_16x16x32_bf16 v[48:51], v[200:203], v[208:211], v[48:51]
	v_mfma_f32_16x16x32_bf16 v[36:39], v[192:195], v[216:219], v[36:39]
	v_mfma_f32_16x16x32_bf16 v[32:35], v[200:203], v[216:219], v[32:35]
	v_mfma_f32_16x16x32_bf16 v[20:23], v[192:195], v[224:227], v[20:23]
	v_mfma_f32_16x16x32_bf16 v[16:19], v[200:203], v[224:227], v[16:19]
	v_mfma_f32_16x16x32_bf16 v[4:7], v[192:195], v[232:235], v[4:7]
	v_mfma_f32_16x16x32_bf16 v[0:3], v[200:203], v[232:235], v[0:3]
	s_setprio 0
	s_barrier
	s_add_i32 s47, 0, 0x18000
	s_add_i32 s50, 0, 0x1c000
	v_add_u32_e32 v164, s47, v153
	v_add_u32_e32 v184, s50, v153
	ds_read_b128 v[146:149], v164
	ds_read_b128 v[156:159], v164 offset:1024
	ds_read_b128 v[160:163], v164 offset:2048
	ds_read_b128 v[164:167], v164 offset:3072
	ds_read_b128 v[168:171], v184
	ds_read_b128 v[192:195], v184 offset:1024
	ds_read_b128 v[196:199], v184 offset:2048
	ds_read_b128 v[200:203], v184 offset:3072
	s_add_u32 s24, s64, 0x40000
	s_addc_u32 s25, s65, 0
	s_mov_b32 m0, s71
	v_lshl_add_u64 v[242:243], s[24:25], 0, v[140:141]
	ds_read_b128 v[204:207], v155 offset:32768
	ds_read_b128 v[208:211], v155 offset:33792
	ds_read_b128 v[212:215], v155 offset:34816
	ds_read_b128 v[216:219], v155 offset:35840
	ds_read_b128 v[220:223], v155 offset:36864
	ds_read_b128 v[224:227], v155 offset:37888
	ds_read_b128 v[228:231], v155 offset:38912
	ds_read_b128 v[232:235], v155 offset:39936
	global_load_lds_dwordx4 v[242:243], off
	v_lshl_add_u64 v[242:243], s[24:25], 0, v[130:131]
	s_mov_b32 m0, s87
	s_nop 0
	global_load_lds_dwordx4 v[242:243], off
	s_waitcnt vmcnt(8)
	s_waitcnt lgkmcnt(0)
	s_barrier
	s_setprio 1
	v_mfma_f32_16x16x32_bf16 v[124:127], v[146:149], v[204:207], v[124:127]
	v_mfma_f32_16x16x32_bf16 v[120:123], v[160:163], v[204:207], v[120:123]
	v_mfma_f32_16x16x32_bf16 v[108:111], v[146:149], v[212:215], v[108:111]
	v_mfma_f32_16x16x32_bf16 v[104:107], v[160:163], v[212:215], v[104:107]
	v_mfma_f32_16x16x32_bf16 v[92:95], v[146:149], v[220:223], v[92:95]
	v_mfma_f32_16x16x32_bf16 v[88:91], v[160:163], v[220:223], v[88:91]
	v_mfma_f32_16x16x32_bf16 v[76:79], v[146:149], v[228:231], v[76:79]
	v_mfma_f32_16x16x32_bf16 v[72:75], v[160:163], v[228:231], v[72:75]
	v_mfma_f32_16x16x32_bf16 v[124:127], v[156:159], v[208:211], v[124:127]
	v_mfma_f32_16x16x32_bf16 v[120:123], v[164:167], v[208:211], v[120:123]
	v_mfma_f32_16x16x32_bf16 v[108:111], v[156:159], v[216:219], v[108:111]
	v_mfma_f32_16x16x32_bf16 v[104:107], v[164:167], v[216:219], v[104:107]
	v_mfma_f32_16x16x32_bf16 v[92:95], v[156:159], v[224:227], v[92:95]
	v_mfma_f32_16x16x32_bf16 v[88:91], v[164:167], v[224:227], v[88:91]
	v_mfma_f32_16x16x32_bf16 v[76:79], v[156:159], v[232:235], v[76:79]
	v_mfma_f32_16x16x32_bf16 v[72:75], v[164:167], v[232:235], v[72:75]
	v_mfma_f32_16x16x32_bf16 v[116:119], v[168:171], v[204:207], v[116:119]
	v_mfma_f32_16x16x32_bf16 v[112:115], v[196:199], v[204:207], v[112:115]
	v_mfma_f32_16x16x32_bf16 v[100:103], v[168:171], v[212:215], v[100:103]
	v_mfma_f32_16x16x32_bf16 v[96:99], v[196:199], v[212:215], v[96:99]
	v_mfma_f32_16x16x32_bf16 v[84:87], v[168:171], v[220:223], v[84:87]
	v_mfma_f32_16x16x32_bf16 v[80:83], v[196:199], v[220:223], v[80:83]
	v_mfma_f32_16x16x32_bf16 v[68:71], v[168:171], v[228:231], v[68:71]
	v_mfma_f32_16x16x32_bf16 v[64:67], v[196:199], v[228:231], v[64:67]
	v_mfma_f32_16x16x32_bf16 v[116:119], v[192:195], v[208:211], v[116:119]
	v_mfma_f32_16x16x32_bf16 v[112:115], v[200:203], v[208:211], v[112:115]
	v_mfma_f32_16x16x32_bf16 v[100:103], v[192:195], v[216:219], v[100:103]
	v_mfma_f32_16x16x32_bf16 v[96:99], v[200:203], v[216:219], v[96:99]
	v_mfma_f32_16x16x32_bf16 v[84:87], v[192:195], v[224:227], v[84:87]
	v_mfma_f32_16x16x32_bf16 v[80:83], v[200:203], v[224:227], v[80:83]
	v_mfma_f32_16x16x32_bf16 v[68:71], v[192:195], v[232:235], v[68:71]
	v_mfma_f32_16x16x32_bf16 v[64:67], v[200:203], v[232:235], v[64:67]
	s_setprio 0
	s_barrier
; #define PG8_STAGE(bufoff, gbase, voff) do { _Pragma("unroll") for (int _i = 0; _i < 2; ++_i) \
;         __builtin_amdgcn_global_load_lds((const unsigned*)((const char*)(gbase) + (voff)[_i]), (PG8_LAS unsigned*)(lds + (bufoff) + ldsw + _i * 8192), 16, 0, 0); } while (0)
; #define PG8_LDA(dst, b, h) do { _Pragma("unroll") for (int m = 0; m < 4; ++m) _Pragma("unroll") for (int k = 0; k < 2; ++k) dst[m][k] = *(const PG8_LAS bf16x8*)(lds + PG8_SA(b, h) + aoff + m * 2048 + k * 1024); } while (0)
; #define PG8_LDB(dst, b, h) do { _Pragma("unroll") for (int n = 0; n < 2; ++n) _Pragma("unroll") for (int k = 0; k < 2; ++k) dst[n][k] = *(const PG8_LAS bf16x8*)(lds + PG8_SB(b, h) + boff + n * 2048 + k * 1024); } while (0)
; template <class Epi, class Sched, bool ALIGN_EPI = false, bool SP2 = false>
; __device__ __forceinline__ void gemm_phase(PG8_LAS unsigned char* lds, const Gemm g, const Sched& S, const Epi& E) {
;     ...
;         for (int t = 0; t < nt; t += 2) {
;             const bool last = (t == nt - 2);
;             const char* a1 = cA + (size_t)(t + 1) * kstep;
;             const char* a2 = last ? nA : cA + (size_t)(t + 2) * kstep; const char* b2 = last ? nB : cB + (size_t)(t + 2) * kstep;
;             const char* a3 = a2 + kstep; const char* b3 = b2 + kstep;
;             if (last && has_next) S.a_ready(nxt);
;             if constexpr (SP2) {
;             PG8_LDB(B0, 0, 0); PG8_LDB(B1, 0, 1); PG8_SCHED; PG8_LDA(At, 0, 0); PG8_STAGE(PG8_SA(1, 1), a1 + hstep, voffA);
;             PG8_WAIT_V(8); PG8_WAIT_L(0); PG8_BAR; PG8_MMA(0, 0, At, B0); PG8_MMA(0, 1, At, B1); PG8_BAR; PG8_SCHED;
;             PG8_LDA(At, 0, 1); PG8_STAGE(PG8_SB(0, 0), b2, voffB); PG8_STAGE(PG8_SB(0, 1), b2 + hstep, voffB); PG8_STAGE(PG8_SA(0, 0), a2, voffA);
;             PG8_WAIT_V(8); PG8_WAIT_L(0); PG8_BAR; PG8_MMA(1, 0, At, B0); PG8_MMA(1, 1, At, B1); PG8_BAR; PG8_SCHED;
;             PG8_LDB(B0, 1, 0); PG8_LDB(B1, 1, 1); PG8_SCHED; PG8_LDA(At, 1, 0); PG8_STAGE(PG8_SA(0, 1), a2 + hstep, voffA);
;             PG8_WAIT_V(8); PG8_WAIT_L(0); PG8_BAR; PG8_MMA(0, 0, At, B0); PG8_MMA(0, 1, At, B1); PG8_BAR; PG8_SCHED;
;             PG8_LDA(At, 1, 1); PG8_STAGE(PG8_SB(1, 0), b3, voffB); PG8_STAGE(PG8_SB(1, 1), b3 + hstep, voffB); PG8_STAGE(PG8_SA(1, 0), a3, voffA);
;             PG8_WAIT_V(8); PG8_WAIT_L(0); PG8_BAR; PG8_MMA(1, 0, At, B0); PG8_MMA(1, 1, At, B1); PG8_BAR; PG8_SCHED;
	s_add_i32 s24, s47, s66
	v_lshl_add_u64 v[150:151], v[150:151], 0, s[14:15]
	s_mov_b32 m0, s24
	ds_read_b128 v[204:207], v155 offset:49152
	ds_read_b128 v[208:211], v155 offset:50176
	ds_read_b128 v[212:215], v155 offset:51200
	ds_read_b128 v[216:219], v155 offset:52224
	ds_read_b128 v[220:223], v155 offset:53248
	ds_read_b128 v[224:227], v155 offset:54272
	ds_read_b128 v[228:231], v155 offset:55296
	ds_read_b128 v[232:235], v155 offset:56320
	global_load_lds_dwordx4 v[150:151], off
	s_add_i32 m0, s24, 0x2000
	s_add_u32 s24, s62, 0x40080
	v_lshl_add_u64 v[150:151], v[236:237], 0, s[14:15]
	s_addc_u32 s25, s63, 0
	s_add_i32 s47, s50, s66
	global_load_lds_dwordx4 v[150:151], off
	v_lshl_add_u64 v[150:151], s[24:25], 0, v[132:133]
	s_mov_b32 m0, s47
	s_nop 0
	global_load_lds_dwordx4 v[150:151], off
	v_lshl_add_u64 v[150:151], s[24:25], 0, v[128:129]
	s_add_i32 m0, s47, 0x2000
	s_nop 0
	global_load_lds_dwordx4 v[150:151], off
	v_lshl_add_u64 v[150:151], v[238:239], 0, s[14:15]
	s_mov_b32 m0, s88
	s_nop 0
	global_load_lds_dwordx4 v[150:151], off
	v_lshl_add_u64 v[150:151], v[240:241], 0, s[14:15]
	s_mov_b32 m0, s89
	s_nop 0
	global_load_lds_dwordx4 v[150:151], off
	s_waitcnt vmcnt(8)
	s_waitcnt lgkmcnt(0)
	s_barrier
	s_setprio 1
	v_mfma_f32_16x16x32_bf16 v[60:63], v[146:149], v[204:207], v[60:63]
	v_mfma_f32_16x16x32_bf16 v[56:59], v[160:163], v[204:207], v[56:59]
	v_mfma_f32_16x16x32_bf16 v[44:47], v[146:149], v[212:215], v[44:47]
	v_mfma_f32_16x16x32_bf16 v[40:43], v[160:163], v[212:215], v[40:43]
	v_mfma_f32_16x16x32_bf16 v[28:31], v[146:149], v[220:223], v[28:31]
	v_mfma_f32_16x16x32_bf16 v[24:27], v[160:163], v[220:223], v[24:27]
	v_mfma_f32_16x16x32_bf16 v[12:15], v[146:149], v[228:231], v[12:15]
	v_mfma_f32_16x16x32_bf16 v[8:11], v[160:163], v[228:231], v[8:11]
	v_mfma_f32_16x16x32_bf16 v[60:63], v[156:159], v[208:211], v[60:63]
	v_mfma_f32_16x16x32_bf16 v[56:59], v[164:167], v[208:211], v[56:59]
	v_mfma_f32_16x16x32_bf16 v[44:47], v[156:159], v[216:219], v[44:47]
	v_mfma_f32_16x16x32_bf16 v[40:43], v[164:167], v[216:219], v[40:43]
	v_mfma_f32_16x16x32_bf16 v[28:31], v[156:159], v[224:227], v[28:31]
	v_mfma_f32_16x16x32_bf16 v[24:27], v[164:167], v[224:227], v[24:27]
	v_mfma_f32_16x16x32_bf16 v[12:15], v[156:159], v[232:235], v[12:15]
	v_mfma_f32_16x16x32_bf16 v[8:11], v[164:167], v[232:235], v[8:11]
	v_mfma_f32_16x16x32_bf16 v[52:55], v[168:171], v[204:207], v[52:55]
	v_mfma_f32_16x16x32_bf16 v[48:51], v[196:199], v[204:207], v[48:51]
	v_mfma_f32_16x16x32_bf16 v[36:39], v[168:171], v[212:215], v[36:39]
	v_mfma_f32_16x16x32_bf16 v[32:35], v[196:199], v[212:215], v[32:35]
	v_mfma_f32_16x16x32_bf16 v[20:23], v[168:171], v[220:223], v[20:23]
	v_mfma_f32_16x16x32_bf16 v[16:19], v[196:199], v[220:223], v[16:19]
	v_mfma_f32_16x16x32_bf16 v[4:7], v[168:171], v[228:231], v[4:7]
	v_mfma_f32_16x16x32_bf16 v[0:3], v[196:199], v[228:231], v[0:3]
	v_mfma_f32_16x16x32_bf16 v[52:55], v[192:195], v[208:211], v[52:55]
	v_mfma_f32_16x16x32_bf16 v[48:51], v[200:203], v[208:211], v[48:51]
	v_mfma_f32_16x16x32_bf16 v[36:39], v[192:195], v[216:219], v[36:39]
	v_mfma_f32_16x16x32_bf16 v[32:35], v[200:203], v[216:219], v[32:35]
	v_mfma_f32_16x16x32_bf16 v[20:23], v[192:195], v[224:227], v[20:23]
	v_mfma_f32_16x16x32_bf16 v[16:19], v[200:203], v[224:227], v[16:19]
	v_mfma_f32_16x16x32_bf16 v[4:7], v[192:195], v[232:235], v[4:7]
	v_mfma_f32_16x16x32_bf16 v[0:3], v[200:203], v[232:235], v[0:3]
	s_setprio 0
	s_barrier
	s_add_i32 s45, s45, 2
	s_add_u32 s60, s60, 0x100
	s_addc_u32 s61, s61, 0
	s_add_u32 s33, s33, 0x100
	s_addc_u32 s44, s44, 0
	s_cmp_gt_u32 s45, 13
.LBB0_44:
	s_add_u32 s24, s60, 0xfffc0080
	s_addc_u32 s25, s61, -1
	s_add_i32 s47, 0, 0x10000
	s_cmp_eq_u32 s45, 12
	s_cselect_b32 s65, s1, s25
	s_cselect_b32 s64, s12, s24
	v_add_u32_e32 v150, s47, v153
	s_cselect_b32 s63, s3, s44
	s_cselect_b32 s62, s22, s33
	s_add_i32 s50, 0, 0x14000
	ds_read_b128 v[146:149], v150
	ds_read_b128 v[156:159], v150 offset:1024
	ds_read_b128 v[160:163], v150 offset:2048
	ds_read_b128 v[164:167], v150 offset:3072
	v_add_u32_e32 v150, s50, v153
	ds_read_b128 v[168:171], v150
	ds_read_b128 v[192:195], v150 offset:1024
	ds_read_b128 v[196:199], v150 offset:2048
	ds_read_b128 v[200:203], v150 offset:3072
	v_lshl_add_u64 v[150:151], s[60:61], 0, v[142:143]
	s_add_i32 m0, s68, 0xc000
	ds_read_b128 v[204:207], v155
	ds_read_b128 v[208:211], v155 offset:1024
	ds_read_b128 v[212:215], v155 offset:2048
	ds_read_b128 v[216:219], v155 offset:3072
	ds_read_b128 v[220:223], v155 offset:4096
	ds_read_b128 v[224:227], v155 offset:5120
	ds_read_b128 v[228:231], v155 offset:6144
	ds_read_b128 v[232:235], v155 offset:7168
	global_load_lds_dwordx4 v[150:151], off
	v_lshl_add_u64 v[150:151], s[60:61], 0, v[144:145]
	s_add_i32 m0, s68, 0xe000
	s_nop 0
	global_load_lds_dwordx4 v[150:151], off
	s_waitcnt vmcnt(8)
	s_waitcnt lgkmcnt(0)
	s_barrier
; #define PG8_STAGE(bufoff, gbase, voff) do { _Pragma("unroll") for (int _i = 0; _i < 2; ++_i) \
;         __builtin_amdgcn_global_load_lds((const unsigned*)((const char*)(gbase) + (voff)[_i]), (PG8_LAS unsigned*)(lds + (bufoff) + ldsw + _i * 8192), 16, 0, 0); } while (0)
; #define PG8_LDA(dst, b, h) do { _Pragma("unroll") for (int m = 0; m < 4; ++m) _Pragma("unroll") for (int k = 0; k < 2; ++k) dst[m][k] = *(const PG8_LAS bf16x8*)(lds + PG8_SA(b, h) + aoff + m * 2048 + k * 1024); } while (0)
; #define PG8_MMA(ai, bj, At, Bt) do { __builtin_amdgcn_s_setprio(1); _Pragma("unroll") for (int m = 0; m < 4; ++m) _Pragma("unroll") for (int n = 0; n < 2; ++n) _Pragma("unroll") for (int k = 0; k < 2; ++k) \
;         acc[ai][bj][m][n] = __builtin_amdgcn_mfma_f32_16x16x32_bf16(Bt[n][k], At[m][k], acc[ai][bj][m][n], 0, 0, 0); __builtin_amdgcn_s_setprio(0); } while (0)
; #define PG8_WAIT_V(n) asm volatile("s_waitcnt vmcnt(" #n ")" ::: "memory")
; #define PG8_WAIT_L(n) asm volatile("s_waitcnt lgkmcnt(" #n ")" ::: "memory")
; #define PG8_BAR __builtin_amdgcn_s_barrier()
; #define PG8_SCHED __builtin_amdgcn_sched_barrier(0)
; template <class Epi, class Sched, bool ALIGN_EPI = false, bool SP2 = false>
; __device__ __forceinline__ void gemm_phase(PG8_LAS unsigned char* lds, const Gemm g, const Sched& S, const Epi& E) {
;     ...
;             PG8_WAIT_V(8); PG8_WAIT_L(0); PG8_BAR; PG8_MMA(0, 0, At, B0); PG8_MMA(0, 1, At, B1); PG8_BAR; PG8_SCHED;
;             PG8_LDA(At, 0, 1); PG8_STAGE(PG8_SB(0, 0), b2, voffB); PG8_STAGE(PG8_SB(0, 1), b2 + hstep, voffB); PG8_STAGE(PG8_SA(0, 0), a2, voffA);
;             PG8_WAIT_V(8); PG8_WAIT_L(0); PG8_BAR; PG8_MMA(1, 0, At, B0); PG8_MMA(1, 1, At, B1); PG8_BAR; PG8_SCHED;
	s_setprio 1
	v_mfma_f32_16x16x32_bf16 v[124:127], v[146:149], v[204:207], v[124:127]
	v_mfma_f32_16x16x32_bf16 v[120:123], v[160:163], v[204:207], v[120:123]
	v_mfma_f32_16x16x32_bf16 v[108:111], v[146:149], v[212:215], v[108:111]
	v_mfma_f32_16x16x32_bf16 v[104:107], v[160:163], v[212:215], v[104:107]
	v_mfma_f32_16x16x32_bf16 v[92:95], v[146:149], v[220:223], v[92:95]
	v_mfma_f32_16x16x32_bf16 v[88:91], v[160:163], v[220:223], v[88:91]
	v_mfma_f32_16x16x32_bf16 v[76:79], v[146:149], v[228:231], v[76:79]
	v_mfma_f32_16x16x32_bf16 v[72:75], v[160:163], v[228:231], v[72:75]
	v_mfma_f32_16x16x32_bf16 v[124:127], v[156:159], v[208:211], v[124:127]
	v_mfma_f32_16x16x32_bf16 v[120:123], v[164:167], v[208:211], v[120:123]
	v_mfma_f32_16x16x32_bf16 v[108:111], v[156:159], v[216:219], v[108:111]
	v_mfma_f32_16x16x32_bf16 v[104:107], v[164:167], v[216:219], v[104:107]
	v_mfma_f32_16x16x32_bf16 v[92:95], v[156:159], v[224:227], v[92:95]
	v_mfma_f32_16x16x32_bf16 v[88:91], v[164:167], v[224:227], v[88:91]
	v_mfma_f32_16x16x32_bf16 v[76:79], v[156:159], v[232:235], v[76:79]
	v_mfma_f32_16x16x32_bf16 v[72:75], v[164:167], v[232:235], v[72:75]
	v_mfma_f32_16x16x32_bf16 v[116:119], v[168:171], v[204:207], v[116:119]
	v_mfma_f32_16x16x32_bf16 v[112:115], v[196:199], v[204:207], v[112:115]
	v_mfma_f32_16x16x32_bf16 v[100:103], v[168:171], v[212:215], v[100:103]
	v_mfma_f32_16x16x32_bf16 v[96:99], v[196:199], v[212:215], v[96:99]
	v_mfma_f32_16x16x32_bf16 v[84:87], v[168:171], v[220:223], v[84:87]
	v_mfma_f32_16x16x32_bf16 v[80:83], v[196:199], v[220:223], v[80:83]
	v_mfma_f32_16x16x32_bf16 v[68:71], v[168:171], v[228:231], v[68:71]
	v_mfma_f32_16x16x32_bf16 v[64:67], v[196:199], v[228:231], v[64:67]
	v_mfma_f32_16x16x32_bf16 v[116:119], v[192:195], v[208:211], v[116:119]
	v_mfma_f32_16x16x32_bf16 v[112:115], v[200:203], v[208:211], v[112:115]
	v_mfma_f32_16x16x32_bf16 v[100:103], v[192:195], v[216:219], v[100:103]
	v_mfma_f32_16x16x32_bf16 v[96:99], v[200:203], v[216:219], v[96:99]
	v_mfma_f32_16x16x32_bf16 v[84:87], v[192:195], v[224:227], v[84:87]
	v_mfma_f32_16x16x32_bf16 v[80:83], v[200:203], v[224:227], v[80:83]
	v_mfma_f32_16x16x32_bf16 v[68:71], v[192:195], v[232:235], v[68:71]
	v_mfma_f32_16x16x32_bf16 v[64:67], v[200:203], v[232:235], v[64:67]
	s_setprio 0
	s_barrier
	s_add_i32 s24, s47, s66
	v_lshl_add_u64 v[150:151], s[62:63], 0, v[132:133]
	s_mov_b32 m0, s24
	ds_read_b128 v[204:207], v155 offset:16384
	ds_read_b128 v[208:211], v155 offset:17408
	ds_read_b128 v[212:215], v155 offset:18432
	ds_read_b128 v[216:219], v155 offset:19456
	ds_read_b128 v[220:223], v155 offset:20480
	ds_read_b128 v[224:227], v155 offset:21504
	ds_read_b128 v[228:231], v155 offset:22528
	ds_read_b128 v[232:235], v155 offset:23552
	global_load_lds_dwordx4 v[150:151], off
	s_add_i32 m0, s24, 0x2000
	s_add_u32 s24, s62, 0x40000
	v_lshl_add_u64 v[236:237], s[62:63], 0, v[128:129]
	s_addc_u32 s25, s63, 0
	s_add_i32 s47, s50, s66
	global_load_lds_dwordx4 v[236:237], off
	v_lshl_add_u64 v[238:239], s[24:25], 0, v[132:133]
	s_mov_b32 m0, s47
	v_lshl_add_u64 v[240:241], s[64:65], 0, v[130:131]
	global_load_lds_dwordx4 v[238:239], off
	v_lshl_add_u64 v[238:239], s[24:25], 0, v[128:129]
	s_add_i32 m0, s47, 0x2000
	s_nop 0
	global_load_lds_dwordx4 v[238:239], off
	v_lshl_add_u64 v[238:239], s[64:65], 0, v[140:141]
	s_mov_b32 m0, s68
	s_nop 0
	global_load_lds_dwordx4 v[238:239], off
	s_mov_b32 m0, s69
	s_nop 0
	global_load_lds_dwordx4 v[240:241], off
	s_waitcnt vmcnt(8)
	s_waitcnt lgkmcnt(0)
	s_barrier
	s_setprio 1
	v_mfma_f32_16x16x32_bf16 v[60:63], v[146:149], v[204:207], v[60:63]
	v_mfma_f32_16x16x32_bf16 v[56:59], v[160:163], v[204:207], v[56:59]
	v_mfma_f32_16x16x32_bf16 v[44:47], v[146:149], v[212:215], v[44:47]
	v_mfma_f32_16x16x32_bf16 v[40:43], v[160:163], v[212:215], v[40:43]
	v_mfma_f32_16x16x32_bf16 v[28:31], v[146:149], v[220:223], v[28:31]
	v_mfma_f32_16x16x32_bf16 v[24:27], v[160:163], v[220:223], v[24:27]
	v_mfma_f32_16x16x32_bf16 v[12:15], v[146:149], v[228:231], v[12:15]
	v_mfma_f32_16x16x32_bf16 v[8:11], v[160:163], v[228:231], v[8:11]
	v_mfma_f32_16x16x32_bf16 v[60:63], v[156:159], v[208:211], v[60:63]
	v_mfma_f32_16x16x32_bf16 v[56:59], v[164:167], v[208:211], v[56:59]
	v_mfma_f32_16x16x32_bf16 v[44:47], v[156:159], v[216:219], v[44:47]
	v_mfma_f32_16x16x32_bf16 v[40:43], v[164:167], v[216:219], v[40:43]
	v_mfma_f32_16x16x32_bf16 v[28:31], v[156:159], v[224:227], v[28:31]
	v_mfma_f32_16x16x32_bf16 v[24:27], v[164:167], v[224:227], v[24:27]
	v_mfma_f32_16x16x32_bf16 v[12:15], v[156:159], v[232:235], v[12:15]
	v_mfma_f32_16x16x32_bf16 v[8:11], v[164:167], v[232:235], v[8:11]
	v_mfma_f32_16x16x32_bf16 v[52:55], v[168:171], v[204:207], v[52:55]
	v_mfma_f32_16x16x32_bf16 v[48:51], v[196:199], v[204:207], v[48:51]
	v_mfma_f32_16x16x32_bf16 v[36:39], v[168:171], v[212:215], v[36:39]
	v_mfma_f32_16x16x32_bf16 v[32:35], v[196:199], v[212:215], v[32:35]
	v_mfma_f32_16x16x32_bf16 v[20:23], v[168:171], v[220:223], v[20:23]
	v_mfma_f32_16x16x32_bf16 v[16:19], v[196:199], v[220:223], v[16:19]
	v_mfma_f32_16x16x32_bf16 v[4:7], v[168:171], v[228:231], v[4:7]
	v_mfma_f32_16x16x32_bf16 v[0:3], v[196:199], v[228:231], v[0:3]
	v_mfma_f32_16x16x32_bf16 v[52:55], v[192:195], v[208:211], v[52:55]
	v_mfma_f32_16x16x32_bf16 v[48:51], v[200:203], v[208:211], v[48:51]
	v_mfma_f32_16x16x32_bf16 v[36:39], v[192:195], v[216:219], v[36:39]
	v_mfma_f32_16x16x32_bf16 v[32:35], v[200:203], v[216:219], v[32:35]
	v_mfma_f32_16x16x32_bf16 v[20:23], v[192:195], v[224:227], v[20:23]
	v_mfma_f32_16x16x32_bf16 v[16:19], v[200:203], v[224:227], v[16:19]
	v_mfma_f32_16x16x32_bf16 v[4:7], v[192:195], v[232:235], v[4:7]
	v_mfma_f32_16x16x32_bf16 v[0:3], v[200:203], v[232:235], v[0:3]
	s_setprio 0
	s_barrier
; #define PG8_STAGE(bufoff, gbase, voff) do { _Pragma("unroll") for (int _i = 0; _i < 2; ++_i) \
;         __builtin_amdgcn_global_load_lds((const unsigned*)((const char*)(gbase) + (voff)[_i]), (PG8_LAS unsigned*)(lds + (bufoff) + ldsw + _i * 8192), 16, 0, 0); } while (0)
; #define PG8_LDA(dst, b, h) do { _Pragma("unroll") for (int m = 0; m < 4; ++m) _Pragma("unroll") for (int k = 0; k < 2; ++k) dst[m][k] = *(const PG8_LAS bf16x8*)(lds + PG8_SA(b, h) + aoff + m * 2048 + k * 1024); } while (0)
; #define PG8_LDB(dst, b, h) do { _Pragma("unroll") for (int n = 0; n < 2; ++n) _Pragma("unroll") for (int k = 0; k < 2; ++k) dst[n][k] = *(const PG8_LAS bf16x8*)(lds + PG8_SB(b, h) + boff + n * 2048 + k * 1024); } while (0)
; #define PG8_MMA(ai, bj, At, Bt) do { __builtin_amdgcn_s_setprio(1); _Pragma("unroll") for (int m = 0; m < 4; ++m) _Pragma("unroll") for (int n = 0; n < 2; ++n) _Pragma("unroll") for (int k = 0; k < 2; ++k) \
;         acc[ai][bj][m][n] = __builtin_amdgcn_mfma_f32_16x16x32_bf16(Bt[n][k], At[m][k], acc[ai][bj][m][n], 0, 0, 0); __builtin_amdgcn_s_setprio(0); } while (0)
; #define PG8_WAIT_V(n) asm volatile("s_waitcnt vmcnt(" #n ")" ::: "memory")
; #define PG8_WAIT_L(n) asm volatile("s_waitcnt lgkmcnt(" #n ")" ::: "memory")
; #define PG8_BAR __builtin_amdgcn_s_barrier()
; #define PG8_SCHED __builtin_amdgcn_sched_barrier(0)
; template <class Epi, class Sched, bool ALIGN_EPI = false, bool SP2 = false>
; __device__ __forceinline__ void gemm_phase(PG8_LAS unsigned char* lds, const Gemm g, const Sched& S, const Epi& E) {
;     ...
;             PG8_LDB(B0, 1, 0); PG8_LDB(B1, 1, 1); PG8_SCHED; PG8_LDA(At, 1, 0); PG8_STAGE(PG8_SA(0, 1), a2 + hstep, voffA);
;             PG8_WAIT_V(8); PG8_WAIT_L(0); PG8_BAR; PG8_MMA(0, 0, At, B0); PG8_MMA(0, 1, At, B1); PG8_BAR; PG8_SCHED;
	s_add_i32 s47, 0, 0x18000
	s_add_i32 s50, 0, 0x1c000
	v_add_u32_e32 v164, s47, v153
	v_add_u32_e32 v184, s50, v153
	ds_read_b128 v[146:149], v164
	ds_read_b128 v[156:159], v164 offset:1024
	ds_read_b128 v[160:163], v164 offset:2048
	ds_read_b128 v[164:167], v164 offset:3072
	ds_read_b128 v[168:171], v184
	ds_read_b128 v[192:195], v184 offset:1024
	ds_read_b128 v[196:199], v184 offset:2048
	ds_read_b128 v[200:203], v184 offset:3072
	s_add_u32 s24, s64, 0x40000
	s_addc_u32 s25, s65, 0
	s_mov_b32 m0, s71
	v_lshl_add_u64 v[242:243], s[24:25], 0, v[140:141]
	ds_read_b128 v[204:207], v155 offset:32768
	ds_read_b128 v[208:211], v155 offset:33792
	ds_read_b128 v[212:215], v155 offset:34816
	ds_read_b128 v[216:219], v155 offset:35840
	ds_read_b128 v[220:223], v155 offset:36864
	ds_read_b128 v[224:227], v155 offset:37888
	ds_read_b128 v[228:231], v155 offset:38912
	ds_read_b128 v[232:235], v155 offset:39936
	global_load_lds_dwordx4 v[242:243], off
	v_lshl_add_u64 v[242:243], s[24:25], 0, v[130:131]
	s_mov_b32 m0, s87
	s_nop 0
	global_load_lds_dwordx4 v[242:243], off
	s_waitcnt vmcnt(8)
	s_waitcnt lgkmcnt(0)
	s_barrier
	s_setprio 1
	v_mfma_f32_16x16x32_bf16 v[124:127], v[146:149], v[204:207], v[124:127]
	v_mfma_f32_16x16x32_bf16 v[120:123], v[160:163], v[204:207], v[120:123]
	v_mfma_f32_16x16x32_bf16 v[108:111], v[146:149], v[212:215], v[108:111]
	v_mfma_f32_16x16x32_bf16 v[104:107], v[160:163], v[212:215], v[104:107]
	v_mfma_f32_16x16x32_bf16 v[92:95], v[146:149], v[220:223], v[92:95]
	v_mfma_f32_16x16x32_bf16 v[88:91], v[160:163], v[220:223], v[88:91]
	v_mfma_f32_16x16x32_bf16 v[76:79], v[146:149], v[228:231], v[76:79]
	v_mfma_f32_16x16x32_bf16 v[72:75], v[160:163], v[228:231], v[72:75]
	v_mfma_f32_16x16x32_bf16 v[124:127], v[156:159], v[208:211], v[124:127]
	v_mfma_f32_16x16x32_bf16 v[120:123], v[164:167], v[208:211], v[120:123]
	v_mfma_f32_16x16x32_bf16 v[108:111], v[156:159], v[216:219], v[108:111]
	v_mfma_f32_16x16x32_bf16 v[104:107], v[164:167], v[216:219], v[104:107]
	v_mfma_f32_16x16x32_bf16 v[92:95], v[156:159], v[224:227], v[92:95]
	v_mfma_f32_16x16x32_bf16 v[88:91], v[164:167], v[224:227], v[88:91]
	v_mfma_f32_16x16x32_bf16 v[76:79], v[156:159], v[232:235], v[76:79]
	v_mfma_f32_16x16x32_bf16 v[72:75], v[164:167], v[232:235], v[72:75]
	v_mfma_f32_16x16x32_bf16 v[116:119], v[168:171], v[204:207], v[116:119]
	v_mfma_f32_16x16x32_bf16 v[112:115], v[196:199], v[204:207], v[112:115]
	v_mfma_f32_16x16x32_bf16 v[100:103], v[168:171], v[212:215], v[100:103]
	v_mfma_f32_16x16x32_bf16 v[96:99], v[196:199], v[212:215], v[96:99]
	v_mfma_f32_16x16x32_bf16 v[84:87], v[168:171], v[220:223], v[84:87]
	v_mfma_f32_16x16x32_bf16 v[80:83], v[196:199], v[220:223], v[80:83]
	v_mfma_f32_16x16x32_bf16 v[68:71], v[168:171], v[228:231], v[68:71]
	v_mfma_f32_16x16x32_bf16 v[64:67], v[196:199], v[228:231], v[64:67]
	v_mfma_f32_16x16x32_bf16 v[116:119], v[192:195], v[208:211], v[116:119]
	v_mfma_f32_16x16x32_bf16 v[112:115], v[200:203], v[208:211], v[112:115]
	v_mfma_f32_16x16x32_bf16 v[100:103], v[192:195], v[216:219], v[100:103]
	v_mfma_f32_16x16x32_bf16 v[96:99], v[200:203], v[216:219], v[96:99]
	v_mfma_f32_16x16x32_bf16 v[84:87], v[192:195], v[224:227], v[84:87]
	v_mfma_f32_16x16x32_bf16 v[80:83], v[200:203], v[224:227], v[80:83]
	v_mfma_f32_16x16x32_bf16 v[68:71], v[192:195], v[232:235], v[68:71]
	v_mfma_f32_16x16x32_bf16 v[64:67], v[200:203], v[232:235], v[64:67]
	s_setprio 0
	s_barrier
; #define PG8_STAGE(bufoff, gbase, voff) do { _Pragma("unroll") for (int _i = 0; _i < 2; ++_i) \
;         __builtin_amdgcn_global_load_lds((const unsigned*)((const char*)(gbase) + (voff)[_i]), (PG8_LAS unsigned*)(lds + (bufoff) + ldsw + _i * 8192), 16, 0, 0); } while (0)
; #define PG8_LDA(dst, b, h) do { _Pragma("unroll") for (int m = 0; m < 4; ++m) _Pragma("unroll") for (int k = 0; k < 2; ++k) dst[m][k] = *(const PG8_LAS bf16x8*)(lds + PG8_SA(b, h) + aoff + m * 2048 + k * 1024); } while (0)
; #define PG8_MMA(ai, bj, At, Bt) do { __builtin_amdgcn_s_setprio(1); _Pragma("unroll") for (int m = 0; m < 4; ++m) _Pragma("unroll") for (int n = 0; n < 2; ++n) _Pragma("unroll") for (int k = 0; k < 2; ++k) \
;         acc[ai][bj][m][n] = __builtin_amdgcn_mfma_f32_16x16x32_bf16(Bt[n][k], At[m][k], acc[ai][bj][m][n], 0, 0, 0); __builtin_amdgcn_s_setprio(0); } while (0)
; #define PG8_WAIT_V(n) asm volatile("s_waitcnt vmcnt(" #n ")" ::: "memory")
; #define PG8_WAIT_L(n) asm volatile("s_waitcnt lgkmcnt(" #n ")" ::: "memory")
; #define PG8_BAR __builtin_amdgcn_s_barrier()
; #define PG8_SCHED __builtin_amdgcn_sched_barrier(0)
; template <class Epi, class Sched, bool ALIGN_EPI = false, bool SP2 = false>
; __device__ __forceinline__ void gemm_phase(PG8_LAS unsigned char* lds, const Gemm g, const Sched& S, const Epi& E) {
;     ...
;             PG8_LDA(At, 1, 1); PG8_STAGE(PG8_SB(1, 0), b3, voffB); PG8_STAGE(PG8_SB(1, 1), b3 + hstep, voffB); PG8_STAGE(PG8_SA(1, 0), a3, voffA);
;             PG8_WAIT_V(8); PG8_WAIT_L(0); PG8_BAR; PG8_MMA(1, 0, At, B0); PG8_MMA(1, 1, At, B1); PG8_BAR; PG8_SCHED;
;     ...
;         if constexpr (ALIGN_EPI) { if (wr == 0) PG8_BAR; }
	s_add_i32 s24, s47, s66
	v_lshl_add_u64 v[150:151], v[150:151], 0, s[14:15]
	s_mov_b32 m0, s24
	ds_read_b128 v[204:207], v155 offset:49152
	ds_read_b128 v[208:211], v155 offset:50176
	ds_read_b128 v[212:215], v155 offset:51200
	ds_read_b128 v[216:219], v155 offset:52224
	ds_read_b128 v[220:223], v155 offset:53248
	ds_read_b128 v[224:227], v155 offset:54272
	ds_read_b128 v[228:231], v155 offset:55296
	ds_read_b128 v[232:235], v155 offset:56320
	global_load_lds_dwordx4 v[150:151], off
	s_add_i32 m0, s24, 0x2000
	s_add_u32 s24, s62, 0x40080
	v_lshl_add_u64 v[150:151], v[236:237], 0, s[14:15]
	s_addc_u32 s25, s63, 0
	s_add_i32 s47, s50, s66
	global_load_lds_dwordx4 v[150:151], off
	v_lshl_add_u64 v[150:151], s[24:25], 0, v[132:133]
	s_mov_b32 m0, s47
	s_nop 0
	global_load_lds_dwordx4 v[150:151], off
	v_lshl_add_u64 v[150:151], s[24:25], 0, v[128:129]
	s_add_i32 m0, s47, 0x2000
	s_nop 0
	global_load_lds_dwordx4 v[150:151], off
	v_lshl_add_u64 v[150:151], v[238:239], 0, s[14:15]
	s_mov_b32 m0, s88
	s_nop 0
	global_load_lds_dwordx4 v[150:151], off
	v_lshl_add_u64 v[150:151], v[240:241], 0, s[14:15]
	s_mov_b32 m0, s89
	s_nop 0
	global_load_lds_dwordx4 v[150:151], off
	s_waitcnt vmcnt(8)
	s_waitcnt lgkmcnt(0)
	s_barrier
	s_setprio 1
	v_mfma_f32_16x16x32_bf16 v[60:63], v[146:149], v[204:207], v[60:63]
	v_mfma_f32_16x16x32_bf16 v[56:59], v[160:163], v[204:207], v[56:59]
	v_mfma_f32_16x16x32_bf16 v[44:47], v[146:149], v[212:215], v[44:47]
	v_mfma_f32_16x16x32_bf16 v[40:43], v[160:163], v[212:215], v[40:43]
	v_mfma_f32_16x16x32_bf16 v[28:31], v[146:149], v[220:223], v[28:31]
	v_mfma_f32_16x16x32_bf16 v[24:27], v[160:163], v[220:223], v[24:27]
	v_mfma_f32_16x16x32_bf16 v[12:15], v[146:149], v[228:231], v[12:15]
	v_mfma_f32_16x16x32_bf16 v[8:11], v[160:163], v[228:231], v[8:11]
	v_mfma_f32_16x16x32_bf16 v[60:63], v[156:159], v[208:211], v[60:63]
	v_mfma_f32_16x16x32_bf16 v[56:59], v[164:167], v[208:211], v[56:59]
	v_mfma_f32_16x16x32_bf16 v[44:47], v[156:159], v[216:219], v[44:47]
	v_mfma_f32_16x16x32_bf16 v[40:43], v[164:167], v[216:219], v[40:43]
	v_mfma_f32_16x16x32_bf16 v[28:31], v[156:159], v[224:227], v[28:31]
	v_mfma_f32_16x16x32_bf16 v[24:27], v[164:167], v[224:227], v[24:27]
	v_mfma_f32_16x16x32_bf16 v[12:15], v[156:159], v[232:235], v[12:15]
	v_mfma_f32_16x16x32_bf16 v[8:11], v[164:167], v[232:235], v[8:11]
	v_mfma_f32_16x16x32_bf16 v[52:55], v[168:171], v[204:207], v[52:55]
	v_mfma_f32_16x16x32_bf16 v[48:51], v[196:199], v[204:207], v[48:51]
	v_mfma_f32_16x16x32_bf16 v[36:39], v[168:171], v[212:215], v[36:39]
	v_mfma_f32_16x16x32_bf16 v[32:35], v[196:199], v[212:215], v[32:35]
	v_mfma_f32_16x16x32_bf16 v[20:23], v[168:171], v[220:223], v[20:23]
	v_mfma_f32_16x16x32_bf16 v[16:19], v[196:199], v[220:223], v[16:19]
	v_mfma_f32_16x16x32_bf16 v[4:7], v[168:171], v[228:231], v[4:7]
	v_mfma_f32_16x16x32_bf16 v[0:3], v[196:199], v[228:231], v[0:3]
	v_mfma_f32_16x16x32_bf16 v[52:55], v[192:195], v[208:211], v[52:55]
	v_mfma_f32_16x16x32_bf16 v[48:51], v[200:203], v[208:211], v[48:51]
	v_mfma_f32_16x16x32_bf16 v[36:39], v[192:195], v[216:219], v[36:39]
	v_mfma_f32_16x16x32_bf16 v[32:35], v[200:203], v[216:219], v[32:35]
	v_mfma_f32_16x16x32_bf16 v[20:23], v[192:195], v[224:227], v[20:23]
	v_mfma_f32_16x16x32_bf16 v[16:19], v[200:203], v[224:227], v[16:19]
	v_mfma_f32_16x16x32_bf16 v[4:7], v[192:195], v[232:235], v[4:7]
	v_mfma_f32_16x16x32_bf16 v[0:3], v[200:203], v[232:235], v[0:3]
	s_setprio 0
	s_barrier
	s_add_i32 s45, s45, 2
	s_add_u32 s60, s60, 0x100
	s_addc_u32 s61, s61, 0
	s_add_u32 s33, s33, 0x100
	s_addc_u32 s44, s44, 0
	s_cmp_gt_u32 s45, 13
	s_cbranch_scc0 .LBB0_44
	s_and_b64 vcc, exec, s[20:21]
	s_cbranch_vccz .LBB0_47
	s_barrier

; #define PG8_STAGE(bufoff, gbase, voff) do { _Pragma("unroll") for (int _i = 0; _i < 2; ++_i) \
;         __builtin_amdgcn_global_load_lds((const unsigned*)((const char*)(gbase) + (voff)[_i]), (PG8_LAS unsigned*)(lds + (bufoff) + ldsw + _i * 8192), 16, 0, 0); } while (0)
; #define PG8_LDA(dst, b, h) do { _Pragma("unroll") for (int m = 0; m < 4; ++m) _Pragma("unroll") for (int k = 0; k < 2; ++k) dst[m][k] = *(const PG8_LAS bf16x8*)(lds + PG8_SA(b, h) + aoff + m * 2048 + k * 1024); } while (0)
; #define PG8_LDB(dst, b, h) do { _Pragma("unroll") for (int n = 0; n < 2; ++n) _Pragma("unroll") for (int k = 0; k < 2; ++k) dst[n][k] = *(const PG8_LAS bf16x8*)(lds + PG8_SB(b, h) + boff + n * 2048 + k * 1024); } while (0)
; #define PG8_WAIT_V(n) asm volatile("s_waitcnt vmcnt(" #n ")" ::: "memory")
; #define PG8_WAIT_L(n) asm volatile("s_waitcnt lgkmcnt(" #n ")" ::: "memory")
; #define PG8_BAR __builtin_amdgcn_s_barrier()
; #define PG8_SCHED __builtin_amdgcn_sched_barrier(0)
; template <class Epi, class Sched, bool ALIGN_EPI = false, bool SP2 = false>
; __device__ __forceinline__ void gemm_phase(PG8_LAS unsigned char* lds, const Gemm g, const Sched& S, const Epi& E) {
;     ...
;         const bool has_next = S.next(ui + 1, nxt);
;         const char* nA = has_next ? (const char*)g.A + (size_t)nxt.pm * tstep : cA; const char* nB = has_next ? (const char*)g.Bt + (size_t)nxt.pn * tstep : cB;
;         for (int t = 0; t < nt; t += 2) {
;             const bool last = (t == nt - 2);
;             const char* a1 = cA + (size_t)(t + 1) * kstep;
;             const char* a2 = last ? nA : cA + (size_t)(t + 2) * kstep; const char* b2 = last ? nB : cB + (size_t)(t + 2) * kstep;
;             const char* a3 = a2 + kstep; const char* b3 = b2 + kstep;
;             if (last && has_next) S.a_ready(nxt);
;             if constexpr (SP2) {
;             PG8_LDB(B0, 0, 0); PG8_LDB(B1, 0, 1); PG8_SCHED; PG8_LDA(At, 0, 0); PG8_STAGE(PG8_SA(1, 1), a1 + hstep, voffA);
;             PG8_WAIT_V(8); PG8_WAIT_L(0); PG8_BAR; PG8_MMA(0, 0, At, B0); PG8_MMA(0, 1, At, B1); PG8_BAR; PG8_SCHED;
;             PG8_LDA(At, 0, 1); PG8_STAGE(PG8_SB(0, 0), b2, voffB); PG8_STAGE(PG8_SB(0, 1), b2 + hstep, voffB); PG8_STAGE(PG8_SA(0, 0), a2, voffA);
;             PG8_WAIT_V(8); PG8_WAIT_L(0); PG8_BAR; PG8_MMA(1, 0, At, B0); PG8_MMA(1, 1, At, B1); PG8_BAR; PG8_SCHED;
.LBB0_121:
	s_add_u32 s22, s46, 0x100
	s_addc_u32 s33, s47, 0
	s_mov_b32 s50, -2
	s_add_u32 s42, s44, 0x100
	s_addc_u32 s43, s45, 0
	s_add_i32 s24, 0, 0x10000
	s_cmp_eq_u32 s50, 8
	s_cselect_b32 s69, s65, s43
	s_cselect_b32 s68, s64, s42
	s_cselect_b32 s47, s67, s33
	s_cselect_b32 s46, s66, s22
	s_add_i32 s51, 0, 0x14000
	v_add_u32_e32 v162, s24, v150
	v_add_u32_e32 v170, s51, v150
	ds_read_b128 v[146:149], v162
	ds_read_b128 v[154:157], v162 offset:1024
	ds_read_b128 v[158:161], v162 offset:2048
	ds_read_b128 v[162:165], v162 offset:3072
	ds_read_b128 v[166:169], v170
	ds_read_b128 v[192:195], v170 offset:1024
	ds_read_b128 v[196:199], v170 offset:2048
	ds_read_b128 v[200:203], v170 offset:3072
	v_lshl_add_u64 v[170:171], s[44:45], 0, v[142:143]
	s_add_i32 m0, s71, 0xc000
	ds_read_b128 v[204:207], v153
	ds_read_b128 v[208:211], v153 offset:1024
	ds_read_b128 v[212:215], v153 offset:2048
	ds_read_b128 v[216:219], v153 offset:3072
	ds_read_b128 v[220:223], v153 offset:4096
	ds_read_b128 v[224:227], v153 offset:5120
	ds_read_b128 v[228:231], v153 offset:6144
	ds_read_b128 v[232:235], v153 offset:7168
	global_load_lds_dwordx4 v[170:171], off
	v_lshl_add_u64 v[170:171], s[44:45], 0, v[144:145]
	s_add_i32 m0, s71, 0xe000
	s_nop 0
	global_load_lds_dwordx4 v[170:171], off
	s_waitcnt vmcnt(8)
	s_waitcnt lgkmcnt(0)
	s_barrier
	s_setprio 1
	v_mfma_f32_16x16x32_bf16 v[124:127], v[146:149], v[204:207], 0
	v_mfma_f32_16x16x32_bf16 v[120:123], v[158:161], v[204:207], 0
	v_mfma_f32_16x16x32_bf16 v[108:111], v[146:149], v[212:215], 0
	v_mfma_f32_16x16x32_bf16 v[104:107], v[158:161], v[212:215], 0
	v_mfma_f32_16x16x32_bf16 v[92:95], v[146:149], v[220:223], 0
	v_mfma_f32_16x16x32_bf16 v[88:91], v[158:161], v[220:223], 0
	v_mfma_f32_16x16x32_bf16 v[76:79], v[146:149], v[228:231], 0
	v_mfma_f32_16x16x32_bf16 v[72:75], v[158:161], v[228:231], 0
	v_mfma_f32_16x16x32_bf16 v[124:127], v[154:157], v[208:211], v[124:127]
	v_mfma_f32_16x16x32_bf16 v[120:123], v[162:165], v[208:211], v[120:123]
	v_mfma_f32_16x16x32_bf16 v[108:111], v[154:157], v[216:219], v[108:111]
	v_mfma_f32_16x16x32_bf16 v[104:107], v[162:165], v[216:219], v[104:107]
	v_mfma_f32_16x16x32_bf16 v[92:95], v[154:157], v[224:227], v[92:95]
	v_mfma_f32_16x16x32_bf16 v[88:91], v[162:165], v[224:227], v[88:91]
	v_mfma_f32_16x16x32_bf16 v[76:79], v[154:157], v[232:235], v[76:79]
	v_mfma_f32_16x16x32_bf16 v[72:75], v[162:165], v[232:235], v[72:75]
	v_mfma_f32_16x16x32_bf16 v[116:119], v[166:169], v[204:207], 0
	v_mfma_f32_16x16x32_bf16 v[112:115], v[196:199], v[204:207], 0
	v_mfma_f32_16x16x32_bf16 v[100:103], v[166:169], v[212:215], 0
	v_mfma_f32_16x16x32_bf16 v[96:99], v[196:199], v[212:215], 0
	v_mfma_f32_16x16x32_bf16 v[84:87], v[166:169], v[220:223], 0
	v_mfma_f32_16x16x32_bf16 v[80:83], v[196:199], v[220:223], 0
	v_mfma_f32_16x16x32_bf16 v[68:71], v[166:169], v[228:231], 0
	v_mfma_f32_16x16x32_bf16 v[64:67], v[196:199], v[228:231], 0
	v_mfma_f32_16x16x32_bf16 v[116:119], v[192:195], v[208:211], v[116:119]
	v_mfma_f32_16x16x32_bf16 v[112:115], v[200:203], v[208:211], v[112:115]
	v_mfma_f32_16x16x32_bf16 v[100:103], v[192:195], v[216:219], v[100:103]
	v_mfma_f32_16x16x32_bf16 v[96:99], v[200:203], v[216:219], v[96:99]
	v_mfma_f32_16x16x32_bf16 v[84:87], v[192:195], v[224:227], v[84:87]
	v_mfma_f32_16x16x32_bf16 v[80:83], v[200:203], v[224:227], v[80:83]
	v_mfma_f32_16x16x32_bf16 v[68:71], v[192:195], v[232:235], v[68:71]
	v_mfma_f32_16x16x32_bf16 v[64:67], v[200:203], v[232:235], v[64:67]
	s_setprio 0
	s_barrier
	s_add_i32 s24, s24, s29
	v_lshl_add_u64 v[170:171], s[46:47], 0, v[128:129]
	s_mov_b32 m0, s24
	ds_read_b128 v[204:207], v153 offset:16384
	ds_read_b128 v[208:211], v153 offset:17408
	ds_read_b128 v[212:215], v153 offset:18432
	ds_read_b128 v[216:219], v153 offset:19456
	ds_read_b128 v[220:223], v153 offset:20480
	ds_read_b128 v[224:227], v153 offset:21504
	ds_read_b128 v[228:231], v153 offset:22528
	ds_read_b128 v[232:235], v153 offset:23552
	global_load_lds_dwordx4 v[170:171], off
	s_add_i32 m0, s24, 0x2000
	s_add_u32 s24, s46, 0x30000
	v_lshl_add_u64 v[236:237], s[46:47], 0, v[130:131]
	s_addc_u32 s25, s47, 0
	s_add_i32 s44, s51, s29
	global_load_lds_dwordx4 v[236:237], off
	v_lshl_add_u64 v[238:239], s[24:25], 0, v[128:129]
	s_mov_b32 m0, s44
	v_lshl_add_u64 v[240:241], s[68:69], 0, v[130:131]
	global_load_lds_dwordx4 v[238:239], off
	v_lshl_add_u64 v[238:239], s[24:25], 0, v[130:131]
	s_add_i32 m0, s44, 0x2000
	s_nop 0
	global_load_lds_dwordx4 v[238:239], off
	v_lshl_add_u64 v[238:239], s[68:69], 0, v[128:129]
	s_mov_b32 m0, s71
	s_nop 0
	global_load_lds_dwordx4 v[238:239], off
	s_mov_b32 m0, s87
	s_nop 0
	global_load_lds_dwordx4 v[240:241], off
	s_waitcnt vmcnt(8)
	s_waitcnt lgkmcnt(0)
	s_barrier
; #define PG8_STAGE(bufoff, gbase, voff) do { _Pragma("unroll") for (int _i = 0; _i < 2; ++_i) \
;         __builtin_amdgcn_global_load_lds((const unsigned*)((const char*)(gbase) + (voff)[_i]), (PG8_LAS unsigned*)(lds + (bufoff) + ldsw + _i * 8192), 16, 0, 0); } while (0)
; #define PG8_LDA(dst, b, h) do { _Pragma("unroll") for (int m = 0; m < 4; ++m) _Pragma("unroll") for (int k = 0; k < 2; ++k) dst[m][k] = *(const PG8_LAS bf16x8*)(lds + PG8_SA(b, h) + aoff + m * 2048 + k * 1024); } while (0)
; #define PG8_LDB(dst, b, h) do { _Pragma("unroll") for (int n = 0; n < 2; ++n) _Pragma("unroll") for (int k = 0; k < 2; ++k) dst[n][k] = *(const PG8_LAS bf16x8*)(lds + PG8_SB(b, h) + boff + n * 2048 + k * 1024); } while (0)
; #define PG8_MMA(ai, bj, At, Bt) do { __builtin_amdgcn_s_setprio(1); _Pragma("unroll") for (int m = 0; m < 4; ++m) _Pragma("unroll") for (int n = 0; n < 2; ++n) _Pragma("unroll") for (int k = 0; k < 2; ++k) \
;         acc[ai][bj][m][n] = __builtin_amdgcn_mfma_f32_16x16x32_bf16(Bt[n][k], At[m][k], acc[ai][bj][m][n], 0, 0, 0); __builtin_amdgcn_s_setprio(0); } while (0)
; #define PG8_WAIT_V(n) asm volatile("s_waitcnt vmcnt(" #n ")" ::: "memory")
; #define PG8_WAIT_L(n) asm volatile("s_waitcnt lgkmcnt(" #n ")" ::: "memory")
; #define PG8_BAR __builtin_amdgcn_s_barrier()
; #define PG8_SCHED __builtin_amdgcn_sched_barrier(0)
; template <class Epi, class Sched, bool ALIGN_EPI = false, bool SP2 = false>
; __device__ __forceinline__ void gemm_phase(PG8_LAS unsigned char* lds, const Gemm g, const Sched& S, const Epi& E) {
;     ...
;             PG8_WAIT_V(8); PG8_WAIT_L(0); PG8_BAR; PG8_MMA(1, 0, At, B0); PG8_MMA(1, 1, At, B1); PG8_BAR; PG8_SCHED;
;             PG8_LDB(B0, 1, 0); PG8_LDB(B1, 1, 1); PG8_SCHED; PG8_LDA(At, 1, 0); PG8_STAGE(PG8_SA(0, 1), a2 + hstep, voffA);
;             PG8_WAIT_V(8); PG8_WAIT_L(0); PG8_BAR; PG8_MMA(0, 0, At, B0); PG8_MMA(0, 1, At, B1); PG8_BAR; PG8_SCHED;
	s_setprio 1
	v_mfma_f32_16x16x32_bf16 v[60:63], v[146:149], v[204:207], 0
	v_mfma_f32_16x16x32_bf16 v[56:59], v[158:161], v[204:207], 0
	v_mfma_f32_16x16x32_bf16 v[44:47], v[146:149], v[212:215], 0
	v_mfma_f32_16x16x32_bf16 v[40:43], v[158:161], v[212:215], 0
	v_mfma_f32_16x16x32_bf16 v[28:31], v[146:149], v[220:223], 0
	v_mfma_f32_16x16x32_bf16 v[24:27], v[158:161], v[220:223], 0
	v_mfma_f32_16x16x32_bf16 v[12:15], v[146:149], v[228:231], 0
	v_mfma_f32_16x16x32_bf16 v[8:11], v[158:161], v[228:231], 0
	v_mfma_f32_16x16x32_bf16 v[60:63], v[154:157], v[208:211], v[60:63]
	v_mfma_f32_16x16x32_bf16 v[56:59], v[162:165], v[208:211], v[56:59]
	v_mfma_f32_16x16x32_bf16 v[44:47], v[154:157], v[216:219], v[44:47]
	v_mfma_f32_16x16x32_bf16 v[40:43], v[162:165], v[216:219], v[40:43]
	v_mfma_f32_16x16x32_bf16 v[28:31], v[154:157], v[224:227], v[28:31]
	v_mfma_f32_16x16x32_bf16 v[24:27], v[162:165], v[224:227], v[24:27]
	v_mfma_f32_16x16x32_bf16 v[12:15], v[154:157], v[232:235], v[12:15]
	v_mfma_f32_16x16x32_bf16 v[8:11], v[162:165], v[232:235], v[8:11]
	v_mfma_f32_16x16x32_bf16 v[52:55], v[166:169], v[204:207], 0
	v_mfma_f32_16x16x32_bf16 v[48:51], v[196:199], v[204:207], 0
	v_mfma_f32_16x16x32_bf16 v[36:39], v[166:169], v[212:215], 0
	v_mfma_f32_16x16x32_bf16 v[32:35], v[196:199], v[212:215], 0
	v_mfma_f32_16x16x32_bf16 v[20:23], v[166:169], v[220:223], 0
	v_mfma_f32_16x16x32_bf16 v[16:19], v[196:199], v[220:223], 0
	v_mfma_f32_16x16x32_bf16 v[4:7], v[166:169], v[228:231], 0
	v_mfma_f32_16x16x32_bf16 v[0:3], v[196:199], v[228:231], 0
	v_mfma_f32_16x16x32_bf16 v[52:55], v[192:195], v[208:211], v[52:55]
	v_mfma_f32_16x16x32_bf16 v[48:51], v[200:203], v[208:211], v[48:51]
	v_mfma_f32_16x16x32_bf16 v[36:39], v[192:195], v[216:219], v[36:39]
	v_mfma_f32_16x16x32_bf16 v[32:35], v[200:203], v[216:219], v[32:35]
	v_mfma_f32_16x16x32_bf16 v[20:23], v[192:195], v[224:227], v[20:23]
	v_mfma_f32_16x16x32_bf16 v[16:19], v[200:203], v[224:227], v[16:19]
	v_mfma_f32_16x16x32_bf16 v[4:7], v[192:195], v[232:235], v[4:7]
	v_mfma_f32_16x16x32_bf16 v[0:3], v[200:203], v[232:235], v[0:3]
	s_setprio 0
	s_barrier
	s_add_i32 s44, 0, 0x18000
	s_add_i32 s45, 0, 0x1c000
	v_add_u32_e32 v162, s44, v150
	v_add_u32_e32 v184, s45, v150
	ds_read_b128 v[146:149], v162
	ds_read_b128 v[154:157], v162 offset:1024
	ds_read_b128 v[158:161], v162 offset:2048
	ds_read_b128 v[162:165], v162 offset:3072
	ds_read_b128 v[166:169], v184
	ds_read_b128 v[192:195], v184 offset:1024
	ds_read_b128 v[196:199], v184 offset:2048
	ds_read_b128 v[200:203], v184 offset:3072
	s_add_u32 s24, s68, 0x30000
	s_addc_u32 s25, s69, 0
	s_mov_b32 m0, s88
	v_lshl_add_u64 v[242:243], s[24:25], 0, v[128:129]
	ds_read_b128 v[204:207], v153 offset:32768
	ds_read_b128 v[208:211], v153 offset:33792
	ds_read_b128 v[212:215], v153 offset:34816
	ds_read_b128 v[216:219], v153 offset:35840
	ds_read_b128 v[220:223], v153 offset:36864
	ds_read_b128 v[224:227], v153 offset:37888
	ds_read_b128 v[228:231], v153 offset:38912
	ds_read_b128 v[232:235], v153 offset:39936
	global_load_lds_dwordx4 v[242:243], off
	v_lshl_add_u64 v[242:243], s[24:25], 0, v[130:131]
	s_mov_b32 m0, s89
	s_nop 0
	global_load_lds_dwordx4 v[242:243], off
	s_waitcnt vmcnt(8)
	s_waitcnt lgkmcnt(0)
	s_barrier
	s_setprio 1
	v_mfma_f32_16x16x32_bf16 v[124:127], v[146:149], v[204:207], v[124:127]
	v_mfma_f32_16x16x32_bf16 v[120:123], v[158:161], v[204:207], v[120:123]
	v_mfma_f32_16x16x32_bf16 v[108:111], v[146:149], v[212:215], v[108:111]
	v_mfma_f32_16x16x32_bf16 v[104:107], v[158:161], v[212:215], v[104:107]
	v_mfma_f32_16x16x32_bf16 v[92:95], v[146:149], v[220:223], v[92:95]
	v_mfma_f32_16x16x32_bf16 v[88:91], v[158:161], v[220:223], v[88:91]
	v_mfma_f32_16x16x32_bf16 v[76:79], v[146:149], v[228:231], v[76:79]
	v_mfma_f32_16x16x32_bf16 v[72:75], v[158:161], v[228:231], v[72:75]
	v_mfma_f32_16x16x32_bf16 v[124:127], v[154:157], v[208:211], v[124:127]
	v_mfma_f32_16x16x32_bf16 v[120:123], v[162:165], v[208:211], v[120:123]
	v_mfma_f32_16x16x32_bf16 v[108:111], v[154:157], v[216:219], v[108:111]
	v_mfma_f32_16x16x32_bf16 v[104:107], v[162:165], v[216:219], v[104:107]
	v_mfma_f32_16x16x32_bf16 v[92:95], v[154:157], v[224:227], v[92:95]
	v_mfma_f32_16x16x32_bf16 v[88:91], v[162:165], v[224:227], v[88:91]
	v_mfma_f32_16x16x32_bf16 v[76:79], v[154:157], v[232:235], v[76:79]
	v_mfma_f32_16x16x32_bf16 v[72:75], v[162:165], v[232:235], v[72:75]
	v_mfma_f32_16x16x32_bf16 v[116:119], v[166:169], v[204:207], v[116:119]
	v_mfma_f32_16x16x32_bf16 v[112:115], v[196:199], v[204:207], v[112:115]
	v_mfma_f32_16x16x32_bf16 v[100:103], v[166:169], v[212:215], v[100:103]
	v_mfma_f32_16x16x32_bf16 v[96:99], v[196:199], v[212:215], v[96:99]
	v_mfma_f32_16x16x32_bf16 v[84:87], v[166:169], v[220:223], v[84:87]
	v_mfma_f32_16x16x32_bf16 v[80:83], v[196:199], v[220:223], v[80:83]
	v_mfma_f32_16x16x32_bf16 v[68:71], v[166:169], v[228:231], v[68:71]
	v_mfma_f32_16x16x32_bf16 v[64:67], v[196:199], v[228:231], v[64:67]
	v_mfma_f32_16x16x32_bf16 v[116:119], v[192:195], v[208:211], v[116:119]
	v_mfma_f32_16x16x32_bf16 v[112:115], v[200:203], v[208:211], v[112:115]
	v_mfma_f32_16x16x32_bf16 v[100:103], v[192:195], v[216:219], v[100:103]
	v_mfma_f32_16x16x32_bf16 v[96:99], v[200:203], v[216:219], v[96:99]
	v_mfma_f32_16x16x32_bf16 v[84:87], v[192:195], v[224:227], v[84:87]
	v_mfma_f32_16x16x32_bf16 v[80:83], v[200:203], v[224:227], v[80:83]
	v_mfma_f32_16x16x32_bf16 v[68:71], v[192:195], v[232:235], v[68:71]
	v_mfma_f32_16x16x32_bf16 v[64:67], v[200:203], v[232:235], v[64:67]
	s_setprio 0
	s_barrier
; #define PG8_STAGE(bufoff, gbase, voff) do { _Pragma("unroll") for (int _i = 0; _i < 2; ++_i) \
;         __builtin_amdgcn_global_load_lds((const unsigned*)((const char*)(gbase) + (voff)[_i]), (PG8_LAS unsigned*)(lds + (bufoff) + ldsw + _i * 8192), 16, 0, 0); } while (0)
; #define PG8_LDA(dst, b, h) do { _Pragma("unroll") for (int m = 0; m < 4; ++m) _Pragma("unroll") for (int k = 0; k < 2; ++k) dst[m][k] = *(const PG8_LAS bf16x8*)(lds + PG8_SA(b, h) + aoff + m * 2048 + k * 1024); } while (0)
; #define PG8_LDB(dst, b, h) do { _Pragma("unroll") for (int n = 0; n < 2; ++n) _Pragma("unroll") for (int k = 0; k < 2; ++k) dst[n][k] = *(const PG8_LAS bf16x8*)(lds + PG8_SB(b, h) + boff + n * 2048 + k * 1024); } while (0)
; template <class Epi, class Sched, bool ALIGN_EPI = false, bool SP2 = false>
; __device__ __forceinline__ void gemm_phase(PG8_LAS unsigned char* lds, const Gemm g, const Sched& S, const Epi& E) {
;     ...
;         for (int t = 0; t < nt; t += 2) {
;             const bool last = (t == nt - 2);
;             const char* a1 = cA + (size_t)(t + 1) * kstep;
;             const char* a2 = last ? nA : cA + (size_t)(t + 2) * kstep; const char* b2 = last ? nB : cB + (size_t)(t + 2) * kstep;
;             const char* a3 = a2 + kstep; const char* b3 = b2 + kstep;
;             if (last && has_next) S.a_ready(nxt);
;             if constexpr (SP2) {
;             PG8_LDB(B0, 0, 0); PG8_LDB(B1, 0, 1); PG8_SCHED; PG8_LDA(At, 0, 0); PG8_STAGE(PG8_SA(1, 1), a1 + hstep, voffA);
;             PG8_WAIT_V(8); PG8_WAIT_L(0); PG8_BAR; PG8_MMA(0, 0, At, B0); PG8_MMA(0, 1, At, B1); PG8_BAR; PG8_SCHED;
;             PG8_LDA(At, 0, 1); PG8_STAGE(PG8_SB(0, 0), b2, voffB); PG8_STAGE(PG8_SB(0, 1), b2 + hstep, voffB); PG8_STAGE(PG8_SA(0, 0), a2, voffA);
;             PG8_WAIT_V(8); PG8_WAIT_L(0); PG8_BAR; PG8_MMA(1, 0, At, B0); PG8_MMA(1, 1, At, B1); PG8_BAR; PG8_SCHED;
;             PG8_LDB(B0, 1, 0); PG8_LDB(B1, 1, 1); PG8_SCHED; PG8_LDA(At, 1, 0); PG8_STAGE(PG8_SA(0, 1), a2 + hstep, voffA);
;             PG8_WAIT_V(8); PG8_WAIT_L(0); PG8_BAR; PG8_MMA(0, 0, At, B0); PG8_MMA(0, 1, At, B1); PG8_BAR; PG8_SCHED;
;             PG8_LDA(At, 1, 1); PG8_STAGE(PG8_SB(1, 0), b3, voffB); PG8_STAGE(PG8_SB(1, 1), b3 + hstep, voffB); PG8_STAGE(PG8_SA(1, 0), a3, voffA);
;             PG8_WAIT_V(8); PG8_WAIT_L(0); PG8_BAR; PG8_MMA(1, 0, At, B0); PG8_MMA(1, 1, At, B1); PG8_BAR; PG8_SCHED;
	s_add_i32 s24, s44, s29
	v_lshl_add_u64 v[170:171], v[170:171], 0, s[14:15]
	s_mov_b32 m0, s24
	ds_read_b128 v[204:207], v153 offset:49152
	ds_read_b128 v[208:211], v153 offset:50176
	ds_read_b128 v[212:215], v153 offset:51200
	ds_read_b128 v[216:219], v153 offset:52224
	ds_read_b128 v[220:223], v153 offset:53248
	ds_read_b128 v[224:227], v153 offset:54272
	ds_read_b128 v[228:231], v153 offset:55296
	ds_read_b128 v[232:235], v153 offset:56320
	global_load_lds_dwordx4 v[170:171], off
	s_add_i32 m0, s24, 0x2000
	s_add_u32 s24, s46, 0x30080
	v_lshl_add_u64 v[170:171], v[236:237], 0, s[14:15]
	s_addc_u32 s25, s47, 0
	s_add_i32 s44, s45, s29
	global_load_lds_dwordx4 v[170:171], off
	v_lshl_add_u64 v[170:171], s[24:25], 0, v[128:129]
	s_mov_b32 m0, s44
	s_nop 0
	global_load_lds_dwordx4 v[170:171], off
	v_lshl_add_u64 v[170:171], s[24:25], 0, v[130:131]
	s_add_i32 m0, s44, 0x2000
	s_nop 0
	global_load_lds_dwordx4 v[170:171], off
	v_lshl_add_u64 v[170:171], v[238:239], 0, s[14:15]
	s_mov_b32 m0, s91
	s_nop 0
	global_load_lds_dwordx4 v[170:171], off
	v_lshl_add_u64 v[170:171], v[240:241], 0, s[14:15]
	s_mov_b32 m0, s92
	s_nop 0
	global_load_lds_dwordx4 v[170:171], off
	s_waitcnt vmcnt(8)
	s_waitcnt lgkmcnt(0)
	s_barrier
	s_setprio 1
	v_mfma_f32_16x16x32_bf16 v[60:63], v[146:149], v[204:207], v[60:63]
	v_mfma_f32_16x16x32_bf16 v[56:59], v[158:161], v[204:207], v[56:59]
	v_mfma_f32_16x16x32_bf16 v[44:47], v[146:149], v[212:215], v[44:47]
	v_mfma_f32_16x16x32_bf16 v[40:43], v[158:161], v[212:215], v[40:43]
	v_mfma_f32_16x16x32_bf16 v[28:31], v[146:149], v[220:223], v[28:31]
	v_mfma_f32_16x16x32_bf16 v[24:27], v[158:161], v[220:223], v[24:27]
	v_mfma_f32_16x16x32_bf16 v[12:15], v[146:149], v[228:231], v[12:15]
	v_mfma_f32_16x16x32_bf16 v[8:11], v[158:161], v[228:231], v[8:11]
	v_mfma_f32_16x16x32_bf16 v[60:63], v[154:157], v[208:211], v[60:63]
	v_mfma_f32_16x16x32_bf16 v[56:59], v[162:165], v[208:211], v[56:59]
	v_mfma_f32_16x16x32_bf16 v[44:47], v[154:157], v[216:219], v[44:47]
	v_mfma_f32_16x16x32_bf16 v[40:43], v[162:165], v[216:219], v[40:43]
	v_mfma_f32_16x16x32_bf16 v[28:31], v[154:157], v[224:227], v[28:31]
	v_mfma_f32_16x16x32_bf16 v[24:27], v[162:165], v[224:227], v[24:27]
	v_mfma_f32_16x16x32_bf16 v[12:15], v[154:157], v[232:235], v[12:15]
	v_mfma_f32_16x16x32_bf16 v[8:11], v[162:165], v[232:235], v[8:11]
	v_mfma_f32_16x16x32_bf16 v[52:55], v[166:169], v[204:207], v[52:55]
	v_mfma_f32_16x16x32_bf16 v[48:51], v[196:199], v[204:207], v[48:51]
	v_mfma_f32_16x16x32_bf16 v[36:39], v[166:169], v[212:215], v[36:39]
	v_mfma_f32_16x16x32_bf16 v[32:35], v[196:199], v[212:215], v[32:35]
	v_mfma_f32_16x16x32_bf16 v[20:23], v[166:169], v[220:223], v[20:23]
	v_mfma_f32_16x16x32_bf16 v[16:19], v[196:199], v[220:223], v[16:19]
	v_mfma_f32_16x16x32_bf16 v[4:7], v[166:169], v[228:231], v[4:7]
	v_mfma_f32_16x16x32_bf16 v[0:3], v[196:199], v[228:231], v[0:3]
	v_mfma_f32_16x16x32_bf16 v[52:55], v[192:195], v[208:211], v[52:55]
	v_mfma_f32_16x16x32_bf16 v[48:51], v[200:203], v[208:211], v[48:51]
	v_mfma_f32_16x16x32_bf16 v[36:39], v[192:195], v[216:219], v[36:39]
	v_mfma_f32_16x16x32_bf16 v[32:35], v[200:203], v[216:219], v[32:35]
	v_mfma_f32_16x16x32_bf16 v[20:23], v[192:195], v[224:227], v[20:23]
	v_mfma_f32_16x16x32_bf16 v[16:19], v[200:203], v[224:227], v[16:19]
	v_mfma_f32_16x16x32_bf16 v[4:7], v[192:195], v[232:235], v[4:7]
	v_mfma_f32_16x16x32_bf16 v[0:3], v[200:203], v[232:235], v[0:3]
	s_setprio 0
	s_barrier
	s_add_i32 s50, s50, 2
	s_add_u32 s22, s22, 0x100
	s_addc_u32 s33, s33, 0
	s_cmp_gt_u32 s50, 9
	s_mov_b64 s[44:45], s[42:43]
.LBB0_122:
	s_add_u32 s42, s44, 0x100
	s_addc_u32 s43, s45, 0
	s_add_i32 s24, 0, 0x10000
	s_cmp_eq_u32 s50, 8
	s_cselect_b32 s69, s65, s43
	s_cselect_b32 s68, s64, s42
	s_cselect_b32 s47, s67, s33
	s_cselect_b32 s46, s66, s22
	s_add_i32 s51, 0, 0x14000
	v_add_u32_e32 v162, s24, v150
	v_add_u32_e32 v170, s51, v150
	ds_read_b128 v[146:149], v162
	ds_read_b128 v[154:157], v162 offset:1024
	ds_read_b128 v[158:161], v162 offset:2048
	ds_read_b128 v[162:165], v162 offset:3072
	ds_read_b128 v[166:169], v170
	ds_read_b128 v[192:195], v170 offset:1024
	ds_read_b128 v[196:199], v170 offset:2048
	ds_read_b128 v[200:203], v170 offset:3072
	v_lshl_add_u64 v[170:171], s[44:45], 0, v[142:143]
	s_add_i32 m0, s71, 0xc000
	ds_read_b128 v[204:207], v153
	ds_read_b128 v[208:211], v153 offset:1024
	ds_read_b128 v[212:215], v153 offset:2048
	ds_read_b128 v[216:219], v153 offset:3072
	ds_read_b128 v[220:223], v153 offset:4096
	ds_read_b128 v[224:227], v153 offset:5120
	ds_read_b128 v[228:231], v153 offset:6144
	ds_read_b128 v[232:235], v153 offset:7168
	global_load_lds_dwordx4 v[170:171], off
	v_lshl_add_u64 v[170:171], s[44:45], 0, v[144:145]
	s_add_i32 m0, s71, 0xe000
	s_nop 0
	global_load_lds_dwordx4 v[170:171], off
	s_waitcnt vmcnt(8)
	s_waitcnt lgkmcnt(0)
	s_barrier
; #define PG8_STAGE(bufoff, gbase, voff) do { _Pragma("unroll") for (int _i = 0; _i < 2; ++_i) \
;         __builtin_amdgcn_global_load_lds((const unsigned*)((const char*)(gbase) + (voff)[_i]), (PG8_LAS unsigned*)(lds + (bufoff) + ldsw + _i * 8192), 16, 0, 0); } while (0)
; #define PG8_LDA(dst, b, h) do { _Pragma("unroll") for (int m = 0; m < 4; ++m) _Pragma("unroll") for (int k = 0; k < 2; ++k) dst[m][k] = *(const PG8_LAS bf16x8*)(lds + PG8_SA(b, h) + aoff + m * 2048 + k * 1024); } while (0)
; #define PG8_LDB(dst, b, h) do { _Pragma("unroll") for (int n = 0; n < 2; ++n) _Pragma("unroll") for (int k = 0; k < 2; ++k) dst[n][k] = *(const PG8_LAS bf16x8*)(lds + PG8_SB(b, h) + boff + n * 2048 + k * 1024); } while (0)
; #define PG8_MMA(ai, bj, At, Bt) do { __builtin_amdgcn_s_setprio(1); _Pragma("unroll") for (int m = 0; m < 4; ++m) _Pragma("unroll") for (int n = 0; n < 2; ++n) _Pragma("unroll") for (int k = 0; k < 2; ++k) \
;         acc[ai][bj][m][n] = __builtin_amdgcn_mfma_f32_16x16x32_bf16(Bt[n][k], At[m][k], acc[ai][bj][m][n], 0, 0, 0); __builtin_amdgcn_s_setprio(0); } while (0)
; #define PG8_WAIT_V(n) asm volatile("s_waitcnt vmcnt(" #n ")" ::: "memory")
; #define PG8_WAIT_L(n) asm volatile("s_waitcnt lgkmcnt(" #n ")" ::: "memory")
; #define PG8_BAR __builtin_amdgcn_s_barrier()
; #define PG8_SCHED __builtin_amdgcn_sched_barrier(0)
; template <class Epi, class Sched, bool ALIGN_EPI = false, bool SP2 = false>
; __device__ __forceinline__ void gemm_phase(PG8_LAS unsigned char* lds, const Gemm g, const Sched& S, const Epi& E) {
;     ...
;             PG8_LDB(B0, 0, 0); PG8_LDB(B1, 0, 1); PG8_SCHED; PG8_LDA(At, 0, 0); PG8_STAGE(PG8_SA(1, 1), a1 + hstep, voffA);
;             PG8_WAIT_V(8); PG8_WAIT_L(0); PG8_BAR; PG8_MMA(0, 0, At, B0); PG8_MMA(0, 1, At, B1); PG8_BAR; PG8_SCHED;
;             PG8_LDA(At, 0, 1); PG8_STAGE(PG8_SB(0, 0), b2, voffB); PG8_STAGE(PG8_SB(0, 1), b2 + hstep, voffB); PG8_STAGE(PG8_SA(0, 0), a2, voffA);
;             PG8_WAIT_V(8); PG8_WAIT_L(0); PG8_BAR; PG8_MMA(1, 0, At, B0); PG8_MMA(1, 1, At, B1); PG8_BAR; PG8_SCHED;
	s_setprio 1
	v_mfma_f32_16x16x32_bf16 v[124:127], v[146:149], v[204:207], v[124:127]
	v_mfma_f32_16x16x32_bf16 v[120:123], v[158:161], v[204:207], v[120:123]
	v_mfma_f32_16x16x32_bf16 v[108:111], v[146:149], v[212:215], v[108:111]
	v_mfma_f32_16x16x32_bf16 v[104:107], v[158:161], v[212:215], v[104:107]
	v_mfma_f32_16x16x32_bf16 v[92:95], v[146:149], v[220:223], v[92:95]
	v_mfma_f32_16x16x32_bf16 v[88:91], v[158:161], v[220:223], v[88:91]
	v_mfma_f32_16x16x32_bf16 v[76:79], v[146:149], v[228:231], v[76:79]
	v_mfma_f32_16x16x32_bf16 v[72:75], v[158:161], v[228:231], v[72:75]
	v_mfma_f32_16x16x32_bf16 v[124:127], v[154:157], v[208:211], v[124:127]
	v_mfma_f32_16x16x32_bf16 v[120:123], v[162:165], v[208:211], v[120:123]
	v_mfma_f32_16x16x32_bf16 v[108:111], v[154:157], v[216:219], v[108:111]
	v_mfma_f32_16x16x32_bf16 v[104:107], v[162:165], v[216:219], v[104:107]
	v_mfma_f32_16x16x32_bf16 v[92:95], v[154:157], v[224:227], v[92:95]
	v_mfma_f32_16x16x32_bf16 v[88:91], v[162:165], v[224:227], v[88:91]
	v_mfma_f32_16x16x32_bf16 v[76:79], v[154:157], v[232:235], v[76:79]
	v_mfma_f32_16x16x32_bf16 v[72:75], v[162:165], v[232:235], v[72:75]
	v_mfma_f32_16x16x32_bf16 v[116:119], v[166:169], v[204:207], v[116:119]
	v_mfma_f32_16x16x32_bf16 v[112:115], v[196:199], v[204:207], v[112:115]
	v_mfma_f32_16x16x32_bf16 v[100:103], v[166:169], v[212:215], v[100:103]
	v_mfma_f32_16x16x32_bf16 v[96:99], v[196:199], v[212:215], v[96:99]
	v_mfma_f32_16x16x32_bf16 v[84:87], v[166:169], v[220:223], v[84:87]
	v_mfma_f32_16x16x32_bf16 v[80:83], v[196:199], v[220:223], v[80:83]
	v_mfma_f32_16x16x32_bf16 v[68:71], v[166:169], v[228:231], v[68:71]
	v_mfma_f32_16x16x32_bf16 v[64:67], v[196:199], v[228:231], v[64:67]
	v_mfma_f32_16x16x32_bf16 v[116:119], v[192:195], v[208:211], v[116:119]
	v_mfma_f32_16x16x32_bf16 v[112:115], v[200:203], v[208:211], v[112:115]
	v_mfma_f32_16x16x32_bf16 v[100:103], v[192:195], v[216:219], v[100:103]
	v_mfma_f32_16x16x32_bf16 v[96:99], v[200:203], v[216:219], v[96:99]
	v_mfma_f32_16x16x32_bf16 v[84:87], v[192:195], v[224:227], v[84:87]
	v_mfma_f32_16x16x32_bf16 v[80:83], v[200:203], v[224:227], v[80:83]
	v_mfma_f32_16x16x32_bf16 v[68:71], v[192:195], v[232:235], v[68:71]
	v_mfma_f32_16x16x32_bf16 v[64:67], v[200:203], v[232:235], v[64:67]
	s_setprio 0
	s_barrier
	s_add_i32 s24, s24, s29
	v_lshl_add_u64 v[170:171], s[46:47], 0, v[128:129]
	s_mov_b32 m0, s24
	ds_read_b128 v[204:207], v153 offset:16384
	ds_read_b128 v[208:211], v153 offset:17408
	ds_read_b128 v[212:215], v153 offset:18432
	ds_read_b128 v[216:219], v153 offset:19456
	ds_read_b128 v[220:223], v153 offset:20480
	ds_read_b128 v[224:227], v153 offset:21504
	ds_read_b128 v[228:231], v153 offset:22528
	ds_read_b128 v[232:235], v153 offset:23552
	global_load_lds_dwordx4 v[170:171], off
	s_add_i32 m0, s24, 0x2000
	s_add_u32 s24, s46, 0x30000
	v_lshl_add_u64 v[236:237], s[46:47], 0, v[130:131]
	s_addc_u32 s25, s47, 0
	s_add_i32 s44, s51, s29
	global_load_lds_dwordx4 v[236:237], off
	v_lshl_add_u64 v[238:239], s[24:25], 0, v[128:129]
	s_mov_b32 m0, s44
	v_lshl_add_u64 v[240:241], s[68:69], 0, v[130:131]
	global_load_lds_dwordx4 v[238:239], off
	v_lshl_add_u64 v[238:239], s[24:25], 0, v[130:131]
	s_add_i32 m0, s44, 0x2000
	s_nop 0
	global_load_lds_dwordx4 v[238:239], off
	v_lshl_add_u64 v[238:239], s[68:69], 0, v[128:129]
	s_mov_b32 m0, s71
	s_nop 0
	global_load_lds_dwordx4 v[238:239], off
	s_mov_b32 m0, s87
	s_nop 0
	global_load_lds_dwordx4 v[240:241], off
	s_waitcnt vmcnt(8)
	s_waitcnt lgkmcnt(0)
	s_barrier
	s_setprio 1
	v_mfma_f32_16x16x32_bf16 v[60:63], v[146:149], v[204:207], v[60:63]
	v_mfma_f32_16x16x32_bf16 v[56:59], v[158:161], v[204:207], v[56:59]
	v_mfma_f32_16x16x32_bf16 v[44:47], v[146:149], v[212:215], v[44:47]
	v_mfma_f32_16x16x32_bf16 v[40:43], v[158:161], v[212:215], v[40:43]
	v_mfma_f32_16x16x32_bf16 v[28:31], v[146:149], v[220:223], v[28:31]
	v_mfma_f32_16x16x32_bf16 v[24:27], v[158:161], v[220:223], v[24:27]
	v_mfma_f32_16x16x32_bf16 v[12:15], v[146:149], v[228:231], v[12:15]
	v_mfma_f32_16x16x32_bf16 v[8:11], v[158:161], v[228:231], v[8:11]
	v_mfma_f32_16x16x32_bf16 v[60:63], v[154:157], v[208:211], v[60:63]
	v_mfma_f32_16x16x32_bf16 v[56:59], v[162:165], v[208:211], v[56:59]
	v_mfma_f32_16x16x32_bf16 v[44:47], v[154:157], v[216:219], v[44:47]
	v_mfma_f32_16x16x32_bf16 v[40:43], v[162:165], v[216:219], v[40:43]
	v_mfma_f32_16x16x32_bf16 v[28:31], v[154:157], v[224:227], v[28:31]
	v_mfma_f32_16x16x32_bf16 v[24:27], v[162:165], v[224:227], v[24:27]
	v_mfma_f32_16x16x32_bf16 v[12:15], v[154:157], v[232:235], v[12:15]
	v_mfma_f32_16x16x32_bf16 v[8:11], v[162:165], v[232:235], v[8:11]
	v_mfma_f32_16x16x32_bf16 v[52:55], v[166:169], v[204:207], v[52:55]
	v_mfma_f32_16x16x32_bf16 v[48:51], v[196:199], v[204:207], v[48:51]
	v_mfma_f32_16x16x32_bf16 v[36:39], v[166:169], v[212:215], v[36:39]
	v_mfma_f32_16x16x32_bf16 v[32:35], v[196:199], v[212:215], v[32:35]
	v_mfma_f32_16x16x32_bf16 v[20:23], v[166:169], v[220:223], v[20:23]
	v_mfma_f32_16x16x32_bf16 v[16:19], v[196:199], v[220:223], v[16:19]
	v_mfma_f32_16x16x32_bf16 v[4:7], v[166:169], v[228:231], v[4:7]
	v_mfma_f32_16x16x32_bf16 v[0:3], v[196:199], v[228:231], v[0:3]
	v_mfma_f32_16x16x32_bf16 v[52:55], v[192:195], v[208:211], v[52:55]
	v_mfma_f32_16x16x32_bf16 v[48:51], v[200:203], v[208:211], v[48:51]
	v_mfma_f32_16x16x32_bf16 v[36:39], v[192:195], v[216:219], v[36:39]
	v_mfma_f32_16x16x32_bf16 v[32:35], v[200:203], v[216:219], v[32:35]
	v_mfma_f32_16x16x32_bf16 v[20:23], v[192:195], v[224:227], v[20:23]
	v_mfma_f32_16x16x32_bf16 v[16:19], v[200:203], v[224:227], v[16:19]
	v_mfma_f32_16x16x32_bf16 v[4:7], v[192:195], v[232:235], v[4:7]
	v_mfma_f32_16x16x32_bf16 v[0:3], v[200:203], v[232:235], v[0:3]
	s_setprio 0
	s_barrier
; #define PG8_STAGE(bufoff, gbase, voff) do { _Pragma("unroll") for (int _i = 0; _i < 2; ++_i) \
;         __builtin_amdgcn_global_load_lds((const unsigned*)((const char*)(gbase) + (voff)[_i]), (PG8_LAS unsigned*)(lds + (bufoff) + ldsw + _i * 8192), 16, 0, 0); } while (0)
; #define PG8_LDA(dst, b, h) do { _Pragma("unroll") for (int m = 0; m < 4; ++m) _Pragma("unroll") for (int k = 0; k < 2; ++k) dst[m][k] = *(const PG8_LAS bf16x8*)(lds + PG8_SA(b, h) + aoff + m * 2048 + k * 1024); } while (0)
; #define PG8_LDB(dst, b, h) do { _Pragma("unroll") for (int n = 0; n < 2; ++n) _Pragma("unroll") for (int k = 0; k < 2; ++k) dst[n][k] = *(const PG8_LAS bf16x8*)(lds + PG8_SB(b, h) + boff + n * 2048 + k * 1024); } while (0)
; #define PG8_MMA(ai, bj, At, Bt) do { __builtin_amdgcn_s_setprio(1); _Pragma("unroll") for (int m = 0; m < 4; ++m) _Pragma("unroll") for (int n = 0; n < 2; ++n) _Pragma("unroll") for (int k = 0; k < 2; ++k) \
;         acc[ai][bj][m][n] = __builtin_amdgcn_mfma_f32_16x16x32_bf16(Bt[n][k], At[m][k], acc[ai][bj][m][n], 0, 0, 0); __builtin_amdgcn_s_setprio(0); } while (0)
; #define PG8_WAIT_V(n) asm volatile("s_waitcnt vmcnt(" #n ")" ::: "memory")
; #define PG8_WAIT_L(n) asm volatile("s_waitcnt lgkmcnt(" #n ")" ::: "memory")
; #define PG8_BAR __builtin_amdgcn_s_barrier()
; #define PG8_SCHED __builtin_amdgcn_sched_barrier(0)
; template <class Epi, class Sched, bool ALIGN_EPI = false, bool SP2 = false>
; __device__ __forceinline__ void gemm_phase(PG8_LAS unsigned char* lds, const Gemm g, const Sched& S, const Epi& E) {
;     ...
;             PG8_LDB(B0, 1, 0); PG8_LDB(B1, 1, 1); PG8_SCHED; PG8_LDA(At, 1, 0); PG8_STAGE(PG8_SA(0, 1), a2 + hstep, voffA);
;             PG8_WAIT_V(8); PG8_WAIT_L(0); PG8_BAR; PG8_MMA(0, 0, At, B0); PG8_MMA(0, 1, At, B1); PG8_BAR; PG8_SCHED;
	s_add_i32 s44, 0, 0x18000
	s_add_i32 s45, 0, 0x1c000
	v_add_u32_e32 v162, s44, v150
	v_add_u32_e32 v184, s45, v150
	ds_read_b128 v[146:149], v162
	ds_read_b128 v[154:157], v162 offset:1024
	ds_read_b128 v[158:161], v162 offset:2048
	ds_read_b128 v[162:165], v162 offset:3072
	ds_read_b128 v[166:169], v184
	ds_read_b128 v[192:195], v184 offset:1024
	ds_read_b128 v[196:199], v184 offset:2048
	ds_read_b128 v[200:203], v184 offset:3072
	s_add_u32 s24, s68, 0x30000
	s_addc_u32 s25, s69, 0
	s_mov_b32 m0, s88
	v_lshl_add_u64 v[242:243], s[24:25], 0, v[128:129]
	ds_read_b128 v[204:207], v153 offset:32768
	ds_read_b128 v[208:211], v153 offset:33792
	ds_read_b128 v[212:215], v153 offset:34816
	ds_read_b128 v[216:219], v153 offset:35840
	ds_read_b128 v[220:223], v153 offset:36864
	ds_read_b128 v[224:227], v153 offset:37888
	ds_read_b128 v[228:231], v153 offset:38912
	ds_read_b128 v[232:235], v153 offset:39936
	global_load_lds_dwordx4 v[242:243], off
	v_lshl_add_u64 v[242:243], s[24:25], 0, v[130:131]
	s_mov_b32 m0, s89
	s_nop 0
	global_load_lds_dwordx4 v[242:243], off
	s_waitcnt vmcnt(8)
	s_waitcnt lgkmcnt(0)
	s_barrier
	s_setprio 1
	v_mfma_f32_16x16x32_bf16 v[124:127], v[146:149], v[204:207], v[124:127]
	v_mfma_f32_16x16x32_bf16 v[120:123], v[158:161], v[204:207], v[120:123]
	v_mfma_f32_16x16x32_bf16 v[108:111], v[146:149], v[212:215], v[108:111]
	v_mfma_f32_16x16x32_bf16 v[104:107], v[158:161], v[212:215], v[104:107]
	v_mfma_f32_16x16x32_bf16 v[92:95], v[146:149], v[220:223], v[92:95]
	v_mfma_f32_16x16x32_bf16 v[88:91], v[158:161], v[220:223], v[88:91]
	v_mfma_f32_16x16x32_bf16 v[76:79], v[146:149], v[228:231], v[76:79]
	v_mfma_f32_16x16x32_bf16 v[72:75], v[158:161], v[228:231], v[72:75]
	v_mfma_f32_16x16x32_bf16 v[124:127], v[154:157], v[208:211], v[124:127]
	v_mfma_f32_16x16x32_bf16 v[120:123], v[162:165], v[208:211], v[120:123]
	v_mfma_f32_16x16x32_bf16 v[108:111], v[154:157], v[216:219], v[108:111]
	v_mfma_f32_16x16x32_bf16 v[104:107], v[162:165], v[216:219], v[104:107]
	v_mfma_f32_16x16x32_bf16 v[92:95], v[154:157], v[224:227], v[92:95]
	v_mfma_f32_16x16x32_bf16 v[88:91], v[162:165], v[224:227], v[88:91]
	v_mfma_f32_16x16x32_bf16 v[76:79], v[154:157], v[232:235], v[76:79]
	v_mfma_f32_16x16x32_bf16 v[72:75], v[162:165], v[232:235], v[72:75]
	v_mfma_f32_16x16x32_bf16 v[116:119], v[166:169], v[204:207], v[116:119]
	v_mfma_f32_16x16x32_bf16 v[112:115], v[196:199], v[204:207], v[112:115]
	v_mfma_f32_16x16x32_bf16 v[100:103], v[166:169], v[212:215], v[100:103]
	v_mfma_f32_16x16x32_bf16 v[96:99], v[196:199], v[212:215], v[96:99]
	v_mfma_f32_16x16x32_bf16 v[84:87], v[166:169], v[220:223], v[84:87]
	v_mfma_f32_16x16x32_bf16 v[80:83], v[196:199], v[220:223], v[80:83]
	v_mfma_f32_16x16x32_bf16 v[68:71], v[166:169], v[228:231], v[68:71]
	v_mfma_f32_16x16x32_bf16 v[64:67], v[196:199], v[228:231], v[64:67]
	v_mfma_f32_16x16x32_bf16 v[116:119], v[192:195], v[208:211], v[116:119]
	v_mfma_f32_16x16x32_bf16 v[112:115], v[200:203], v[208:211], v[112:115]
	v_mfma_f32_16x16x32_bf16 v[100:103], v[192:195], v[216:219], v[100:103]
	v_mfma_f32_16x16x32_bf16 v[96:99], v[200:203], v[216:219], v[96:99]
	v_mfma_f32_16x16x32_bf16 v[84:87], v[192:195], v[224:227], v[84:87]
	v_mfma_f32_16x16x32_bf16 v[80:83], v[200:203], v[224:227], v[80:83]
	v_mfma_f32_16x16x32_bf16 v[68:71], v[192:195], v[232:235], v[68:71]
	v_mfma_f32_16x16x32_bf16 v[64:67], v[200:203], v[232:235], v[64:67]
	s_setprio 0
	s_barrier
; #define PG8_STAGE(bufoff, gbase, voff) do { _Pragma("unroll") for (int _i = 0; _i < 2; ++_i) \
;         __builtin_amdgcn_global_load_lds((const unsigned*)((const char*)(gbase) + (voff)[_i]), (PG8_LAS unsigned*)(lds + (bufoff) + ldsw + _i * 8192), 16, 0, 0); } while (0)
; #define PG8_LDA(dst, b, h) do { _Pragma("unroll") for (int m = 0; m < 4; ++m) _Pragma("unroll") for (int k = 0; k < 2; ++k) dst[m][k] = *(const PG8_LAS bf16x8*)(lds + PG8_SA(b, h) + aoff + m * 2048 + k * 1024); } while (0)
; #define PG8_MMA(ai, bj, At, Bt) do { __builtin_amdgcn_s_setprio(1); _Pragma("unroll") for (int m = 0; m < 4; ++m) _Pragma("unroll") for (int n = 0; n < 2; ++n) _Pragma("unroll") for (int k = 0; k < 2; ++k) \
;         acc[ai][bj][m][n] = __builtin_amdgcn_mfma_f32_16x16x32_bf16(Bt[n][k], At[m][k], acc[ai][bj][m][n], 0, 0, 0); __builtin_amdgcn_s_setprio(0); } while (0)
; #define PG8_WAIT_V(n) asm volatile("s_waitcnt vmcnt(" #n ")" ::: "memory")
; #define PG8_WAIT_L(n) asm volatile("s_waitcnt lgkmcnt(" #n ")" ::: "memory")
; #define PG8_BAR __builtin_amdgcn_s_barrier()
; #define PG8_SCHED __builtin_amdgcn_sched_barrier(0)
; template <class Epi, class Sched, bool ALIGN_EPI = false, bool SP2 = false>
; __device__ __forceinline__ void gemm_phase(PG8_LAS unsigned char* lds, const Gemm g, const Sched& S, const Epi& E) {
;     ...
;             PG8_LDA(At, 1, 1); PG8_STAGE(PG8_SB(1, 0), b3, voffB); PG8_STAGE(PG8_SB(1, 1), b3 + hstep, voffB); PG8_STAGE(PG8_SA(1, 0), a3, voffA);
;             PG8_WAIT_V(8); PG8_WAIT_L(0); PG8_BAR; PG8_MMA(1, 0, At, B0); PG8_MMA(1, 1, At, B1); PG8_BAR; PG8_SCHED;
;     ...
;         if constexpr (ALIGN_EPI) { if (wr == 0) PG8_BAR; }
	s_add_i32 s24, s44, s29
	v_lshl_add_u64 v[170:171], v[170:171], 0, s[14:15]
	s_mov_b32 m0, s24
	ds_read_b128 v[204:207], v153 offset:49152
	ds_read_b128 v[208:211], v153 offset:50176
	ds_read_b128 v[212:215], v153 offset:51200
	ds_read_b128 v[216:219], v153 offset:52224
	ds_read_b128 v[220:223], v153 offset:53248
	ds_read_b128 v[224:227], v153 offset:54272
	ds_read_b128 v[228:231], v153 offset:55296
	ds_read_b128 v[232:235], v153 offset:56320
	global_load_lds_dwordx4 v[170:171], off
	s_add_i32 m0, s24, 0x2000
	s_add_u32 s24, s46, 0x30080
	v_lshl_add_u64 v[170:171], v[236:237], 0, s[14:15]
	s_addc_u32 s25, s47, 0
	s_add_i32 s44, s45, s29
	global_load_lds_dwordx4 v[170:171], off
	v_lshl_add_u64 v[170:171], s[24:25], 0, v[128:129]
	s_mov_b32 m0, s44
	s_nop 0
	global_load_lds_dwordx4 v[170:171], off
	v_lshl_add_u64 v[170:171], s[24:25], 0, v[130:131]
	s_add_i32 m0, s44, 0x2000
	s_nop 0
	global_load_lds_dwordx4 v[170:171], off
	v_lshl_add_u64 v[170:171], v[238:239], 0, s[14:15]
	s_mov_b32 m0, s91
	s_nop 0
	global_load_lds_dwordx4 v[170:171], off
	v_lshl_add_u64 v[170:171], v[240:241], 0, s[14:15]
	s_mov_b32 m0, s92
	s_nop 0
	global_load_lds_dwordx4 v[170:171], off
	s_waitcnt vmcnt(8)
	s_waitcnt lgkmcnt(0)
	s_barrier
	s_setprio 1
	v_mfma_f32_16x16x32_bf16 v[60:63], v[146:149], v[204:207], v[60:63]
	v_mfma_f32_16x16x32_bf16 v[56:59], v[158:161], v[204:207], v[56:59]
	v_mfma_f32_16x16x32_bf16 v[44:47], v[146:149], v[212:215], v[44:47]
	v_mfma_f32_16x16x32_bf16 v[40:43], v[158:161], v[212:215], v[40:43]
	v_mfma_f32_16x16x32_bf16 v[28:31], v[146:149], v[220:223], v[28:31]
	v_mfma_f32_16x16x32_bf16 v[24:27], v[158:161], v[220:223], v[24:27]
	v_mfma_f32_16x16x32_bf16 v[12:15], v[146:149], v[228:231], v[12:15]
	v_mfma_f32_16x16x32_bf16 v[8:11], v[158:161], v[228:231], v[8:11]
	v_mfma_f32_16x16x32_bf16 v[60:63], v[154:157], v[208:211], v[60:63]
	v_mfma_f32_16x16x32_bf16 v[56:59], v[162:165], v[208:211], v[56:59]
	v_mfma_f32_16x16x32_bf16 v[44:47], v[154:157], v[216:219], v[44:47]
	v_mfma_f32_16x16x32_bf16 v[40:43], v[162:165], v[216:219], v[40:43]
	v_mfma_f32_16x16x32_bf16 v[28:31], v[154:157], v[224:227], v[28:31]
	v_mfma_f32_16x16x32_bf16 v[24:27], v[162:165], v[224:227], v[24:27]
	v_mfma_f32_16x16x32_bf16 v[12:15], v[154:157], v[232:235], v[12:15]
	v_mfma_f32_16x16x32_bf16 v[8:11], v[162:165], v[232:235], v[8:11]
	v_mfma_f32_16x16x32_bf16 v[52:55], v[166:169], v[204:207], v[52:55]
	v_mfma_f32_16x16x32_bf16 v[48:51], v[196:199], v[204:207], v[48:51]
	v_mfma_f32_16x16x32_bf16 v[36:39], v[166:169], v[212:215], v[36:39]
	v_mfma_f32_16x16x32_bf16 v[32:35], v[196:199], v[212:215], v[32:35]
	v_mfma_f32_16x16x32_bf16 v[20:23], v[166:169], v[220:223], v[20:23]
	v_mfma_f32_16x16x32_bf16 v[16:19], v[196:199], v[220:223], v[16:19]
	v_mfma_f32_16x16x32_bf16 v[4:7], v[166:169], v[228:231], v[4:7]
	v_mfma_f32_16x16x32_bf16 v[0:3], v[196:199], v[228:231], v[0:3]
	v_mfma_f32_16x16x32_bf16 v[52:55], v[192:195], v[208:211], v[52:55]
	v_mfma_f32_16x16x32_bf16 v[48:51], v[200:203], v[208:211], v[48:51]
	v_mfma_f32_16x16x32_bf16 v[36:39], v[192:195], v[216:219], v[36:39]
	v_mfma_f32_16x16x32_bf16 v[32:35], v[200:203], v[216:219], v[32:35]
	v_mfma_f32_16x16x32_bf16 v[20:23], v[192:195], v[224:227], v[20:23]
	v_mfma_f32_16x16x32_bf16 v[16:19], v[200:203], v[224:227], v[16:19]
	v_mfma_f32_16x16x32_bf16 v[4:7], v[192:195], v[232:235], v[4:7]
	v_mfma_f32_16x16x32_bf16 v[0:3], v[200:203], v[232:235], v[0:3]
	s_setprio 0
	s_barrier
	s_add_i32 s50, s50, 2
	s_add_u32 s22, s22, 0x100
	s_addc_u32 s33, s33, 0
	s_cmp_gt_u32 s50, 9
	s_mov_b64 s[44:45], s[42:43]
	s_cbranch_scc0 .LBB0_122
	s_and_b64 vcc, exec, s[2:3]
	s_cbranch_vccz .LBB0_125
	s_barrier

; #define PG8_STAGE(bufoff, gbase, voff) do { _Pragma("unroll") for (int _i = 0; _i < 2; ++_i) \
;         __builtin_amdgcn_global_load_lds((const unsigned*)((const char*)(gbase) + (voff)[_i]), (PG8_LAS unsigned*)(lds + (bufoff) + ldsw + _i * 8192), 16, 0, 0); } while (0)
; #define PG8_LDA(dst, b, h) do { _Pragma("unroll") for (int m = 0; m < 4; ++m) _Pragma("unroll") for (int k = 0; k < 2; ++k) dst[m][k] = *(const PG8_LAS bf16x8*)(lds + PG8_SA(b, h) + aoff + m * 2048 + k * 1024); } while (0)
; #define PG8_LDB(dst, b, h) do { _Pragma("unroll") for (int n = 0; n < 2; ++n) _Pragma("unroll") for (int k = 0; k < 2; ++k) dst[n][k] = *(const PG8_LAS bf16x8*)(lds + PG8_SB(b, h) + boff + n * 2048 + k * 1024); } while (0)
; #define PG8_WAIT_V(n) asm volatile("s_waitcnt vmcnt(" #n ")" ::: "memory")
; #define PG8_WAIT_L(n) asm volatile("s_waitcnt lgkmcnt(" #n ")" ::: "memory")
; #define PG8_BAR __builtin_amdgcn_s_barrier()
; #define PG8_SCHED __builtin_amdgcn_sched_barrier(0)
; template <class Epi, class Sched, bool ALIGN_EPI = false, bool SP2 = false>
; __device__ __forceinline__ void gemm_phase(PG8_LAS unsigned char* lds, const Gemm g, const Sched& S, const Epi& E) {
;     ...
;         const bool has_next = S.next(ui + 1, nxt);
;         const char* nA = has_next ? (const char*)g.A + (size_t)nxt.pm * tstep : cA; const char* nB = has_next ? (const char*)g.Bt + (size_t)nxt.pn * tstep : cB;
;         for (int t = 0; t < nt; t += 2) {
;             const bool last = (t == nt - 2);
;             const char* a1 = cA + (size_t)(t + 1) * kstep;
;             const char* a2 = last ? nA : cA + (size_t)(t + 2) * kstep; const char* b2 = last ? nB : cB + (size_t)(t + 2) * kstep;
;             const char* a3 = a2 + kstep; const char* b3 = b2 + kstep;
;             if (last && has_next) S.a_ready(nxt);
;             if constexpr (SP2) {
;             PG8_LDB(B0, 0, 0); PG8_LDB(B1, 0, 1); PG8_SCHED; PG8_LDA(At, 0, 0); PG8_STAGE(PG8_SA(1, 1), a1 + hstep, voffA);
;             PG8_WAIT_V(8); PG8_WAIT_L(0); PG8_BAR; PG8_MMA(0, 0, At, B0); PG8_MMA(0, 1, At, B1); PG8_BAR; PG8_SCHED;
;             PG8_LDA(At, 0, 1); PG8_STAGE(PG8_SB(0, 0), b2, voffB); PG8_STAGE(PG8_SB(0, 1), b2 + hstep, voffB); PG8_STAGE(PG8_SA(0, 0), a2, voffA);
;             PG8_WAIT_V(8); PG8_WAIT_L(0); PG8_BAR; PG8_MMA(1, 0, At, B0); PG8_MMA(1, 1, At, B1); PG8_BAR; PG8_SCHED;
.LBB0_174:
	s_ashr_i32 s39, s38, 31
	s_lshl_b64 s[0:1], s[38:39], 19
	s_add_u32 s48, s23, s0
	s_addc_u32 s49, s12, s1
	s_and_b64 s[0:1], s[42:43], exec
	s_cselect_b32 s0, s49, s57
	s_cselect_b32 s1, s48, s56
	s_ashr_i32 s37, s36, 31
	s_lshl_b64 s[24:25], s[36:37], 19
	s_add_u32 s52, s85, s24
	s_addc_u32 s53, s86, s25
	s_and_b64 s[24:25], s[42:43], exec
	s_cselect_b32 s10, s53, s59
	s_cselect_b32 s22, s52, s58
	s_add_u32 s56, s56, 0x40080
	s_addc_u32 s57, s57, 0
	s_add_u32 s33, s58, 0x100
	s_addc_u32 s37, s59, 0
	s_mov_b32 s39, -2
	s_waitcnt lgkmcnt(0)
	s_add_u32 s24, s56, 0xfffc0080
	s_addc_u32 s25, s57, -1
	s_add_i32 s45, 0, 0x10000
	s_cmp_eq_u32 s39, 12
	s_cselect_b32 s61, s0, s25
	s_cselect_b32 s60, s1, s24
	v_add_u32_e32 v132, s45, v192
	s_cselect_b32 s59, s10, s37
	s_cselect_b32 s58, s22, s33
	s_add_i32 s47, 0, 0x14000
	ds_read_b128 v[128:131], v132
	ds_read_b128 v[158:161], v132 offset:1024
	ds_read_b128 v[162:165], v132 offset:2048
	ds_read_b128 v[166:169], v132 offset:3072
	v_add_u32_e32 v132, s47, v192
	ds_read_b128 v[194:197], v132
	ds_read_b128 v[198:201], v132 offset:1024
	ds_read_b128 v[202:205], v132 offset:2048
	ds_read_b128 v[206:209], v132 offset:3072
	v_lshl_add_u64 v[170:171], s[56:57], 0, v[154:155]
	s_add_i32 m0, s73, 0xc000
	ds_read_b128 v[210:213], v193
	ds_read_b128 v[214:217], v193 offset:1024
	ds_read_b128 v[218:221], v193 offset:2048
	ds_read_b128 v[222:225], v193 offset:3072
	ds_read_b128 v[226:229], v193 offset:4096
	ds_read_b128 v[230:233], v193 offset:5120
	ds_read_b128 v[234:237], v193 offset:6144
	ds_read_b128 v[238:241], v193 offset:7168
	global_load_lds_dwordx4 v[170:171], off
	v_lshl_add_u64 v[170:171], s[56:57], 0, v[156:157]
	s_add_i32 m0, s73, 0xe000
	s_nop 0
	global_load_lds_dwordx4 v[170:171], off
	s_waitcnt vmcnt(8)
	s_waitcnt lgkmcnt(0)
	s_barrier
	s_setprio 1
	v_mfma_f32_16x16x32_bf16 v[124:127], v[128:131], v[210:213], 0
	v_mfma_f32_16x16x32_bf16 v[120:123], v[162:165], v[210:213], 0
	v_mfma_f32_16x16x32_bf16 v[108:111], v[128:131], v[218:221], 0
	v_mfma_f32_16x16x32_bf16 v[104:107], v[162:165], v[218:221], 0
	v_mfma_f32_16x16x32_bf16 v[92:95], v[128:131], v[226:229], 0
	v_mfma_f32_16x16x32_bf16 v[88:91], v[162:165], v[226:229], 0
	v_mfma_f32_16x16x32_bf16 v[76:79], v[128:131], v[234:237], 0
	v_mfma_f32_16x16x32_bf16 v[72:75], v[162:165], v[234:237], 0
	v_mfma_f32_16x16x32_bf16 v[124:127], v[158:161], v[214:217], v[124:127]
	v_mfma_f32_16x16x32_bf16 v[120:123], v[166:169], v[214:217], v[120:123]
	v_mfma_f32_16x16x32_bf16 v[108:111], v[158:161], v[222:225], v[108:111]
	v_mfma_f32_16x16x32_bf16 v[104:107], v[166:169], v[222:225], v[104:107]
	v_mfma_f32_16x16x32_bf16 v[92:95], v[158:161], v[230:233], v[92:95]
	v_mfma_f32_16x16x32_bf16 v[88:91], v[166:169], v[230:233], v[88:91]
	v_mfma_f32_16x16x32_bf16 v[76:79], v[158:161], v[238:241], v[76:79]
	v_mfma_f32_16x16x32_bf16 v[72:75], v[166:169], v[238:241], v[72:75]
	v_mfma_f32_16x16x32_bf16 v[116:119], v[194:197], v[210:213], 0
	v_mfma_f32_16x16x32_bf16 v[112:115], v[202:205], v[210:213], 0
	v_mfma_f32_16x16x32_bf16 v[100:103], v[194:197], v[218:221], 0
	v_mfma_f32_16x16x32_bf16 v[96:99], v[202:205], v[218:221], 0
	v_mfma_f32_16x16x32_bf16 v[84:87], v[194:197], v[226:229], 0
	v_mfma_f32_16x16x32_bf16 v[80:83], v[202:205], v[226:229], 0
	v_mfma_f32_16x16x32_bf16 v[68:71], v[194:197], v[234:237], 0
	v_mfma_f32_16x16x32_bf16 v[64:67], v[202:205], v[234:237], 0
	v_mfma_f32_16x16x32_bf16 v[116:119], v[198:201], v[214:217], v[116:119]
	v_mfma_f32_16x16x32_bf16 v[112:115], v[206:209], v[214:217], v[112:115]
	v_mfma_f32_16x16x32_bf16 v[100:103], v[198:201], v[222:225], v[100:103]
	v_mfma_f32_16x16x32_bf16 v[96:99], v[206:209], v[222:225], v[96:99]
	v_mfma_f32_16x16x32_bf16 v[84:87], v[198:201], v[230:233], v[84:87]
	v_mfma_f32_16x16x32_bf16 v[80:83], v[206:209], v[230:233], v[80:83]
	v_mfma_f32_16x16x32_bf16 v[68:71], v[198:201], v[238:241], v[68:71]
	v_mfma_f32_16x16x32_bf16 v[64:67], v[206:209], v[238:241], v[64:67]
	s_setprio 0
	s_barrier
	s_add_i32 s24, s45, s29
	v_lshl_add_u64 v[170:171], s[58:59], 0, v[142:143]
	s_mov_b32 m0, s24
	ds_read_b128 v[210:213], v193 offset:16384
	ds_read_b128 v[214:217], v193 offset:17408
	ds_read_b128 v[218:221], v193 offset:18432
	ds_read_b128 v[222:225], v193 offset:19456
	ds_read_b128 v[226:229], v193 offset:20480
	ds_read_b128 v[230:233], v193 offset:21504
	ds_read_b128 v[234:237], v193 offset:22528
	ds_read_b128 v[238:241], v193 offset:23552
	global_load_lds_dwordx4 v[170:171], off
	s_add_i32 m0, s24, 0x2000
	s_add_u32 s24, s58, 0x40000
	v_lshl_add_u64 v[242:243], s[58:59], 0, v[146:147]
	s_addc_u32 s25, s59, 0
	s_add_i32 s45, s47, s29
	global_load_lds_dwordx4 v[242:243], off
	v_lshl_add_u64 v[244:245], s[24:25], 0, v[142:143]
	s_mov_b32 m0, s45
	v_lshl_add_u64 v[246:247], s[60:61], 0, v[144:145]
	global_load_lds_dwordx4 v[244:245], off
	v_lshl_add_u64 v[244:245], s[24:25], 0, v[146:147]
	s_add_i32 m0, s45, 0x2000
	s_nop 0
	global_load_lds_dwordx4 v[244:245], off
	v_lshl_add_u64 v[244:245], s[60:61], 0, v[140:141]
	s_mov_b32 m0, s73
	s_nop 0
	global_load_lds_dwordx4 v[244:245], off
	s_mov_b32 m0, s87
	s_nop 0
	global_load_lds_dwordx4 v[246:247], off
	s_waitcnt vmcnt(8)
	s_waitcnt lgkmcnt(0)
	s_barrier
; #define PG8_STAGE(bufoff, gbase, voff) do { _Pragma("unroll") for (int _i = 0; _i < 2; ++_i) \
;         __builtin_amdgcn_global_load_lds((const unsigned*)((const char*)(gbase) + (voff)[_i]), (PG8_LAS unsigned*)(lds + (bufoff) + ldsw + _i * 8192), 16, 0, 0); } while (0)
; #define PG8_LDA(dst, b, h) do { _Pragma("unroll") for (int m = 0; m < 4; ++m) _Pragma("unroll") for (int k = 0; k < 2; ++k) dst[m][k] = *(const PG8_LAS bf16x8*)(lds + PG8_SA(b, h) + aoff + m * 2048 + k * 1024); } while (0)
; #define PG8_LDB(dst, b, h) do { _Pragma("unroll") for (int n = 0; n < 2; ++n) _Pragma("unroll") for (int k = 0; k < 2; ++k) dst[n][k] = *(const PG8_LAS bf16x8*)(lds + PG8_SB(b, h) + boff + n * 2048 + k * 1024); } while (0)
; #define PG8_MMA(ai, bj, At, Bt) do { __builtin_amdgcn_s_setprio(1); _Pragma("unroll") for (int m = 0; m < 4; ++m) _Pragma("unroll") for (int n = 0; n < 2; ++n) _Pragma("unroll") for (int k = 0; k < 2; ++k) \
;         acc[ai][bj][m][n] = __builtin_amdgcn_mfma_f32_16x16x32_bf16(Bt[n][k], At[m][k], acc[ai][bj][m][n], 0, 0, 0); __builtin_amdgcn_s_setprio(0); } while (0)
; #define PG8_WAIT_V(n) asm volatile("s_waitcnt vmcnt(" #n ")" ::: "memory")
; #define PG8_WAIT_L(n) asm volatile("s_waitcnt lgkmcnt(" #n ")" ::: "memory")
; #define PG8_BAR __builtin_amdgcn_s_barrier()
; #define PG8_SCHED __builtin_amdgcn_sched_barrier(0)
; template <class Epi, class Sched, bool ALIGN_EPI = false, bool SP2 = false>
; __device__ __forceinline__ void gemm_phase(PG8_LAS unsigned char* lds, const Gemm g, const Sched& S, const Epi& E) {
;     ...
;             PG8_WAIT_V(8); PG8_WAIT_L(0); PG8_BAR; PG8_MMA(1, 0, At, B0); PG8_MMA(1, 1, At, B1); PG8_BAR; PG8_SCHED;
;             PG8_LDB(B0, 1, 0); PG8_LDB(B1, 1, 1); PG8_SCHED; PG8_LDA(At, 1, 0); PG8_STAGE(PG8_SA(0, 1), a2 + hstep, voffA);
;             PG8_WAIT_V(8); PG8_WAIT_L(0); PG8_BAR; PG8_MMA(0, 0, At, B0); PG8_MMA(0, 1, At, B1); PG8_BAR; PG8_SCHED;
	s_setprio 1
	v_mfma_f32_16x16x32_bf16 v[60:63], v[128:131], v[210:213], 0
	v_mfma_f32_16x16x32_bf16 v[56:59], v[162:165], v[210:213], 0
	v_mfma_f32_16x16x32_bf16 v[44:47], v[128:131], v[218:221], 0
	v_mfma_f32_16x16x32_bf16 v[40:43], v[162:165], v[218:221], 0
	v_mfma_f32_16x16x32_bf16 v[28:31], v[128:131], v[226:229], 0
	v_mfma_f32_16x16x32_bf16 v[24:27], v[162:165], v[226:229], 0
	v_mfma_f32_16x16x32_bf16 v[12:15], v[128:131], v[234:237], 0
	v_mfma_f32_16x16x32_bf16 v[8:11], v[162:165], v[234:237], 0
	v_mfma_f32_16x16x32_bf16 v[60:63], v[158:161], v[214:217], v[60:63]
	v_mfma_f32_16x16x32_bf16 v[56:59], v[166:169], v[214:217], v[56:59]
	v_mfma_f32_16x16x32_bf16 v[44:47], v[158:161], v[222:225], v[44:47]
	v_mfma_f32_16x16x32_bf16 v[40:43], v[166:169], v[222:225], v[40:43]
	v_mfma_f32_16x16x32_bf16 v[28:31], v[158:161], v[230:233], v[28:31]
	v_mfma_f32_16x16x32_bf16 v[24:27], v[166:169], v[230:233], v[24:27]
	v_mfma_f32_16x16x32_bf16 v[12:15], v[158:161], v[238:241], v[12:15]
	v_mfma_f32_16x16x32_bf16 v[8:11], v[166:169], v[238:241], v[8:11]
	v_mfma_f32_16x16x32_bf16 v[52:55], v[194:197], v[210:213], 0
	v_mfma_f32_16x16x32_bf16 v[48:51], v[202:205], v[210:213], 0
	v_mfma_f32_16x16x32_bf16 v[36:39], v[194:197], v[218:221], 0
	v_mfma_f32_16x16x32_bf16 v[32:35], v[202:205], v[218:221], 0
	v_mfma_f32_16x16x32_bf16 v[20:23], v[194:197], v[226:229], 0
	v_mfma_f32_16x16x32_bf16 v[16:19], v[202:205], v[226:229], 0
	v_mfma_f32_16x16x32_bf16 v[4:7], v[194:197], v[234:237], 0
	v_mfma_f32_16x16x32_bf16 v[0:3], v[202:205], v[234:237], 0
	v_mfma_f32_16x16x32_bf16 v[52:55], v[198:201], v[214:217], v[52:55]
	v_mfma_f32_16x16x32_bf16 v[48:51], v[206:209], v[214:217], v[48:51]
	v_mfma_f32_16x16x32_bf16 v[36:39], v[198:201], v[222:225], v[36:39]
	v_mfma_f32_16x16x32_bf16 v[32:35], v[206:209], v[222:225], v[32:35]
	v_mfma_f32_16x16x32_bf16 v[20:23], v[198:201], v[230:233], v[20:23]
	v_mfma_f32_16x16x32_bf16 v[16:19], v[206:209], v[230:233], v[16:19]
	v_mfma_f32_16x16x32_bf16 v[4:7], v[198:201], v[238:241], v[4:7]
	v_mfma_f32_16x16x32_bf16 v[0:3], v[206:209], v[238:241], v[0:3]
	s_setprio 0
	s_barrier
	s_add_i32 s45, 0, 0x18000
	v_add_u32_e32 v132, s45, v192
	s_add_i32 s47, 0, 0x1c000
	ds_read_b128 v[128:131], v132
	ds_read_b128 v[158:161], v132 offset:1024
	ds_read_b128 v[162:165], v132 offset:2048
	ds_read_b128 v[166:169], v132 offset:3072
	v_add_u32_e32 v132, s47, v192
	ds_read_b128 v[194:197], v132
	ds_read_b128 v[198:201], v132 offset:1024
	ds_read_b128 v[202:205], v132 offset:2048
	ds_read_b128 v[206:209], v132 offset:3072
	s_add_u32 s24, s60, 0x40000
	s_addc_u32 s25, s61, 0
	s_mov_b32 m0, s88
	v_lshl_add_u64 v[248:249], s[24:25], 0, v[140:141]
	ds_read_b128 v[210:213], v193 offset:32768
	ds_read_b128 v[214:217], v193 offset:33792
	ds_read_b128 v[218:221], v193 offset:34816
	ds_read_b128 v[222:225], v193 offset:35840
	ds_read_b128 v[226:229], v193 offset:36864
	ds_read_b128 v[230:233], v193 offset:37888
	ds_read_b128 v[234:237], v193 offset:38912
	ds_read_b128 v[238:241], v193 offset:39936
	global_load_lds_dwordx4 v[248:249], off
	v_lshl_add_u64 v[248:249], s[24:25], 0, v[144:145]
	s_mov_b32 m0, s89
	s_nop 0
	global_load_lds_dwordx4 v[248:249], off
	s_waitcnt vmcnt(8)
	s_waitcnt lgkmcnt(0)
	s_barrier
	s_setprio 1
	v_mfma_f32_16x16x32_bf16 v[124:127], v[128:131], v[210:213], v[124:127]
	v_mfma_f32_16x16x32_bf16 v[120:123], v[162:165], v[210:213], v[120:123]
	v_mfma_f32_16x16x32_bf16 v[108:111], v[128:131], v[218:221], v[108:111]
	v_mfma_f32_16x16x32_bf16 v[104:107], v[162:165], v[218:221], v[104:107]
	v_mfma_f32_16x16x32_bf16 v[92:95], v[128:131], v[226:229], v[92:95]
	v_mfma_f32_16x16x32_bf16 v[88:91], v[162:165], v[226:229], v[88:91]
	v_mfma_f32_16x16x32_bf16 v[76:79], v[128:131], v[234:237], v[76:79]
	v_mfma_f32_16x16x32_bf16 v[72:75], v[162:165], v[234:237], v[72:75]
	v_mfma_f32_16x16x32_bf16 v[124:127], v[158:161], v[214:217], v[124:127]
	v_mfma_f32_16x16x32_bf16 v[120:123], v[166:169], v[214:217], v[120:123]
	v_mfma_f32_16x16x32_bf16 v[108:111], v[158:161], v[222:225], v[108:111]
	v_mfma_f32_16x16x32_bf16 v[104:107], v[166:169], v[222:225], v[104:107]
	v_mfma_f32_16x16x32_bf16 v[92:95], v[158:161], v[230:233], v[92:95]
	v_mfma_f32_16x16x32_bf16 v[88:91], v[166:169], v[230:233], v[88:91]
	v_mfma_f32_16x16x32_bf16 v[76:79], v[158:161], v[238:241], v[76:79]
	v_mfma_f32_16x16x32_bf16 v[72:75], v[166:169], v[238:241], v[72:75]
	v_mfma_f32_16x16x32_bf16 v[116:119], v[194:197], v[210:213], v[116:119]
	v_mfma_f32_16x16x32_bf16 v[112:115], v[202:205], v[210:213], v[112:115]
	v_mfma_f32_16x16x32_bf16 v[100:103], v[194:197], v[218:221], v[100:103]
	v_mfma_f32_16x16x32_bf16 v[96:99], v[202:205], v[218:221], v[96:99]
	v_mfma_f32_16x16x32_bf16 v[84:87], v[194:197], v[226:229], v[84:87]
	v_mfma_f32_16x16x32_bf16 v[80:83], v[202:205], v[226:229], v[80:83]
	v_mfma_f32_16x16x32_bf16 v[68:71], v[194:197], v[234:237], v[68:71]
	v_mfma_f32_16x16x32_bf16 v[64:67], v[202:205], v[234:237], v[64:67]
	v_mfma_f32_16x16x32_bf16 v[116:119], v[198:201], v[214:217], v[116:119]
	v_mfma_f32_16x16x32_bf16 v[112:115], v[206:209], v[214:217], v[112:115]
	v_mfma_f32_16x16x32_bf16 v[100:103], v[198:201], v[222:225], v[100:103]
	v_mfma_f32_16x16x32_bf16 v[96:99], v[206:209], v[222:225], v[96:99]
	v_mfma_f32_16x16x32_bf16 v[84:87], v[198:201], v[230:233], v[84:87]
	v_mfma_f32_16x16x32_bf16 v[80:83], v[206:209], v[230:233], v[80:83]
	v_mfma_f32_16x16x32_bf16 v[68:71], v[198:201], v[238:241], v[68:71]
	v_mfma_f32_16x16x32_bf16 v[64:67], v[206:209], v[238:241], v[64:67]
	s_setprio 0
	s_barrier
; #define PG8_STAGE(bufoff, gbase, voff) do { _Pragma("unroll") for (int _i = 0; _i < 2; ++_i) \
;         __builtin_amdgcn_global_load_lds((const unsigned*)((const char*)(gbase) + (voff)[_i]), (PG8_LAS unsigned*)(lds + (bufoff) + ldsw + _i * 8192), 16, 0, 0); } while (0)
; #define PG8_LDA(dst, b, h) do { _Pragma("unroll") for (int m = 0; m < 4; ++m) _Pragma("unroll") for (int k = 0; k < 2; ++k) dst[m][k] = *(const PG8_LAS bf16x8*)(lds + PG8_SA(b, h) + aoff + m * 2048 + k * 1024); } while (0)
; #define PG8_LDB(dst, b, h) do { _Pragma("unroll") for (int n = 0; n < 2; ++n) _Pragma("unroll") for (int k = 0; k < 2; ++k) dst[n][k] = *(const PG8_LAS bf16x8*)(lds + PG8_SB(b, h) + boff + n * 2048 + k * 1024); } while (0)
; #define PG8_MMA(ai, bj, At, Bt) do { __builtin_amdgcn_s_setprio(1); _Pragma("unroll") for (int m = 0; m < 4; ++m) _Pragma("unroll") for (int n = 0; n < 2; ++n) _Pragma("unroll") for (int k = 0; k < 2; ++k) \
;         acc[ai][bj][m][n] = __builtin_amdgcn_mfma_f32_16x16x32_bf16(Bt[n][k], At[m][k], acc[ai][bj][m][n], 0, 0, 0); __builtin_amdgcn_s_setprio(0); } while (0)
; #define PG8_WAIT_V(n) asm volatile("s_waitcnt vmcnt(" #n ")" ::: "memory")
; #define PG8_BAR __builtin_amdgcn_s_barrier()
; template <class Epi, class Sched, bool ALIGN_EPI = false, bool SP2 = false>
; __device__ __forceinline__ void gemm_phase(PG8_LAS unsigned char* lds, const Gemm g, const Sched& S, const Epi& E) {
;     ...
;         for (int t = 0; t < nt; t += 2) {
;             const bool last = (t == nt - 2);
;             const char* a1 = cA + (size_t)(t + 1) * kstep;
;             const char* a2 = last ? nA : cA + (size_t)(t + 2) * kstep; const char* b2 = last ? nB : cB + (size_t)(t + 2) * kstep;
;             const char* a3 = a2 + kstep; const char* b3 = b2 + kstep;
;             if (last && has_next) S.a_ready(nxt);
;             if constexpr (SP2) {
;             PG8_LDB(B0, 0, 0); PG8_LDB(B1, 0, 1); PG8_SCHED; PG8_LDA(At, 0, 0); PG8_STAGE(PG8_SA(1, 1), a1 + hstep, voffA);
;             PG8_WAIT_V(8); PG8_WAIT_L(0); PG8_BAR; PG8_MMA(0, 0, At, B0); PG8_MMA(0, 1, At, B1); PG8_BAR; PG8_SCHED;
;     ...
;             PG8_LDA(At, 1, 1); PG8_STAGE(PG8_SB(1, 0), b3, voffB); PG8_STAGE(PG8_SB(1, 1), b3 + hstep, voffB); PG8_STAGE(PG8_SA(1, 0), a3, voffA);
;             PG8_WAIT_V(8); PG8_WAIT_L(0); PG8_BAR; PG8_MMA(1, 0, At, B0); PG8_MMA(1, 1, At, B1); PG8_BAR; PG8_SCHED;
	s_add_i32 s24, s45, s29
	v_lshl_add_u64 v[170:171], v[170:171], 0, s[14:15]
	s_mov_b32 m0, s24
	ds_read_b128 v[210:213], v193 offset:49152
	ds_read_b128 v[214:217], v193 offset:50176
	ds_read_b128 v[218:221], v193 offset:51200
	ds_read_b128 v[222:225], v193 offset:52224
	ds_read_b128 v[226:229], v193 offset:53248
	ds_read_b128 v[230:233], v193 offset:54272
	ds_read_b128 v[234:237], v193 offset:55296
	ds_read_b128 v[238:241], v193 offset:56320
	global_load_lds_dwordx4 v[170:171], off
	s_add_i32 m0, s24, 0x2000
	s_add_u32 s24, s58, 0x40080
	v_lshl_add_u64 v[170:171], v[242:243], 0, s[14:15]
	s_addc_u32 s25, s59, 0
	s_add_i32 s45, s47, s29
	global_load_lds_dwordx4 v[170:171], off
	v_lshl_add_u64 v[170:171], s[24:25], 0, v[142:143]
	s_mov_b32 m0, s45
	s_nop 0
	global_load_lds_dwordx4 v[170:171], off
	v_lshl_add_u64 v[170:171], s[24:25], 0, v[146:147]
	s_add_i32 m0, s45, 0x2000
	s_nop 0
	global_load_lds_dwordx4 v[170:171], off
	v_lshl_add_u64 v[170:171], v[244:245], 0, s[14:15]
	s_mov_b32 m0, s90
	s_nop 0
	global_load_lds_dwordx4 v[170:171], off
	v_lshl_add_u64 v[170:171], v[246:247], 0, s[14:15]
	s_mov_b32 m0, s91
	s_nop 0
	global_load_lds_dwordx4 v[170:171], off
	s_waitcnt vmcnt(8)
	s_waitcnt lgkmcnt(0)
	s_barrier
	s_setprio 1
	v_mfma_f32_16x16x32_bf16 v[60:63], v[128:131], v[210:213], v[60:63]
	v_mfma_f32_16x16x32_bf16 v[56:59], v[162:165], v[210:213], v[56:59]
	v_mfma_f32_16x16x32_bf16 v[44:47], v[128:131], v[218:221], v[44:47]
	v_mfma_f32_16x16x32_bf16 v[40:43], v[162:165], v[218:221], v[40:43]
	v_mfma_f32_16x16x32_bf16 v[28:31], v[128:131], v[226:229], v[28:31]
	v_mfma_f32_16x16x32_bf16 v[24:27], v[162:165], v[226:229], v[24:27]
	v_mfma_f32_16x16x32_bf16 v[12:15], v[128:131], v[234:237], v[12:15]
	v_mfma_f32_16x16x32_bf16 v[8:11], v[162:165], v[234:237], v[8:11]
	v_mfma_f32_16x16x32_bf16 v[60:63], v[158:161], v[214:217], v[60:63]
	v_mfma_f32_16x16x32_bf16 v[56:59], v[166:169], v[214:217], v[56:59]
	v_mfma_f32_16x16x32_bf16 v[44:47], v[158:161], v[222:225], v[44:47]
	v_mfma_f32_16x16x32_bf16 v[40:43], v[166:169], v[222:225], v[40:43]
	v_mfma_f32_16x16x32_bf16 v[28:31], v[158:161], v[230:233], v[28:31]
	v_mfma_f32_16x16x32_bf16 v[24:27], v[166:169], v[230:233], v[24:27]
	v_mfma_f32_16x16x32_bf16 v[12:15], v[158:161], v[238:241], v[12:15]
	v_mfma_f32_16x16x32_bf16 v[8:11], v[166:169], v[238:241], v[8:11]
	v_mfma_f32_16x16x32_bf16 v[52:55], v[194:197], v[210:213], v[52:55]
	v_mfma_f32_16x16x32_bf16 v[48:51], v[202:205], v[210:213], v[48:51]
	v_mfma_f32_16x16x32_bf16 v[36:39], v[194:197], v[218:221], v[36:39]
	v_mfma_f32_16x16x32_bf16 v[32:35], v[202:205], v[218:221], v[32:35]
	v_mfma_f32_16x16x32_bf16 v[20:23], v[194:197], v[226:229], v[20:23]
	v_mfma_f32_16x16x32_bf16 v[16:19], v[202:205], v[226:229], v[16:19]
	v_mfma_f32_16x16x32_bf16 v[4:7], v[194:197], v[234:237], v[4:7]
	v_mfma_f32_16x16x32_bf16 v[0:3], v[202:205], v[234:237], v[0:3]
	v_mfma_f32_16x16x32_bf16 v[52:55], v[198:201], v[214:217], v[52:55]
	v_mfma_f32_16x16x32_bf16 v[48:51], v[206:209], v[214:217], v[48:51]
	v_mfma_f32_16x16x32_bf16 v[36:39], v[198:201], v[222:225], v[36:39]
	v_mfma_f32_16x16x32_bf16 v[32:35], v[206:209], v[222:225], v[32:35]
	v_mfma_f32_16x16x32_bf16 v[20:23], v[198:201], v[230:233], v[20:23]
	v_mfma_f32_16x16x32_bf16 v[16:19], v[206:209], v[230:233], v[16:19]
	v_mfma_f32_16x16x32_bf16 v[4:7], v[198:201], v[238:241], v[4:7]
	v_mfma_f32_16x16x32_bf16 v[0:3], v[206:209], v[238:241], v[0:3]
	s_setprio 0
	s_barrier
	s_add_i32 s39, s39, 2
	s_add_u32 s56, s56, 0x100
	s_addc_u32 s57, s57, 0
	s_add_u32 s33, s33, 0x100
	s_addc_u32 s37, s37, 0
	s_cmp_gt_u32 s39, 13
.LBB0_175:
	s_add_u32 s24, s56, 0xfffc0080
	s_addc_u32 s25, s57, -1
	s_add_i32 s45, 0, 0x10000
	s_cmp_eq_u32 s39, 12
	s_cselect_b32 s61, s0, s25
	s_cselect_b32 s60, s1, s24
	v_add_u32_e32 v132, s45, v192
	s_cselect_b32 s59, s10, s37
	s_cselect_b32 s58, s22, s33
	s_add_i32 s47, 0, 0x14000
	ds_read_b128 v[128:131], v132
	ds_read_b128 v[158:161], v132 offset:1024
	ds_read_b128 v[162:165], v132 offset:2048
	ds_read_b128 v[166:169], v132 offset:3072
	v_add_u32_e32 v132, s47, v192
	ds_read_b128 v[194:197], v132
	ds_read_b128 v[198:201], v132 offset:1024
	ds_read_b128 v[202:205], v132 offset:2048
	ds_read_b128 v[206:209], v132 offset:3072
	v_lshl_add_u64 v[170:171], s[56:57], 0, v[154:155]
	s_add_i32 m0, s73, 0xc000
	ds_read_b128 v[210:213], v193
	ds_read_b128 v[214:217], v193 offset:1024
	ds_read_b128 v[218:221], v193 offset:2048
	ds_read_b128 v[222:225], v193 offset:3072
	ds_read_b128 v[226:229], v193 offset:4096
	ds_read_b128 v[230:233], v193 offset:5120
	ds_read_b128 v[234:237], v193 offset:6144
	ds_read_b128 v[238:241], v193 offset:7168
	global_load_lds_dwordx4 v[170:171], off
	v_lshl_add_u64 v[170:171], s[56:57], 0, v[156:157]
	s_add_i32 m0, s73, 0xe000
	s_nop 0
	global_load_lds_dwordx4 v[170:171], off
	s_waitcnt vmcnt(8)
	s_waitcnt lgkmcnt(0)
	s_barrier
; #define PG8_STAGE(bufoff, gbase, voff) do { _Pragma("unroll") for (int _i = 0; _i < 2; ++_i) \
;         __builtin_amdgcn_global_load_lds((const unsigned*)((const char*)(gbase) + (voff)[_i]), (PG8_LAS unsigned*)(lds + (bufoff) + ldsw + _i * 8192), 16, 0, 0); } while (0)
; #define PG8_LDA(dst, b, h) do { _Pragma("unroll") for (int m = 0; m < 4; ++m) _Pragma("unroll") for (int k = 0; k < 2; ++k) dst[m][k] = *(const PG8_LAS bf16x8*)(lds + PG8_SA(b, h) + aoff + m * 2048 + k * 1024); } while (0)
; #define PG8_MMA(ai, bj, At, Bt) do { __builtin_amdgcn_s_setprio(1); _Pragma("unroll") for (int m = 0; m < 4; ++m) _Pragma("unroll") for (int n = 0; n < 2; ++n) _Pragma("unroll") for (int k = 0; k < 2; ++k) \
;         acc[ai][bj][m][n] = __builtin_amdgcn_mfma_f32_16x16x32_bf16(Bt[n][k], At[m][k], acc[ai][bj][m][n], 0, 0, 0); __builtin_amdgcn_s_setprio(0); } while (0)
; #define PG8_WAIT_V(n) asm volatile("s_waitcnt vmcnt(" #n ")" ::: "memory")
; #define PG8_WAIT_L(n) asm volatile("s_waitcnt lgkmcnt(" #n ")" ::: "memory")
; #define PG8_BAR __builtin_amdgcn_s_barrier()
; #define PG8_SCHED __builtin_amdgcn_sched_barrier(0)
; template <class Epi, class Sched, bool ALIGN_EPI = false, bool SP2 = false>
; __device__ __forceinline__ void gemm_phase(PG8_LAS unsigned char* lds, const Gemm g, const Sched& S, const Epi& E) {
;     ...
;             PG8_WAIT_V(8); PG8_WAIT_L(0); PG8_BAR; PG8_MMA(0, 0, At, B0); PG8_MMA(0, 1, At, B1); PG8_BAR; PG8_SCHED;
;             PG8_LDA(At, 0, 1); PG8_STAGE(PG8_SB(0, 0), b2, voffB); PG8_STAGE(PG8_SB(0, 1), b2 + hstep, voffB); PG8_STAGE(PG8_SA(0, 0), a2, voffA);
;             PG8_WAIT_V(8); PG8_WAIT_L(0); PG8_BAR; PG8_MMA(1, 0, At, B0); PG8_MMA(1, 1, At, B1); PG8_BAR; PG8_SCHED;
	s_setprio 1
	v_mfma_f32_16x16x32_bf16 v[124:127], v[128:131], v[210:213], v[124:127]
	v_mfma_f32_16x16x32_bf16 v[120:123], v[162:165], v[210:213], v[120:123]
	v_mfma_f32_16x16x32_bf16 v[108:111], v[128:131], v[218:221], v[108:111]
	v_mfma_f32_16x16x32_bf16 v[104:107], v[162:165], v[218:221], v[104:107]
	v_mfma_f32_16x16x32_bf16 v[92:95], v[128:131], v[226:229], v[92:95]
	v_mfma_f32_16x16x32_bf16 v[88:91], v[162:165], v[226:229], v[88:91]
	v_mfma_f32_16x16x32_bf16 v[76:79], v[128:131], v[234:237], v[76:79]
	v_mfma_f32_16x16x32_bf16 v[72:75], v[162:165], v[234:237], v[72:75]
	v_mfma_f32_16x16x32_bf16 v[124:127], v[158:161], v[214:217], v[124:127]
	v_mfma_f32_16x16x32_bf16 v[120:123], v[166:169], v[214:217], v[120:123]
	v_mfma_f32_16x16x32_bf16 v[108:111], v[158:161], v[222:225], v[108:111]
	v_mfma_f32_16x16x32_bf16 v[104:107], v[166:169], v[222:225], v[104:107]
	v_mfma_f32_16x16x32_bf16 v[92:95], v[158:161], v[230:233], v[92:95]
	v_mfma_f32_16x16x32_bf16 v[88:91], v[166:169], v[230:233], v[88:91]
	v_mfma_f32_16x16x32_bf16 v[76:79], v[158:161], v[238:241], v[76:79]
	v_mfma_f32_16x16x32_bf16 v[72:75], v[166:169], v[238:241], v[72:75]
	v_mfma_f32_16x16x32_bf16 v[116:119], v[194:197], v[210:213], v[116:119]
	v_mfma_f32_16x16x32_bf16 v[112:115], v[202:205], v[210:213], v[112:115]
	v_mfma_f32_16x16x32_bf16 v[100:103], v[194:197], v[218:221], v[100:103]
	v_mfma_f32_16x16x32_bf16 v[96:99], v[202:205], v[218:221], v[96:99]
	v_mfma_f32_16x16x32_bf16 v[84:87], v[194:197], v[226:229], v[84:87]
	v_mfma_f32_16x16x32_bf16 v[80:83], v[202:205], v[226:229], v[80:83]
	v_mfma_f32_16x16x32_bf16 v[68:71], v[194:197], v[234:237], v[68:71]
	v_mfma_f32_16x16x32_bf16 v[64:67], v[202:205], v[234:237], v[64:67]
	v_mfma_f32_16x16x32_bf16 v[116:119], v[198:201], v[214:217], v[116:119]
	v_mfma_f32_16x16x32_bf16 v[112:115], v[206:209], v[214:217], v[112:115]
	v_mfma_f32_16x16x32_bf16 v[100:103], v[198:201], v[222:225], v[100:103]
	v_mfma_f32_16x16x32_bf16 v[96:99], v[206:209], v[222:225], v[96:99]
	v_mfma_f32_16x16x32_bf16 v[84:87], v[198:201], v[230:233], v[84:87]
	v_mfma_f32_16x16x32_bf16 v[80:83], v[206:209], v[230:233], v[80:83]
	v_mfma_f32_16x16x32_bf16 v[68:71], v[198:201], v[238:241], v[68:71]
	v_mfma_f32_16x16x32_bf16 v[64:67], v[206:209], v[238:241], v[64:67]
	s_setprio 0
	s_barrier
	s_add_i32 s24, s45, s29
	v_lshl_add_u64 v[170:171], s[58:59], 0, v[142:143]
	s_mov_b32 m0, s24
	ds_read_b128 v[210:213], v193 offset:16384
	ds_read_b128 v[214:217], v193 offset:17408
	ds_read_b128 v[218:221], v193 offset:18432
	ds_read_b128 v[222:225], v193 offset:19456
	ds_read_b128 v[226:229], v193 offset:20480
	ds_read_b128 v[230:233], v193 offset:21504
	ds_read_b128 v[234:237], v193 offset:22528
	ds_read_b128 v[238:241], v193 offset:23552
	global_load_lds_dwordx4 v[170:171], off
	s_add_i32 m0, s24, 0x2000
	s_add_u32 s24, s58, 0x40000
	v_lshl_add_u64 v[242:243], s[58:59], 0, v[146:147]
	s_addc_u32 s25, s59, 0
	s_add_i32 s45, s47, s29
	global_load_lds_dwordx4 v[242:243], off
	v_lshl_add_u64 v[244:245], s[24:25], 0, v[142:143]
	s_mov_b32 m0, s45
	v_lshl_add_u64 v[246:247], s[60:61], 0, v[144:145]
	global_load_lds_dwordx4 v[244:245], off
	v_lshl_add_u64 v[244:245], s[24:25], 0, v[146:147]
	s_add_i32 m0, s45, 0x2000
	s_nop 0
	global_load_lds_dwordx4 v[244:245], off
	v_lshl_add_u64 v[244:245], s[60:61], 0, v[140:141]
	s_mov_b32 m0, s73
	s_nop 0
	global_load_lds_dwordx4 v[244:245], off
	s_mov_b32 m0, s87
	s_nop 0
	global_load_lds_dwordx4 v[246:247], off
	s_waitcnt vmcnt(8)
	s_waitcnt lgkmcnt(0)
	s_barrier
	s_setprio 1
	v_mfma_f32_16x16x32_bf16 v[60:63], v[128:131], v[210:213], v[60:63]
	v_mfma_f32_16x16x32_bf16 v[56:59], v[162:165], v[210:213], v[56:59]
	v_mfma_f32_16x16x32_bf16 v[44:47], v[128:131], v[218:221], v[44:47]
	v_mfma_f32_16x16x32_bf16 v[40:43], v[162:165], v[218:221], v[40:43]
	v_mfma_f32_16x16x32_bf16 v[28:31], v[128:131], v[226:229], v[28:31]
	v_mfma_f32_16x16x32_bf16 v[24:27], v[162:165], v[226:229], v[24:27]
	v_mfma_f32_16x16x32_bf16 v[12:15], v[128:131], v[234:237], v[12:15]
	v_mfma_f32_16x16x32_bf16 v[8:11], v[162:165], v[234:237], v[8:11]
	v_mfma_f32_16x16x32_bf16 v[60:63], v[158:161], v[214:217], v[60:63]
	v_mfma_f32_16x16x32_bf16 v[56:59], v[166:169], v[214:217], v[56:59]
	v_mfma_f32_16x16x32_bf16 v[44:47], v[158:161], v[222:225], v[44:47]
	v_mfma_f32_16x16x32_bf16 v[40:43], v[166:169], v[222:225], v[40:43]
	v_mfma_f32_16x16x32_bf16 v[28:31], v[158:161], v[230:233], v[28:31]
	v_mfma_f32_16x16x32_bf16 v[24:27], v[166:169], v[230:233], v[24:27]
	v_mfma_f32_16x16x32_bf16 v[12:15], v[158:161], v[238:241], v[12:15]
	v_mfma_f32_16x16x32_bf16 v[8:11], v[166:169], v[238:241], v[8:11]
	v_mfma_f32_16x16x32_bf16 v[52:55], v[194:197], v[210:213], v[52:55]
	v_mfma_f32_16x16x32_bf16 v[48:51], v[202:205], v[210:213], v[48:51]
	v_mfma_f32_16x16x32_bf16 v[36:39], v[194:197], v[218:221], v[36:39]
	v_mfma_f32_16x16x32_bf16 v[32:35], v[202:205], v[218:221], v[32:35]
	v_mfma_f32_16x16x32_bf16 v[20:23], v[194:197], v[226:229], v[20:23]
	v_mfma_f32_16x16x32_bf16 v[16:19], v[202:205], v[226:229], v[16:19]
	v_mfma_f32_16x16x32_bf16 v[4:7], v[194:197], v[234:237], v[4:7]
	v_mfma_f32_16x16x32_bf16 v[0:3], v[202:205], v[234:237], v[0:3]
	v_mfma_f32_16x16x32_bf16 v[52:55], v[198:201], v[214:217], v[52:55]
	v_mfma_f32_16x16x32_bf16 v[48:51], v[206:209], v[214:217], v[48:51]
	v_mfma_f32_16x16x32_bf16 v[36:39], v[198:201], v[222:225], v[36:39]
	v_mfma_f32_16x16x32_bf16 v[32:35], v[206:209], v[222:225], v[32:35]
	v_mfma_f32_16x16x32_bf16 v[20:23], v[198:201], v[230:233], v[20:23]
	v_mfma_f32_16x16x32_bf16 v[16:19], v[206:209], v[230:233], v[16:19]
	v_mfma_f32_16x16x32_bf16 v[4:7], v[198:201], v[238:241], v[4:7]
	v_mfma_f32_16x16x32_bf16 v[0:3], v[206:209], v[238:241], v[0:3]
	s_setprio 0
	s_barrier
; #define PG8_STAGE(bufoff, gbase, voff) do { _Pragma("unroll") for (int _i = 0; _i < 2; ++_i) \
;         __builtin_amdgcn_global_load_lds((const unsigned*)((const char*)(gbase) + (voff)[_i]), (PG8_LAS unsigned*)(lds + (bufoff) + ldsw + _i * 8192), 16, 0, 0); } while (0)
; #define PG8_LDA(dst, b, h) do { _Pragma("unroll") for (int m = 0; m < 4; ++m) _Pragma("unroll") for (int k = 0; k < 2; ++k) dst[m][k] = *(const PG8_LAS bf16x8*)(lds + PG8_SA(b, h) + aoff + m * 2048 + k * 1024); } while (0)
; #define PG8_LDB(dst, b, h) do { _Pragma("unroll") for (int n = 0; n < 2; ++n) _Pragma("unroll") for (int k = 0; k < 2; ++k) dst[n][k] = *(const PG8_LAS bf16x8*)(lds + PG8_SB(b, h) + boff + n * 2048 + k * 1024); } while (0)
; #define PG8_MMA(ai, bj, At, Bt) do { __builtin_amdgcn_s_setprio(1); _Pragma("unroll") for (int m = 0; m < 4; ++m) _Pragma("unroll") for (int n = 0; n < 2; ++n) _Pragma("unroll") for (int k = 0; k < 2; ++k) \
;         acc[ai][bj][m][n] = __builtin_amdgcn_mfma_f32_16x16x32_bf16(Bt[n][k], At[m][k], acc[ai][bj][m][n], 0, 0, 0); __builtin_amdgcn_s_setprio(0); } while (0)
; #define PG8_WAIT_V(n) asm volatile("s_waitcnt vmcnt(" #n ")" ::: "memory")
; #define PG8_WAIT_L(n) asm volatile("s_waitcnt lgkmcnt(" #n ")" ::: "memory")
; #define PG8_BAR __builtin_amdgcn_s_barrier()
; #define PG8_SCHED __builtin_amdgcn_sched_barrier(0)
; template <class Epi, class Sched, bool ALIGN_EPI = false, bool SP2 = false>
; __device__ __forceinline__ void gemm_phase(PG8_LAS unsigned char* lds, const Gemm g, const Sched& S, const Epi& E) {
;     ...
;             PG8_LDB(B0, 1, 0); PG8_LDB(B1, 1, 1); PG8_SCHED; PG8_LDA(At, 1, 0); PG8_STAGE(PG8_SA(0, 1), a2 + hstep, voffA);
;             PG8_WAIT_V(8); PG8_WAIT_L(0); PG8_BAR; PG8_MMA(0, 0, At, B0); PG8_MMA(0, 1, At, B1); PG8_BAR; PG8_SCHED;
	s_add_i32 s45, 0, 0x18000
	v_add_u32_e32 v132, s45, v192
	s_add_i32 s47, 0, 0x1c000
	ds_read_b128 v[128:131], v132
	ds_read_b128 v[158:161], v132 offset:1024
	ds_read_b128 v[162:165], v132 offset:2048
	ds_read_b128 v[166:169], v132 offset:3072
	v_add_u32_e32 v132, s47, v192
	ds_read_b128 v[194:197], v132
	ds_read_b128 v[198:201], v132 offset:1024
	ds_read_b128 v[202:205], v132 offset:2048
	ds_read_b128 v[206:209], v132 offset:3072
	s_add_u32 s24, s60, 0x40000
	s_addc_u32 s25, s61, 0
	s_mov_b32 m0, s88
	v_lshl_add_u64 v[248:249], s[24:25], 0, v[140:141]
	ds_read_b128 v[210:213], v193 offset:32768
	ds_read_b128 v[214:217], v193 offset:33792
	ds_read_b128 v[218:221], v193 offset:34816
	ds_read_b128 v[222:225], v193 offset:35840
	ds_read_b128 v[226:229], v193 offset:36864
	ds_read_b128 v[230:233], v193 offset:37888
	ds_read_b128 v[234:237], v193 offset:38912
	ds_read_b128 v[238:241], v193 offset:39936
	global_load_lds_dwordx4 v[248:249], off
	v_lshl_add_u64 v[248:249], s[24:25], 0, v[144:145]
	s_mov_b32 m0, s89
	s_nop 0
	global_load_lds_dwordx4 v[248:249], off
	s_waitcnt vmcnt(8)
	s_waitcnt lgkmcnt(0)
	s_barrier
	s_setprio 1
	v_mfma_f32_16x16x32_bf16 v[124:127], v[128:131], v[210:213], v[124:127]
	v_mfma_f32_16x16x32_bf16 v[120:123], v[162:165], v[210:213], v[120:123]
	v_mfma_f32_16x16x32_bf16 v[108:111], v[128:131], v[218:221], v[108:111]
	v_mfma_f32_16x16x32_bf16 v[104:107], v[162:165], v[218:221], v[104:107]
	v_mfma_f32_16x16x32_bf16 v[92:95], v[128:131], v[226:229], v[92:95]
	v_mfma_f32_16x16x32_bf16 v[88:91], v[162:165], v[226:229], v[88:91]
	v_mfma_f32_16x16x32_bf16 v[76:79], v[128:131], v[234:237], v[76:79]
	v_mfma_f32_16x16x32_bf16 v[72:75], v[162:165], v[234:237], v[72:75]
	v_mfma_f32_16x16x32_bf16 v[124:127], v[158:161], v[214:217], v[124:127]
	v_mfma_f32_16x16x32_bf16 v[120:123], v[166:169], v[214:217], v[120:123]
	v_mfma_f32_16x16x32_bf16 v[108:111], v[158:161], v[222:225], v[108:111]
	v_mfma_f32_16x16x32_bf16 v[104:107], v[166:169], v[222:225], v[104:107]
	v_mfma_f32_16x16x32_bf16 v[92:95], v[158:161], v[230:233], v[92:95]
	v_mfma_f32_16x16x32_bf16 v[88:91], v[166:169], v[230:233], v[88:91]
	v_mfma_f32_16x16x32_bf16 v[76:79], v[158:161], v[238:241], v[76:79]
	v_mfma_f32_16x16x32_bf16 v[72:75], v[166:169], v[238:241], v[72:75]
	v_mfma_f32_16x16x32_bf16 v[116:119], v[194:197], v[210:213], v[116:119]
	v_mfma_f32_16x16x32_bf16 v[112:115], v[202:205], v[210:213], v[112:115]
	v_mfma_f32_16x16x32_bf16 v[100:103], v[194:197], v[218:221], v[100:103]
	v_mfma_f32_16x16x32_bf16 v[96:99], v[202:205], v[218:221], v[96:99]
	v_mfma_f32_16x16x32_bf16 v[84:87], v[194:197], v[226:229], v[84:87]
	v_mfma_f32_16x16x32_bf16 v[80:83], v[202:205], v[226:229], v[80:83]
	v_mfma_f32_16x16x32_bf16 v[68:71], v[194:197], v[234:237], v[68:71]
	v_mfma_f32_16x16x32_bf16 v[64:67], v[202:205], v[234:237], v[64:67]
	v_mfma_f32_16x16x32_bf16 v[116:119], v[198:201], v[214:217], v[116:119]
	v_mfma_f32_16x16x32_bf16 v[112:115], v[206:209], v[214:217], v[112:115]
	v_mfma_f32_16x16x32_bf16 v[100:103], v[198:201], v[222:225], v[100:103]
	v_mfma_f32_16x16x32_bf16 v[96:99], v[206:209], v[222:225], v[96:99]
	v_mfma_f32_16x16x32_bf16 v[84:87], v[198:201], v[230:233], v[84:87]
	v_mfma_f32_16x16x32_bf16 v[80:83], v[206:209], v[230:233], v[80:83]
	v_mfma_f32_16x16x32_bf16 v[68:71], v[198:201], v[238:241], v[68:71]
	v_mfma_f32_16x16x32_bf16 v[64:67], v[206:209], v[238:241], v[64:67]
	s_setprio 0
	s_barrier
; #define PG8_STAGE(bufoff, gbase, voff) do { _Pragma("unroll") for (int _i = 0; _i < 2; ++_i) \
;         __builtin_amdgcn_global_load_lds((const unsigned*)((const char*)(gbase) + (voff)[_i]), (PG8_LAS unsigned*)(lds + (bufoff) + ldsw + _i * 8192), 16, 0, 0); } while (0)
; #define PG8_LDA(dst, b, h) do { _Pragma("unroll") for (int m = 0; m < 4; ++m) _Pragma("unroll") for (int k = 0; k < 2; ++k) dst[m][k] = *(const PG8_LAS bf16x8*)(lds + PG8_SA(b, h) + aoff + m * 2048 + k * 1024); } while (0)
; #define PG8_MMA(ai, bj, At, Bt) do { __builtin_amdgcn_s_setprio(1); _Pragma("unroll") for (int m = 0; m < 4; ++m) _Pragma("unroll") for (int n = 0; n < 2; ++n) _Pragma("unroll") for (int k = 0; k < 2; ++k) \
;         acc[ai][bj][m][n] = __builtin_amdgcn_mfma_f32_16x16x32_bf16(Bt[n][k], At[m][k], acc[ai][bj][m][n], 0, 0, 0); __builtin_amdgcn_s_setprio(0); } while (0)
; #define PG8_WAIT_V(n) asm volatile("s_waitcnt vmcnt(" #n ")" ::: "memory")
; #define PG8_WAIT_L(n) asm volatile("s_waitcnt lgkmcnt(" #n ")" ::: "memory")
; #define PG8_BAR __builtin_amdgcn_s_barrier()
; #define PG8_SCHED __builtin_amdgcn_sched_barrier(0)
; template <class Epi, class Sched, bool ALIGN_EPI = false, bool SP2 = false>
; __device__ __forceinline__ void gemm_phase(PG8_LAS unsigned char* lds, const Gemm g, const Sched& S, const Epi& E) {
;     ...
;             PG8_LDA(At, 1, 1); PG8_STAGE(PG8_SB(1, 0), b3, voffB); PG8_STAGE(PG8_SB(1, 1), b3 + hstep, voffB); PG8_STAGE(PG8_SA(1, 0), a3, voffA);
;             PG8_WAIT_V(8); PG8_WAIT_L(0); PG8_BAR; PG8_MMA(1, 0, At, B0); PG8_MMA(1, 1, At, B1); PG8_BAR; PG8_SCHED;
;     ...
;         if constexpr (ALIGN_EPI) { if (wr == 0) PG8_BAR; }
	s_add_i32 s24, s45, s29
	v_lshl_add_u64 v[170:171], v[170:171], 0, s[14:15]
	s_mov_b32 m0, s24
	ds_read_b128 v[210:213], v193 offset:49152
	ds_read_b128 v[214:217], v193 offset:50176
	ds_read_b128 v[218:221], v193 offset:51200
	ds_read_b128 v[222:225], v193 offset:52224
	ds_read_b128 v[226:229], v193 offset:53248
	ds_read_b128 v[230:233], v193 offset:54272
	ds_read_b128 v[234:237], v193 offset:55296
	ds_read_b128 v[238:241], v193 offset:56320
	global_load_lds_dwordx4 v[170:171], off
	s_add_i32 m0, s24, 0x2000
	s_add_u32 s24, s58, 0x40080
	v_lshl_add_u64 v[170:171], v[242:243], 0, s[14:15]
	s_addc_u32 s25, s59, 0
	s_add_i32 s45, s47, s29
	global_load_lds_dwordx4 v[170:171], off
	v_lshl_add_u64 v[170:171], s[24:25], 0, v[142:143]
	s_mov_b32 m0, s45
	s_nop 0
	global_load_lds_dwordx4 v[170:171], off
	v_lshl_add_u64 v[170:171], s[24:25], 0, v[146:147]
	s_add_i32 m0, s45, 0x2000
	s_nop 0
	global_load_lds_dwordx4 v[170:171], off
	v_lshl_add_u64 v[170:171], v[244:245], 0, s[14:15]
	s_mov_b32 m0, s90
	s_nop 0
	global_load_lds_dwordx4 v[170:171], off
	v_lshl_add_u64 v[170:171], v[246:247], 0, s[14:15]
	s_mov_b32 m0, s91
	s_nop 0
	global_load_lds_dwordx4 v[170:171], off
	s_waitcnt vmcnt(8)
	s_waitcnt lgkmcnt(0)
	s_barrier
	s_setprio 1
	v_mfma_f32_16x16x32_bf16 v[60:63], v[128:131], v[210:213], v[60:63]
	v_mfma_f32_16x16x32_bf16 v[56:59], v[162:165], v[210:213], v[56:59]
	v_mfma_f32_16x16x32_bf16 v[44:47], v[128:131], v[218:221], v[44:47]
	v_mfma_f32_16x16x32_bf16 v[40:43], v[162:165], v[218:221], v[40:43]
	v_mfma_f32_16x16x32_bf16 v[28:31], v[128:131], v[226:229], v[28:31]
	v_mfma_f32_16x16x32_bf16 v[24:27], v[162:165], v[226:229], v[24:27]
	v_mfma_f32_16x16x32_bf16 v[12:15], v[128:131], v[234:237], v[12:15]
	v_mfma_f32_16x16x32_bf16 v[8:11], v[162:165], v[234:237], v[8:11]
	v_mfma_f32_16x16x32_bf16 v[60:63], v[158:161], v[214:217], v[60:63]
	v_mfma_f32_16x16x32_bf16 v[56:59], v[166:169], v[214:217], v[56:59]
	v_mfma_f32_16x16x32_bf16 v[44:47], v[158:161], v[222:225], v[44:47]
	v_mfma_f32_16x16x32_bf16 v[40:43], v[166:169], v[222:225], v[40:43]
	v_mfma_f32_16x16x32_bf16 v[28:31], v[158:161], v[230:233], v[28:31]
	v_mfma_f32_16x16x32_bf16 v[24:27], v[166:169], v[230:233], v[24:27]
	v_mfma_f32_16x16x32_bf16 v[12:15], v[158:161], v[238:241], v[12:15]
	v_mfma_f32_16x16x32_bf16 v[8:11], v[166:169], v[238:241], v[8:11]
	v_mfma_f32_16x16x32_bf16 v[52:55], v[194:197], v[210:213], v[52:55]
	v_mfma_f32_16x16x32_bf16 v[48:51], v[202:205], v[210:213], v[48:51]
	v_mfma_f32_16x16x32_bf16 v[36:39], v[194:197], v[218:221], v[36:39]
	v_mfma_f32_16x16x32_bf16 v[32:35], v[202:205], v[218:221], v[32:35]
	v_mfma_f32_16x16x32_bf16 v[20:23], v[194:197], v[226:229], v[20:23]
	v_mfma_f32_16x16x32_bf16 v[16:19], v[202:205], v[226:229], v[16:19]
	v_mfma_f32_16x16x32_bf16 v[4:7], v[194:197], v[234:237], v[4:7]
	v_mfma_f32_16x16x32_bf16 v[0:3], v[202:205], v[234:237], v[0:3]
	v_mfma_f32_16x16x32_bf16 v[52:55], v[198:201], v[214:217], v[52:55]
	v_mfma_f32_16x16x32_bf16 v[48:51], v[206:209], v[214:217], v[48:51]
	v_mfma_f32_16x16x32_bf16 v[36:39], v[198:201], v[222:225], v[36:39]
	v_mfma_f32_16x16x32_bf16 v[32:35], v[206:209], v[222:225], v[32:35]
	v_mfma_f32_16x16x32_bf16 v[20:23], v[198:201], v[230:233], v[20:23]
	v_mfma_f32_16x16x32_bf16 v[16:19], v[206:209], v[230:233], v[16:19]
	v_mfma_f32_16x16x32_bf16 v[4:7], v[198:201], v[238:241], v[4:7]
	v_mfma_f32_16x16x32_bf16 v[0:3], v[206:209], v[238:241], v[0:3]
	s_setprio 0
	s_barrier
	s_add_i32 s39, s39, 2
	s_add_u32 s56, s56, 0x100
	s_addc_u32 s57, s57, 0
	s_add_u32 s33, s33, 0x100
	s_addc_u32 s37, s37, 0
	s_cmp_gt_u32 s39, 13
	s_cbranch_scc0 .LBB0_175
	s_and_b64 vcc, exec, s[4:5]
	s_cbranch_vccz .LBB0_178
	s_barrier

; #define PG8_STAGE(bufoff, gbase, voff) do { _Pragma("unroll") for (int _i = 0; _i < 2; ++_i) \
;         __builtin_amdgcn_global_load_lds((const unsigned*)((const char*)(gbase) + (voff)[_i]), (PG8_LAS unsigned*)(lds + (bufoff) + ldsw + _i * 8192), 16, 0, 0); } while (0)
; #define PG8_LDA(dst, b, h) do { _Pragma("unroll") for (int m = 0; m < 4; ++m) _Pragma("unroll") for (int k = 0; k < 2; ++k) dst[m][k] = *(const PG8_LAS bf16x8*)(lds + PG8_SA(b, h) + aoff + m * 2048 + k * 1024); } while (0)
; #define PG8_LDB(dst, b, h) do { _Pragma("unroll") for (int n = 0; n < 2; ++n) _Pragma("unroll") for (int k = 0; k < 2; ++k) dst[n][k] = *(const PG8_LAS bf16x8*)(lds + PG8_SB(b, h) + boff + n * 2048 + k * 1024); } while (0)
; #define PG8_WAIT_V(n) asm volatile("s_waitcnt vmcnt(" #n ")" ::: "memory")
; #define PG8_WAIT_L(n) asm volatile("s_waitcnt lgkmcnt(" #n ")" ::: "memory")
; #define PG8_BAR __builtin_amdgcn_s_barrier()
; #define PG8_SCHED __builtin_amdgcn_sched_barrier(0)
; template <class Epi, class Sched, bool ALIGN_EPI = false, bool SP2 = false>
; __device__ __forceinline__ void gemm_phase(PG8_LAS unsigned char* lds, const Gemm g, const Sched& S, const Epi& E) {
;     ...
;         const bool has_next = S.next(ui + 1, nxt);
;         const char* nA = has_next ? (const char*)g.A + (size_t)nxt.pm * tstep : cA; const char* nB = has_next ? (const char*)g.Bt + (size_t)nxt.pn * tstep : cB;
;         for (int t = 0; t < nt; t += 2) {
;             const bool last = (t == nt - 2);
;             const char* a1 = cA + (size_t)(t + 1) * kstep;
;             const char* a2 = last ? nA : cA + (size_t)(t + 2) * kstep; const char* b2 = last ? nB : cB + (size_t)(t + 2) * kstep;
;             const char* a3 = a2 + kstep; const char* b3 = b2 + kstep;
;             if (last && has_next) S.a_ready(nxt);
;             if constexpr (SP2) {
;             PG8_LDB(B0, 0, 0); PG8_LDB(B1, 0, 1); PG8_SCHED; PG8_LDA(At, 0, 0); PG8_STAGE(PG8_SA(1, 1), a1 + hstep, voffA);
;             PG8_WAIT_V(8); PG8_WAIT_L(0); PG8_BAR; PG8_MMA(0, 0, At, B0); PG8_MMA(0, 1, At, B1); PG8_BAR; PG8_SCHED;
;             PG8_LDA(At, 0, 1); PG8_STAGE(PG8_SB(0, 0), b2, voffB); PG8_STAGE(PG8_SB(0, 1), b2 + hstep, voffB); PG8_STAGE(PG8_SA(0, 0), a2, voffA);
;             PG8_WAIT_V(8); PG8_WAIT_L(0); PG8_BAR; PG8_MMA(1, 0, At, B0); PG8_MMA(1, 1, At, B1); PG8_BAR; PG8_SCHED;
.LBB0_553:
	s_ashr_i32 s21, s20, 31
	s_lshl_b64 s[0:1], s[20:21], 19
	s_add_u32 s38, s26, s0
	s_addc_u32 s39, s27, s1
	s_and_b64 s[0:1], s[42:43], exec
	s_cselect_b32 s0, s39, s57
	s_cselect_b32 s1, s38, s56
	s_ashr_i32 s17, s16, 31
	s_lshl_b64 s[24:25], s[16:17], 19
	s_add_u32 s48, s10, s24
	s_addc_u32 s49, s12, s25
	s_and_b64 s[24:25], s[42:43], exec
	s_cselect_b32 s17, s49, s59
	s_cselect_b32 s21, s48, s58
	s_add_u32 s56, s56, 0x40080
	s_addc_u32 s57, s57, 0
	s_add_u32 s22, s58, 0x100
	s_addc_u32 s33, s59, 0
	s_mov_b32 s45, -2
	s_add_u32 s24, s56, 0xfffc0080
	s_addc_u32 s25, s57, -1
	s_add_i32 s47, 0, 0x10000
	s_cmp_eq_u32 s45, 12
	s_cselect_b32 s61, s0, s25
	s_cselect_b32 s60, s1, s24
	s_cselect_b32 s59, s17, s33
	s_cselect_b32 s58, s21, s22
	s_add_i32 s50, 0, 0x14000
	v_add_u32_e32 v162, s47, v159
	v_add_u32_e32 v170, s50, v159
	ds_read_b128 v[146:149], v162
	ds_read_b128 v[150:153], v162 offset:1024
	ds_read_b128 v[154:157], v162 offset:2048
	ds_read_b128 v[162:165], v162 offset:3072
	ds_read_b128 v[166:169], v170
	ds_read_b128 v[192:195], v170 offset:1024
	ds_read_b128 v[196:199], v170 offset:2048
	ds_read_b128 v[200:203], v170 offset:3072
	v_lshl_add_u64 v[170:171], s[56:57], 0, v[142:143]
	s_add_i32 m0, s29, 0xc000
	ds_read_b128 v[204:207], v161
	ds_read_b128 v[208:211], v161 offset:1024
	ds_read_b128 v[212:215], v161 offset:2048
	ds_read_b128 v[216:219], v161 offset:3072
	ds_read_b128 v[220:223], v161 offset:4096
	ds_read_b128 v[224:227], v161 offset:5120
	ds_read_b128 v[228:231], v161 offset:6144
	ds_read_b128 v[232:235], v161 offset:7168
	global_load_lds_dwordx4 v[170:171], off
	v_lshl_add_u64 v[170:171], s[56:57], 0, v[144:145]
	s_add_i32 m0, s29, 0xe000
	s_nop 0
	global_load_lds_dwordx4 v[170:171], off
	s_waitcnt vmcnt(8)
	s_waitcnt lgkmcnt(0)
	s_barrier
	s_setprio 1
	v_mfma_f32_16x16x32_bf16 v[124:127], v[146:149], v[204:207], 0
	v_mfma_f32_16x16x32_bf16 v[120:123], v[154:157], v[204:207], 0
	v_mfma_f32_16x16x32_bf16 v[108:111], v[146:149], v[212:215], 0
	v_mfma_f32_16x16x32_bf16 v[104:107], v[154:157], v[212:215], 0
	v_mfma_f32_16x16x32_bf16 v[92:95], v[146:149], v[220:223], 0
	v_mfma_f32_16x16x32_bf16 v[88:91], v[154:157], v[220:223], 0
	v_mfma_f32_16x16x32_bf16 v[76:79], v[146:149], v[228:231], 0
	v_mfma_f32_16x16x32_bf16 v[72:75], v[154:157], v[228:231], 0
	v_mfma_f32_16x16x32_bf16 v[124:127], v[150:153], v[208:211], v[124:127]
	v_mfma_f32_16x16x32_bf16 v[120:123], v[162:165], v[208:211], v[120:123]
	v_mfma_f32_16x16x32_bf16 v[108:111], v[150:153], v[216:219], v[108:111]
	v_mfma_f32_16x16x32_bf16 v[104:107], v[162:165], v[216:219], v[104:107]
	v_mfma_f32_16x16x32_bf16 v[92:95], v[150:153], v[224:227], v[92:95]
	v_mfma_f32_16x16x32_bf16 v[88:91], v[162:165], v[224:227], v[88:91]
	v_mfma_f32_16x16x32_bf16 v[76:79], v[150:153], v[232:235], v[76:79]
	v_mfma_f32_16x16x32_bf16 v[72:75], v[162:165], v[232:235], v[72:75]
	v_mfma_f32_16x16x32_bf16 v[116:119], v[166:169], v[204:207], 0
	v_mfma_f32_16x16x32_bf16 v[112:115], v[196:199], v[204:207], 0
	v_mfma_f32_16x16x32_bf16 v[100:103], v[166:169], v[212:215], 0
	v_mfma_f32_16x16x32_bf16 v[96:99], v[196:199], v[212:215], 0
	v_mfma_f32_16x16x32_bf16 v[84:87], v[166:169], v[220:223], 0
	v_mfma_f32_16x16x32_bf16 v[80:83], v[196:199], v[220:223], 0
	v_mfma_f32_16x16x32_bf16 v[68:71], v[166:169], v[228:231], 0
	v_mfma_f32_16x16x32_bf16 v[64:67], v[196:199], v[228:231], 0
	v_mfma_f32_16x16x32_bf16 v[116:119], v[192:195], v[208:211], v[116:119]
	v_mfma_f32_16x16x32_bf16 v[112:115], v[200:203], v[208:211], v[112:115]
	v_mfma_f32_16x16x32_bf16 v[100:103], v[192:195], v[216:219], v[100:103]
	v_mfma_f32_16x16x32_bf16 v[96:99], v[200:203], v[216:219], v[96:99]
	v_mfma_f32_16x16x32_bf16 v[84:87], v[192:195], v[224:227], v[84:87]
	v_mfma_f32_16x16x32_bf16 v[80:83], v[200:203], v[224:227], v[80:83]
	v_mfma_f32_16x16x32_bf16 v[68:71], v[192:195], v[232:235], v[68:71]
	v_mfma_f32_16x16x32_bf16 v[64:67], v[200:203], v[232:235], v[64:67]
	s_setprio 0
	s_barrier
	s_add_i32 s24, s47, s23
	v_lshl_add_u64 v[170:171], s[58:59], 0, v[132:133]
	s_mov_b32 m0, s24
	ds_read_b128 v[204:207], v161 offset:16384
	ds_read_b128 v[208:211], v161 offset:17408
	ds_read_b128 v[212:215], v161 offset:18432
	ds_read_b128 v[216:219], v161 offset:19456
	ds_read_b128 v[220:223], v161 offset:20480
	ds_read_b128 v[224:227], v161 offset:21504
	ds_read_b128 v[228:231], v161 offset:22528
	ds_read_b128 v[232:235], v161 offset:23552
	global_load_lds_dwordx4 v[170:171], off
	s_add_i32 m0, s24, 0x2000
	s_add_u32 s24, s58, 0x40000
	v_lshl_add_u64 v[236:237], s[58:59], 0, v[140:141]
	s_addc_u32 s25, s59, 0
	s_add_i32 s47, s50, s23
	global_load_lds_dwordx4 v[236:237], off
	v_lshl_add_u64 v[238:239], s[24:25], 0, v[132:133]
	s_mov_b32 m0, s47
	v_lshl_add_u64 v[240:241], s[60:61], 0, v[130:131]
	global_load_lds_dwordx4 v[238:239], off
	v_lshl_add_u64 v[238:239], s[24:25], 0, v[140:141]
	s_add_i32 m0, s47, 0x2000
	s_nop 0
	global_load_lds_dwordx4 v[238:239], off
	v_lshl_add_u64 v[238:239], s[60:61], 0, v[128:129]
	s_mov_b32 m0, s29
	s_nop 0
	global_load_lds_dwordx4 v[238:239], off
	s_mov_b32 m0, s62
	s_nop 0
	global_load_lds_dwordx4 v[240:241], off
	s_waitcnt vmcnt(8)
	s_waitcnt lgkmcnt(0)
	s_barrier
; #define PG8_STAGE(bufoff, gbase, voff) do { _Pragma("unroll") for (int _i = 0; _i < 2; ++_i) \
;         __builtin_amdgcn_global_load_lds((const unsigned*)((const char*)(gbase) + (voff)[_i]), (PG8_LAS unsigned*)(lds + (bufoff) + ldsw + _i * 8192), 16, 0, 0); } while (0)
; #define PG8_LDA(dst, b, h) do { _Pragma("unroll") for (int m = 0; m < 4; ++m) _Pragma("unroll") for (int k = 0; k < 2; ++k) dst[m][k] = *(const PG8_LAS bf16x8*)(lds + PG8_SA(b, h) + aoff + m * 2048 + k * 1024); } while (0)
; #define PG8_LDB(dst, b, h) do { _Pragma("unroll") for (int n = 0; n < 2; ++n) _Pragma("unroll") for (int k = 0; k < 2; ++k) dst[n][k] = *(const PG8_LAS bf16x8*)(lds + PG8_SB(b, h) + boff + n * 2048 + k * 1024); } while (0)
; #define PG8_MMA(ai, bj, At, Bt) do { __builtin_amdgcn_s_setprio(1); _Pragma("unroll") for (int m = 0; m < 4; ++m) _Pragma("unroll") for (int n = 0; n < 2; ++n) _Pragma("unroll") for (int k = 0; k < 2; ++k) \
;         acc[ai][bj][m][n] = __builtin_amdgcn_mfma_f32_16x16x32_bf16(Bt[n][k], At[m][k], acc[ai][bj][m][n], 0, 0, 0); __builtin_amdgcn_s_setprio(0); } while (0)
; #define PG8_WAIT_V(n) asm volatile("s_waitcnt vmcnt(" #n ")" ::: "memory")
; #define PG8_WAIT_L(n) asm volatile("s_waitcnt lgkmcnt(" #n ")" ::: "memory")
; #define PG8_BAR __builtin_amdgcn_s_barrier()
; #define PG8_SCHED __builtin_amdgcn_sched_barrier(0)
; template <class Epi, class Sched, bool ALIGN_EPI = false, bool SP2 = false>
; __device__ __forceinline__ void gemm_phase(PG8_LAS unsigned char* lds, const Gemm g, const Sched& S, const Epi& E) {
;     ...
;             PG8_WAIT_V(8); PG8_WAIT_L(0); PG8_BAR; PG8_MMA(1, 0, At, B0); PG8_MMA(1, 1, At, B1); PG8_BAR; PG8_SCHED;
;             PG8_LDB(B0, 1, 0); PG8_LDB(B1, 1, 1); PG8_SCHED; PG8_LDA(At, 1, 0); PG8_STAGE(PG8_SA(0, 1), a2 + hstep, voffA);
;             PG8_WAIT_V(8); PG8_WAIT_L(0); PG8_BAR; PG8_MMA(0, 0, At, B0); PG8_MMA(0, 1, At, B1); PG8_BAR; PG8_SCHED;
	s_setprio 1
	v_mfma_f32_16x16x32_bf16 v[60:63], v[146:149], v[204:207], 0
	v_mfma_f32_16x16x32_bf16 v[56:59], v[154:157], v[204:207], 0
	v_mfma_f32_16x16x32_bf16 v[44:47], v[146:149], v[212:215], 0
	v_mfma_f32_16x16x32_bf16 v[40:43], v[154:157], v[212:215], 0
	v_mfma_f32_16x16x32_bf16 v[28:31], v[146:149], v[220:223], 0
	v_mfma_f32_16x16x32_bf16 v[24:27], v[154:157], v[220:223], 0
	v_mfma_f32_16x16x32_bf16 v[12:15], v[146:149], v[228:231], 0
	v_mfma_f32_16x16x32_bf16 v[8:11], v[154:157], v[228:231], 0
	v_mfma_f32_16x16x32_bf16 v[60:63], v[150:153], v[208:211], v[60:63]
	v_mfma_f32_16x16x32_bf16 v[56:59], v[162:165], v[208:211], v[56:59]
	v_mfma_f32_16x16x32_bf16 v[44:47], v[150:153], v[216:219], v[44:47]
	v_mfma_f32_16x16x32_bf16 v[40:43], v[162:165], v[216:219], v[40:43]
	v_mfma_f32_16x16x32_bf16 v[28:31], v[150:153], v[224:227], v[28:31]
	v_mfma_f32_16x16x32_bf16 v[24:27], v[162:165], v[224:227], v[24:27]
	v_mfma_f32_16x16x32_bf16 v[12:15], v[150:153], v[232:235], v[12:15]
	v_mfma_f32_16x16x32_bf16 v[8:11], v[162:165], v[232:235], v[8:11]
	v_mfma_f32_16x16x32_bf16 v[52:55], v[166:169], v[204:207], 0
	v_mfma_f32_16x16x32_bf16 v[48:51], v[196:199], v[204:207], 0
	v_mfma_f32_16x16x32_bf16 v[36:39], v[166:169], v[212:215], 0
	v_mfma_f32_16x16x32_bf16 v[32:35], v[196:199], v[212:215], 0
	v_mfma_f32_16x16x32_bf16 v[20:23], v[166:169], v[220:223], 0
	v_mfma_f32_16x16x32_bf16 v[16:19], v[196:199], v[220:223], 0
	v_mfma_f32_16x16x32_bf16 v[4:7], v[166:169], v[228:231], 0
	v_mfma_f32_16x16x32_bf16 v[0:3], v[196:199], v[228:231], 0
	v_mfma_f32_16x16x32_bf16 v[52:55], v[192:195], v[208:211], v[52:55]
	v_mfma_f32_16x16x32_bf16 v[48:51], v[200:203], v[208:211], v[48:51]
	v_mfma_f32_16x16x32_bf16 v[36:39], v[192:195], v[216:219], v[36:39]
	v_mfma_f32_16x16x32_bf16 v[32:35], v[200:203], v[216:219], v[32:35]
	v_mfma_f32_16x16x32_bf16 v[20:23], v[192:195], v[224:227], v[20:23]
	v_mfma_f32_16x16x32_bf16 v[16:19], v[200:203], v[224:227], v[16:19]
	v_mfma_f32_16x16x32_bf16 v[4:7], v[192:195], v[232:235], v[4:7]
	v_mfma_f32_16x16x32_bf16 v[0:3], v[200:203], v[232:235], v[0:3]
	s_setprio 0
	s_barrier
	s_add_i32 s47, 0, 0x18000
	s_add_i32 s50, 0, 0x1c000
	v_add_u32_e32 v162, s47, v159
	v_add_u32_e32 v184, s50, v159
	ds_read_b128 v[146:149], v162
	ds_read_b128 v[150:153], v162 offset:1024
	ds_read_b128 v[154:157], v162 offset:2048
	ds_read_b128 v[162:165], v162 offset:3072
	ds_read_b128 v[166:169], v184
	ds_read_b128 v[192:195], v184 offset:1024
	ds_read_b128 v[196:199], v184 offset:2048
	ds_read_b128 v[200:203], v184 offset:3072
	s_add_u32 s24, s60, 0x40000
	s_addc_u32 s25, s61, 0
	s_mov_b32 m0, s63
	v_lshl_add_u64 v[242:243], s[24:25], 0, v[128:129]
	ds_read_b128 v[204:207], v161 offset:32768
	ds_read_b128 v[208:211], v161 offset:33792
	ds_read_b128 v[212:215], v161 offset:34816
	ds_read_b128 v[216:219], v161 offset:35840
	ds_read_b128 v[220:223], v161 offset:36864
	ds_read_b128 v[224:227], v161 offset:37888
	ds_read_b128 v[228:231], v161 offset:38912
	ds_read_b128 v[232:235], v161 offset:39936
	global_load_lds_dwordx4 v[242:243], off
	v_lshl_add_u64 v[242:243], s[24:25], 0, v[130:131]
	s_mov_b32 m0, s64
	s_nop 0
	global_load_lds_dwordx4 v[242:243], off
	s_waitcnt vmcnt(8)
	s_waitcnt lgkmcnt(0)
	s_barrier
	s_setprio 1
	v_mfma_f32_16x16x32_bf16 v[124:127], v[146:149], v[204:207], v[124:127]
	v_mfma_f32_16x16x32_bf16 v[120:123], v[154:157], v[204:207], v[120:123]
	v_mfma_f32_16x16x32_bf16 v[108:111], v[146:149], v[212:215], v[108:111]
	v_mfma_f32_16x16x32_bf16 v[104:107], v[154:157], v[212:215], v[104:107]
	v_mfma_f32_16x16x32_bf16 v[92:95], v[146:149], v[220:223], v[92:95]
	v_mfma_f32_16x16x32_bf16 v[88:91], v[154:157], v[220:223], v[88:91]
	v_mfma_f32_16x16x32_bf16 v[76:79], v[146:149], v[228:231], v[76:79]
	v_mfma_f32_16x16x32_bf16 v[72:75], v[154:157], v[228:231], v[72:75]
	v_mfma_f32_16x16x32_bf16 v[124:127], v[150:153], v[208:211], v[124:127]
	v_mfma_f32_16x16x32_bf16 v[120:123], v[162:165], v[208:211], v[120:123]
	v_mfma_f32_16x16x32_bf16 v[108:111], v[150:153], v[216:219], v[108:111]
	v_mfma_f32_16x16x32_bf16 v[104:107], v[162:165], v[216:219], v[104:107]
	v_mfma_f32_16x16x32_bf16 v[92:95], v[150:153], v[224:227], v[92:95]
	v_mfma_f32_16x16x32_bf16 v[88:91], v[162:165], v[224:227], v[88:91]
	v_mfma_f32_16x16x32_bf16 v[76:79], v[150:153], v[232:235], v[76:79]
	v_mfma_f32_16x16x32_bf16 v[72:75], v[162:165], v[232:235], v[72:75]
	v_mfma_f32_16x16x32_bf16 v[116:119], v[166:169], v[204:207], v[116:119]
	v_mfma_f32_16x16x32_bf16 v[112:115], v[196:199], v[204:207], v[112:115]
	v_mfma_f32_16x16x32_bf16 v[100:103], v[166:169], v[212:215], v[100:103]
	v_mfma_f32_16x16x32_bf16 v[96:99], v[196:199], v[212:215], v[96:99]
	v_mfma_f32_16x16x32_bf16 v[84:87], v[166:169], v[220:223], v[84:87]
	v_mfma_f32_16x16x32_bf16 v[80:83], v[196:199], v[220:223], v[80:83]
	v_mfma_f32_16x16x32_bf16 v[68:71], v[166:169], v[228:231], v[68:71]
	v_mfma_f32_16x16x32_bf16 v[64:67], v[196:199], v[228:231], v[64:67]
	v_mfma_f32_16x16x32_bf16 v[116:119], v[192:195], v[208:211], v[116:119]
	v_mfma_f32_16x16x32_bf16 v[112:115], v[200:203], v[208:211], v[112:115]
	v_mfma_f32_16x16x32_bf16 v[100:103], v[192:195], v[216:219], v[100:103]
	v_mfma_f32_16x16x32_bf16 v[96:99], v[200:203], v[216:219], v[96:99]
	v_mfma_f32_16x16x32_bf16 v[84:87], v[192:195], v[224:227], v[84:87]
	v_mfma_f32_16x16x32_bf16 v[80:83], v[200:203], v[224:227], v[80:83]
	v_mfma_f32_16x16x32_bf16 v[68:71], v[192:195], v[232:235], v[68:71]
	v_mfma_f32_16x16x32_bf16 v[64:67], v[200:203], v[232:235], v[64:67]
	s_setprio 0
	s_barrier
; #define PG8_STAGE(bufoff, gbase, voff) do { _Pragma("unroll") for (int _i = 0; _i < 2; ++_i) \
;         __builtin_amdgcn_global_load_lds((const unsigned*)((const char*)(gbase) + (voff)[_i]), (PG8_LAS unsigned*)(lds + (bufoff) + ldsw + _i * 8192), 16, 0, 0); } while (0)
; #define PG8_LDA(dst, b, h) do { _Pragma("unroll") for (int m = 0; m < 4; ++m) _Pragma("unroll") for (int k = 0; k < 2; ++k) dst[m][k] = *(const PG8_LAS bf16x8*)(lds + PG8_SA(b, h) + aoff + m * 2048 + k * 1024); } while (0)
; #define PG8_LDB(dst, b, h) do { _Pragma("unroll") for (int n = 0; n < 2; ++n) _Pragma("unroll") for (int k = 0; k < 2; ++k) dst[n][k] = *(const PG8_LAS bf16x8*)(lds + PG8_SB(b, h) + boff + n * 2048 + k * 1024); } while (0)
; #define PG8_MMA(ai, bj, At, Bt) do { __builtin_amdgcn_s_setprio(1); _Pragma("unroll") for (int m = 0; m < 4; ++m) _Pragma("unroll") for (int n = 0; n < 2; ++n) _Pragma("unroll") for (int k = 0; k < 2; ++k) \
;         acc[ai][bj][m][n] = __builtin_amdgcn_mfma_f32_16x16x32_bf16(Bt[n][k], At[m][k], acc[ai][bj][m][n], 0, 0, 0); __builtin_amdgcn_s_setprio(0); } while (0)
; #define PG8_WAIT_V(n) asm volatile("s_waitcnt vmcnt(" #n ")" ::: "memory")
; #define PG8_BAR __builtin_amdgcn_s_barrier()
; template <class Epi, class Sched, bool ALIGN_EPI = false, bool SP2 = false>
; __device__ __forceinline__ void gemm_phase(PG8_LAS unsigned char* lds, const Gemm g, const Sched& S, const Epi& E) {
;     ...
;         for (int t = 0; t < nt; t += 2) {
;             const bool last = (t == nt - 2);
;             const char* a1 = cA + (size_t)(t + 1) * kstep;
;             const char* a2 = last ? nA : cA + (size_t)(t + 2) * kstep; const char* b2 = last ? nB : cB + (size_t)(t + 2) * kstep;
;             const char* a3 = a2 + kstep; const char* b3 = b2 + kstep;
;             if (last && has_next) S.a_ready(nxt);
;             if constexpr (SP2) {
;             PG8_LDB(B0, 0, 0); PG8_LDB(B1, 0, 1); PG8_SCHED; PG8_LDA(At, 0, 0); PG8_STAGE(PG8_SA(1, 1), a1 + hstep, voffA);
;             PG8_WAIT_V(8); PG8_WAIT_L(0); PG8_BAR; PG8_MMA(0, 0, At, B0); PG8_MMA(0, 1, At, B1); PG8_BAR; PG8_SCHED;
;     ...
;             PG8_LDA(At, 1, 1); PG8_STAGE(PG8_SB(1, 0), b3, voffB); PG8_STAGE(PG8_SB(1, 1), b3 + hstep, voffB); PG8_STAGE(PG8_SA(1, 0), a3, voffA);
;             PG8_WAIT_V(8); PG8_WAIT_L(0); PG8_BAR; PG8_MMA(1, 0, At, B0); PG8_MMA(1, 1, At, B1); PG8_BAR; PG8_SCHED;
	s_add_i32 s24, s47, s23
	v_lshl_add_u64 v[170:171], v[170:171], 0, s[14:15]
	s_mov_b32 m0, s24
	ds_read_b128 v[204:207], v161 offset:49152
	ds_read_b128 v[208:211], v161 offset:50176
	ds_read_b128 v[212:215], v161 offset:51200
	ds_read_b128 v[216:219], v161 offset:52224
	ds_read_b128 v[220:223], v161 offset:53248
	ds_read_b128 v[224:227], v161 offset:54272
	ds_read_b128 v[228:231], v161 offset:55296
	ds_read_b128 v[232:235], v161 offset:56320
	global_load_lds_dwordx4 v[170:171], off
	s_add_i32 m0, s24, 0x2000
	s_add_u32 s24, s58, 0x40080
	v_lshl_add_u64 v[170:171], v[236:237], 0, s[14:15]
	s_addc_u32 s25, s59, 0
	s_add_i32 s47, s50, s23
	global_load_lds_dwordx4 v[170:171], off
	v_lshl_add_u64 v[170:171], s[24:25], 0, v[132:133]
	s_mov_b32 m0, s47
	s_nop 0
	global_load_lds_dwordx4 v[170:171], off
	v_lshl_add_u64 v[170:171], s[24:25], 0, v[140:141]
	s_add_i32 m0, s47, 0x2000
	s_nop 0
	global_load_lds_dwordx4 v[170:171], off
	v_lshl_add_u64 v[170:171], v[238:239], 0, s[14:15]
	s_mov_b32 m0, s65
	s_nop 0
	global_load_lds_dwordx4 v[170:171], off
	v_lshl_add_u64 v[170:171], v[240:241], 0, s[14:15]
	s_mov_b32 m0, s66
	s_nop 0
	global_load_lds_dwordx4 v[170:171], off
	s_waitcnt vmcnt(8)
	s_waitcnt lgkmcnt(0)
	s_barrier
	s_setprio 1
	v_mfma_f32_16x16x32_bf16 v[60:63], v[146:149], v[204:207], v[60:63]
	v_mfma_f32_16x16x32_bf16 v[56:59], v[154:157], v[204:207], v[56:59]
	v_mfma_f32_16x16x32_bf16 v[44:47], v[146:149], v[212:215], v[44:47]
	v_mfma_f32_16x16x32_bf16 v[40:43], v[154:157], v[212:215], v[40:43]
	v_mfma_f32_16x16x32_bf16 v[28:31], v[146:149], v[220:223], v[28:31]
	v_mfma_f32_16x16x32_bf16 v[24:27], v[154:157], v[220:223], v[24:27]
	v_mfma_f32_16x16x32_bf16 v[12:15], v[146:149], v[228:231], v[12:15]
	v_mfma_f32_16x16x32_bf16 v[8:11], v[154:157], v[228:231], v[8:11]
	v_mfma_f32_16x16x32_bf16 v[60:63], v[150:153], v[208:211], v[60:63]
	v_mfma_f32_16x16x32_bf16 v[56:59], v[162:165], v[208:211], v[56:59]
	v_mfma_f32_16x16x32_bf16 v[44:47], v[150:153], v[216:219], v[44:47]
	v_mfma_f32_16x16x32_bf16 v[40:43], v[162:165], v[216:219], v[40:43]
	v_mfma_f32_16x16x32_bf16 v[28:31], v[150:153], v[224:227], v[28:31]
	v_mfma_f32_16x16x32_bf16 v[24:27], v[162:165], v[224:227], v[24:27]
	v_mfma_f32_16x16x32_bf16 v[12:15], v[150:153], v[232:235], v[12:15]
	v_mfma_f32_16x16x32_bf16 v[8:11], v[162:165], v[232:235], v[8:11]
	v_mfma_f32_16x16x32_bf16 v[52:55], v[166:169], v[204:207], v[52:55]
	v_mfma_f32_16x16x32_bf16 v[48:51], v[196:199], v[204:207], v[48:51]
	v_mfma_f32_16x16x32_bf16 v[36:39], v[166:169], v[212:215], v[36:39]
	v_mfma_f32_16x16x32_bf16 v[32:35], v[196:199], v[212:215], v[32:35]
	v_mfma_f32_16x16x32_bf16 v[20:23], v[166:169], v[220:223], v[20:23]
	v_mfma_f32_16x16x32_bf16 v[16:19], v[196:199], v[220:223], v[16:19]
	v_mfma_f32_16x16x32_bf16 v[4:7], v[166:169], v[228:231], v[4:7]
	v_mfma_f32_16x16x32_bf16 v[0:3], v[196:199], v[228:231], v[0:3]
	v_mfma_f32_16x16x32_bf16 v[52:55], v[192:195], v[208:211], v[52:55]
	v_mfma_f32_16x16x32_bf16 v[48:51], v[200:203], v[208:211], v[48:51]
	v_mfma_f32_16x16x32_bf16 v[36:39], v[192:195], v[216:219], v[36:39]
	v_mfma_f32_16x16x32_bf16 v[32:35], v[200:203], v[216:219], v[32:35]
	v_mfma_f32_16x16x32_bf16 v[20:23], v[192:195], v[224:227], v[20:23]
	v_mfma_f32_16x16x32_bf16 v[16:19], v[200:203], v[224:227], v[16:19]
	v_mfma_f32_16x16x32_bf16 v[4:7], v[192:195], v[232:235], v[4:7]
	v_mfma_f32_16x16x32_bf16 v[0:3], v[200:203], v[232:235], v[0:3]
	s_setprio 0
	s_barrier
	s_add_i32 s45, s45, 2
	s_add_u32 s56, s56, 0x100
	s_addc_u32 s57, s57, 0
	s_add_u32 s22, s22, 0x100
	s_addc_u32 s33, s33, 0
	s_cmp_gt_u32 s45, 13
.LBB0_554:
	s_add_u32 s24, s56, 0xfffc0080
	s_addc_u32 s25, s57, -1
	s_add_i32 s47, 0, 0x10000
	s_cmp_eq_u32 s45, 12
	s_cselect_b32 s61, s0, s25
	s_cselect_b32 s60, s1, s24
	s_cselect_b32 s59, s17, s33
	s_cselect_b32 s58, s21, s22
	s_add_i32 s50, 0, 0x14000
	v_add_u32_e32 v162, s47, v159
	v_add_u32_e32 v170, s50, v159
	ds_read_b128 v[146:149], v162
	ds_read_b128 v[150:153], v162 offset:1024
	ds_read_b128 v[154:157], v162 offset:2048
	ds_read_b128 v[162:165], v162 offset:3072
	ds_read_b128 v[166:169], v170
	ds_read_b128 v[192:195], v170 offset:1024
	ds_read_b128 v[196:199], v170 offset:2048
	ds_read_b128 v[200:203], v170 offset:3072
	v_lshl_add_u64 v[170:171], s[56:57], 0, v[142:143]
	s_add_i32 m0, s29, 0xc000
	ds_read_b128 v[204:207], v161
	ds_read_b128 v[208:211], v161 offset:1024
	ds_read_b128 v[212:215], v161 offset:2048
	ds_read_b128 v[216:219], v161 offset:3072
	ds_read_b128 v[220:223], v161 offset:4096
	ds_read_b128 v[224:227], v161 offset:5120
	ds_read_b128 v[228:231], v161 offset:6144
	ds_read_b128 v[232:235], v161 offset:7168
	global_load_lds_dwordx4 v[170:171], off
	v_lshl_add_u64 v[170:171], s[56:57], 0, v[144:145]
	s_add_i32 m0, s29, 0xe000
	s_nop 0
	global_load_lds_dwordx4 v[170:171], off
	s_waitcnt vmcnt(8)
	s_waitcnt lgkmcnt(0)
	s_barrier
; #define PG8_STAGE(bufoff, gbase, voff) do { _Pragma("unroll") for (int _i = 0; _i < 2; ++_i) \
;         __builtin_amdgcn_global_load_lds((const unsigned*)((const char*)(gbase) + (voff)[_i]), (PG8_LAS unsigned*)(lds + (bufoff) + ldsw + _i * 8192), 16, 0, 0); } while (0)
; #define PG8_LDA(dst, b, h) do { _Pragma("unroll") for (int m = 0; m < 4; ++m) _Pragma("unroll") for (int k = 0; k < 2; ++k) dst[m][k] = *(const PG8_LAS bf16x8*)(lds + PG8_SA(b, h) + aoff + m * 2048 + k * 1024); } while (0)
; #define PG8_MMA(ai, bj, At, Bt) do { __builtin_amdgcn_s_setprio(1); _Pragma("unroll") for (int m = 0; m < 4; ++m) _Pragma("unroll") for (int n = 0; n < 2; ++n) _Pragma("unroll") for (int k = 0; k < 2; ++k) \
;         acc[ai][bj][m][n] = __builtin_amdgcn_mfma_f32_16x16x32_bf16(Bt[n][k], At[m][k], acc[ai][bj][m][n], 0, 0, 0); __builtin_amdgcn_s_setprio(0); } while (0)
; #define PG8_WAIT_V(n) asm volatile("s_waitcnt vmcnt(" #n ")" ::: "memory")
; #define PG8_WAIT_L(n) asm volatile("s_waitcnt lgkmcnt(" #n ")" ::: "memory")
; #define PG8_BAR __builtin_amdgcn_s_barrier()
; #define PG8_SCHED __builtin_amdgcn_sched_barrier(0)
; template <class Epi, class Sched, bool ALIGN_EPI = false, bool SP2 = false>
; __device__ __forceinline__ void gemm_phase(PG8_LAS unsigned char* lds, const Gemm g, const Sched& S, const Epi& E) {
;     ...
;             PG8_WAIT_V(8); PG8_WAIT_L(0); PG8_BAR; PG8_MMA(0, 0, At, B0); PG8_MMA(0, 1, At, B1); PG8_BAR; PG8_SCHED;
;             PG8_LDA(At, 0, 1); PG8_STAGE(PG8_SB(0, 0), b2, voffB); PG8_STAGE(PG8_SB(0, 1), b2 + hstep, voffB); PG8_STAGE(PG8_SA(0, 0), a2, voffA);
;             PG8_WAIT_V(8); PG8_WAIT_L(0); PG8_BAR; PG8_MMA(1, 0, At, B0); PG8_MMA(1, 1, At, B1); PG8_BAR; PG8_SCHED;
	s_setprio 1
	v_mfma_f32_16x16x32_bf16 v[124:127], v[146:149], v[204:207], v[124:127]
	v_mfma_f32_16x16x32_bf16 v[120:123], v[154:157], v[204:207], v[120:123]
	v_mfma_f32_16x16x32_bf16 v[108:111], v[146:149], v[212:215], v[108:111]
	v_mfma_f32_16x16x32_bf16 v[104:107], v[154:157], v[212:215], v[104:107]
	v_mfma_f32_16x16x32_bf16 v[92:95], v[146:149], v[220:223], v[92:95]
	v_mfma_f32_16x16x32_bf16 v[88:91], v[154:157], v[220:223], v[88:91]
	v_mfma_f32_16x16x32_bf16 v[76:79], v[146:149], v[228:231], v[76:79]
	v_mfma_f32_16x16x32_bf16 v[72:75], v[154:157], v[228:231], v[72:75]
	v_mfma_f32_16x16x32_bf16 v[124:127], v[150:153], v[208:211], v[124:127]
	v_mfma_f32_16x16x32_bf16 v[120:123], v[162:165], v[208:211], v[120:123]
	v_mfma_f32_16x16x32_bf16 v[108:111], v[150:153], v[216:219], v[108:111]
	v_mfma_f32_16x16x32_bf16 v[104:107], v[162:165], v[216:219], v[104:107]
	v_mfma_f32_16x16x32_bf16 v[92:95], v[150:153], v[224:227], v[92:95]
	v_mfma_f32_16x16x32_bf16 v[88:91], v[162:165], v[224:227], v[88:91]
	v_mfma_f32_16x16x32_bf16 v[76:79], v[150:153], v[232:235], v[76:79]
	v_mfma_f32_16x16x32_bf16 v[72:75], v[162:165], v[232:235], v[72:75]
	v_mfma_f32_16x16x32_bf16 v[116:119], v[166:169], v[204:207], v[116:119]
	v_mfma_f32_16x16x32_bf16 v[112:115], v[196:199], v[204:207], v[112:115]
	v_mfma_f32_16x16x32_bf16 v[100:103], v[166:169], v[212:215], v[100:103]
	v_mfma_f32_16x16x32_bf16 v[96:99], v[196:199], v[212:215], v[96:99]
	v_mfma_f32_16x16x32_bf16 v[84:87], v[166:169], v[220:223], v[84:87]
	v_mfma_f32_16x16x32_bf16 v[80:83], v[196:199], v[220:223], v[80:83]
	v_mfma_f32_16x16x32_bf16 v[68:71], v[166:169], v[228:231], v[68:71]
	v_mfma_f32_16x16x32_bf16 v[64:67], v[196:199], v[228:231], v[64:67]
	v_mfma_f32_16x16x32_bf16 v[116:119], v[192:195], v[208:211], v[116:119]
	v_mfma_f32_16x16x32_bf16 v[112:115], v[200:203], v[208:211], v[112:115]
	v_mfma_f32_16x16x32_bf16 v[100:103], v[192:195], v[216:219], v[100:103]
	v_mfma_f32_16x16x32_bf16 v[96:99], v[200:203], v[216:219], v[96:99]
	v_mfma_f32_16x16x32_bf16 v[84:87], v[192:195], v[224:227], v[84:87]
	v_mfma_f32_16x16x32_bf16 v[80:83], v[200:203], v[224:227], v[80:83]
	v_mfma_f32_16x16x32_bf16 v[68:71], v[192:195], v[232:235], v[68:71]
	v_mfma_f32_16x16x32_bf16 v[64:67], v[200:203], v[232:235], v[64:67]
	s_setprio 0
	s_barrier
	s_add_i32 s24, s47, s23
	v_lshl_add_u64 v[170:171], s[58:59], 0, v[132:133]
	s_mov_b32 m0, s24
	ds_read_b128 v[204:207], v161 offset:16384
	ds_read_b128 v[208:211], v161 offset:17408
	ds_read_b128 v[212:215], v161 offset:18432
	ds_read_b128 v[216:219], v161 offset:19456
	ds_read_b128 v[220:223], v161 offset:20480
	ds_read_b128 v[224:227], v161 offset:21504
	ds_read_b128 v[228:231], v161 offset:22528
	ds_read_b128 v[232:235], v161 offset:23552
	global_load_lds_dwordx4 v[170:171], off
	s_add_i32 m0, s24, 0x2000
	s_add_u32 s24, s58, 0x40000
	v_lshl_add_u64 v[236:237], s[58:59], 0, v[140:141]
	s_addc_u32 s25, s59, 0
	s_add_i32 s47, s50, s23
	global_load_lds_dwordx4 v[236:237], off
	v_lshl_add_u64 v[238:239], s[24:25], 0, v[132:133]
	s_mov_b32 m0, s47
	v_lshl_add_u64 v[240:241], s[60:61], 0, v[130:131]
	global_load_lds_dwordx4 v[238:239], off
	v_lshl_add_u64 v[238:239], s[24:25], 0, v[140:141]
	s_add_i32 m0, s47, 0x2000
	s_nop 0
	global_load_lds_dwordx4 v[238:239], off
	v_lshl_add_u64 v[238:239], s[60:61], 0, v[128:129]
	s_mov_b32 m0, s29
	s_nop 0
	global_load_lds_dwordx4 v[238:239], off
	s_mov_b32 m0, s62
	s_nop 0
	global_load_lds_dwordx4 v[240:241], off
	s_waitcnt vmcnt(8)
	s_waitcnt lgkmcnt(0)
	s_barrier
	s_setprio 1
	v_mfma_f32_16x16x32_bf16 v[60:63], v[146:149], v[204:207], v[60:63]
	v_mfma_f32_16x16x32_bf16 v[56:59], v[154:157], v[204:207], v[56:59]
	v_mfma_f32_16x16x32_bf16 v[44:47], v[146:149], v[212:215], v[44:47]
	v_mfma_f32_16x16x32_bf16 v[40:43], v[154:157], v[212:215], v[40:43]
	v_mfma_f32_16x16x32_bf16 v[28:31], v[146:149], v[220:223], v[28:31]
	v_mfma_f32_16x16x32_bf16 v[24:27], v[154:157], v[220:223], v[24:27]
	v_mfma_f32_16x16x32_bf16 v[12:15], v[146:149], v[228:231], v[12:15]
	v_mfma_f32_16x16x32_bf16 v[8:11], v[154:157], v[228:231], v[8:11]
	v_mfma_f32_16x16x32_bf16 v[60:63], v[150:153], v[208:211], v[60:63]
	v_mfma_f32_16x16x32_bf16 v[56:59], v[162:165], v[208:211], v[56:59]
	v_mfma_f32_16x16x32_bf16 v[44:47], v[150:153], v[216:219], v[44:47]
	v_mfma_f32_16x16x32_bf16 v[40:43], v[162:165], v[216:219], v[40:43]
	v_mfma_f32_16x16x32_bf16 v[28:31], v[150:153], v[224:227], v[28:31]
	v_mfma_f32_16x16x32_bf16 v[24:27], v[162:165], v[224:227], v[24:27]
	v_mfma_f32_16x16x32_bf16 v[12:15], v[150:153], v[232:235], v[12:15]
	v_mfma_f32_16x16x32_bf16 v[8:11], v[162:165], v[232:235], v[8:11]
	v_mfma_f32_16x16x32_bf16 v[52:55], v[166:169], v[204:207], v[52:55]
	v_mfma_f32_16x16x32_bf16 v[48:51], v[196:199], v[204:207], v[48:51]
	v_mfma_f32_16x16x32_bf16 v[36:39], v[166:169], v[212:215], v[36:39]
	v_mfma_f32_16x16x32_bf16 v[32:35], v[196:199], v[212:215], v[32:35]
	v_mfma_f32_16x16x32_bf16 v[20:23], v[166:169], v[220:223], v[20:23]
	v_mfma_f32_16x16x32_bf16 v[16:19], v[196:199], v[220:223], v[16:19]
	v_mfma_f32_16x16x32_bf16 v[4:7], v[166:169], v[228:231], v[4:7]
	v_mfma_f32_16x16x32_bf16 v[0:3], v[196:199], v[228:231], v[0:3]
	v_mfma_f32_16x16x32_bf16 v[52:55], v[192:195], v[208:211], v[52:55]
	v_mfma_f32_16x16x32_bf16 v[48:51], v[200:203], v[208:211], v[48:51]
	v_mfma_f32_16x16x32_bf16 v[36:39], v[192:195], v[216:219], v[36:39]
	v_mfma_f32_16x16x32_bf16 v[32:35], v[200:203], v[216:219], v[32:35]
	v_mfma_f32_16x16x32_bf16 v[20:23], v[192:195], v[224:227], v[20:23]
	v_mfma_f32_16x16x32_bf16 v[16:19], v[200:203], v[224:227], v[16:19]
	v_mfma_f32_16x16x32_bf16 v[4:7], v[192:195], v[232:235], v[4:7]
	v_mfma_f32_16x16x32_bf16 v[0:3], v[200:203], v[232:235], v[0:3]
	s_setprio 0
	s_barrier
; #define PG8_STAGE(bufoff, gbase, voff) do { _Pragma("unroll") for (int _i = 0; _i < 2; ++_i) \
;         __builtin_amdgcn_global_load_lds((const unsigned*)((const char*)(gbase) + (voff)[_i]), (PG8_LAS unsigned*)(lds + (bufoff) + ldsw + _i * 8192), 16, 0, 0); } while (0)
; #define PG8_LDA(dst, b, h) do { _Pragma("unroll") for (int m = 0; m < 4; ++m) _Pragma("unroll") for (int k = 0; k < 2; ++k) dst[m][k] = *(const PG8_LAS bf16x8*)(lds + PG8_SA(b, h) + aoff + m * 2048 + k * 1024); } while (0)
; #define PG8_LDB(dst, b, h) do { _Pragma("unroll") for (int n = 0; n < 2; ++n) _Pragma("unroll") for (int k = 0; k < 2; ++k) dst[n][k] = *(const PG8_LAS bf16x8*)(lds + PG8_SB(b, h) + boff + n * 2048 + k * 1024); } while (0)
; #define PG8_MMA(ai, bj, At, Bt) do { __builtin_amdgcn_s_setprio(1); _Pragma("unroll") for (int m = 0; m < 4; ++m) _Pragma("unroll") for (int n = 0; n < 2; ++n) _Pragma("unroll") for (int k = 0; k < 2; ++k) \
;         acc[ai][bj][m][n] = __builtin_amdgcn_mfma_f32_16x16x32_bf16(Bt[n][k], At[m][k], acc[ai][bj][m][n], 0, 0, 0); __builtin_amdgcn_s_setprio(0); } while (0)
; #define PG8_WAIT_V(n) asm volatile("s_waitcnt vmcnt(" #n ")" ::: "memory")
; #define PG8_WAIT_L(n) asm volatile("s_waitcnt lgkmcnt(" #n ")" ::: "memory")
; #define PG8_BAR __builtin_amdgcn_s_barrier()
; #define PG8_SCHED __builtin_amdgcn_sched_barrier(0)
; template <class Epi, class Sched, bool ALIGN_EPI = false, bool SP2 = false>
; __device__ __forceinline__ void gemm_phase(PG8_LAS unsigned char* lds, const Gemm g, const Sched& S, const Epi& E) {
;     ...
;             PG8_LDB(B0, 1, 0); PG8_LDB(B1, 1, 1); PG8_SCHED; PG8_LDA(At, 1, 0); PG8_STAGE(PG8_SA(0, 1), a2 + hstep, voffA);
;             PG8_WAIT_V(8); PG8_WAIT_L(0); PG8_BAR; PG8_MMA(0, 0, At, B0); PG8_MMA(0, 1, At, B1); PG8_BAR; PG8_SCHED;
	s_add_i32 s47, 0, 0x18000
	s_add_i32 s50, 0, 0x1c000
	v_add_u32_e32 v162, s47, v159
	v_add_u32_e32 v184, s50, v159
	ds_read_b128 v[146:149], v162
	ds_read_b128 v[150:153], v162 offset:1024
	ds_read_b128 v[154:157], v162 offset:2048
	ds_read_b128 v[162:165], v162 offset:3072
	ds_read_b128 v[166:169], v184
	ds_read_b128 v[192:195], v184 offset:1024
	ds_read_b128 v[196:199], v184 offset:2048
	ds_read_b128 v[200:203], v184 offset:3072
	s_add_u32 s24, s60, 0x40000
	s_addc_u32 s25, s61, 0
	s_mov_b32 m0, s63
	v_lshl_add_u64 v[242:243], s[24:25], 0, v[128:129]
	ds_read_b128 v[204:207], v161 offset:32768
	ds_read_b128 v[208:211], v161 offset:33792
	ds_read_b128 v[212:215], v161 offset:34816
	ds_read_b128 v[216:219], v161 offset:35840
	ds_read_b128 v[220:223], v161 offset:36864
	ds_read_b128 v[224:227], v161 offset:37888
	ds_read_b128 v[228:231], v161 offset:38912
	ds_read_b128 v[232:235], v161 offset:39936
	global_load_lds_dwordx4 v[242:243], off
	v_lshl_add_u64 v[242:243], s[24:25], 0, v[130:131]
	s_mov_b32 m0, s64
	s_nop 0
	global_load_lds_dwordx4 v[242:243], off
	s_waitcnt vmcnt(8)
	s_waitcnt lgkmcnt(0)
	s_barrier
	s_setprio 1
	v_mfma_f32_16x16x32_bf16 v[124:127], v[146:149], v[204:207], v[124:127]
	v_mfma_f32_16x16x32_bf16 v[120:123], v[154:157], v[204:207], v[120:123]
	v_mfma_f32_16x16x32_bf16 v[108:111], v[146:149], v[212:215], v[108:111]
	v_mfma_f32_16x16x32_bf16 v[104:107], v[154:157], v[212:215], v[104:107]
	v_mfma_f32_16x16x32_bf16 v[92:95], v[146:149], v[220:223], v[92:95]
	v_mfma_f32_16x16x32_bf16 v[88:91], v[154:157], v[220:223], v[88:91]
	v_mfma_f32_16x16x32_bf16 v[76:79], v[146:149], v[228:231], v[76:79]
	v_mfma_f32_16x16x32_bf16 v[72:75], v[154:157], v[228:231], v[72:75]
	v_mfma_f32_16x16x32_bf16 v[124:127], v[150:153], v[208:211], v[124:127]
	v_mfma_f32_16x16x32_bf16 v[120:123], v[162:165], v[208:211], v[120:123]
	v_mfma_f32_16x16x32_bf16 v[108:111], v[150:153], v[216:219], v[108:111]
	v_mfma_f32_16x16x32_bf16 v[104:107], v[162:165], v[216:219], v[104:107]
	v_mfma_f32_16x16x32_bf16 v[92:95], v[150:153], v[224:227], v[92:95]
	v_mfma_f32_16x16x32_bf16 v[88:91], v[162:165], v[224:227], v[88:91]
	v_mfma_f32_16x16x32_bf16 v[76:79], v[150:153], v[232:235], v[76:79]
	v_mfma_f32_16x16x32_bf16 v[72:75], v[162:165], v[232:235], v[72:75]
	v_mfma_f32_16x16x32_bf16 v[116:119], v[166:169], v[204:207], v[116:119]
	v_mfma_f32_16x16x32_bf16 v[112:115], v[196:199], v[204:207], v[112:115]
	v_mfma_f32_16x16x32_bf16 v[100:103], v[166:169], v[212:215], v[100:103]
	v_mfma_f32_16x16x32_bf16 v[96:99], v[196:199], v[212:215], v[96:99]
	v_mfma_f32_16x16x32_bf16 v[84:87], v[166:169], v[220:223], v[84:87]
	v_mfma_f32_16x16x32_bf16 v[80:83], v[196:199], v[220:223], v[80:83]
	v_mfma_f32_16x16x32_bf16 v[68:71], v[166:169], v[228:231], v[68:71]
	v_mfma_f32_16x16x32_bf16 v[64:67], v[196:199], v[228:231], v[64:67]
	v_mfma_f32_16x16x32_bf16 v[116:119], v[192:195], v[208:211], v[116:119]
	v_mfma_f32_16x16x32_bf16 v[112:115], v[200:203], v[208:211], v[112:115]
	v_mfma_f32_16x16x32_bf16 v[100:103], v[192:195], v[216:219], v[100:103]
	v_mfma_f32_16x16x32_bf16 v[96:99], v[200:203], v[216:219], v[96:99]
	v_mfma_f32_16x16x32_bf16 v[84:87], v[192:195], v[224:227], v[84:87]
	v_mfma_f32_16x16x32_bf16 v[80:83], v[200:203], v[224:227], v[80:83]
	v_mfma_f32_16x16x32_bf16 v[68:71], v[192:195], v[232:235], v[68:71]
	v_mfma_f32_16x16x32_bf16 v[64:67], v[200:203], v[232:235], v[64:67]
	s_setprio 0
	s_barrier
; #define PG8_STAGE(bufoff, gbase, voff) do { _Pragma("unroll") for (int _i = 0; _i < 2; ++_i) \
;         __builtin_amdgcn_global_load_lds((const unsigned*)((const char*)(gbase) + (voff)[_i]), (PG8_LAS unsigned*)(lds + (bufoff) + ldsw + _i * 8192), 16, 0, 0); } while (0)
; #define PG8_LDA(dst, b, h) do { _Pragma("unroll") for (int m = 0; m < 4; ++m) _Pragma("unroll") for (int k = 0; k < 2; ++k) dst[m][k] = *(const PG8_LAS bf16x8*)(lds + PG8_SA(b, h) + aoff + m * 2048 + k * 1024); } while (0)
; #define PG8_MMA(ai, bj, At, Bt) do { __builtin_amdgcn_s_setprio(1); _Pragma("unroll") for (int m = 0; m < 4; ++m) _Pragma("unroll") for (int n = 0; n < 2; ++n) _Pragma("unroll") for (int k = 0; k < 2; ++k) \
;         acc[ai][bj][m][n] = __builtin_amdgcn_mfma_f32_16x16x32_bf16(Bt[n][k], At[m][k], acc[ai][bj][m][n], 0, 0, 0); __builtin_amdgcn_s_setprio(0); } while (0)
; #define PG8_WAIT_V(n) asm volatile("s_waitcnt vmcnt(" #n ")" ::: "memory")
; #define PG8_WAIT_L(n) asm volatile("s_waitcnt lgkmcnt(" #n ")" ::: "memory")
; #define PG8_BAR __builtin_amdgcn_s_barrier()
; #define PG8_SCHED __builtin_amdgcn_sched_barrier(0)
; template <class Epi, class Sched, bool ALIGN_EPI = false, bool SP2 = false>
; __device__ __forceinline__ void gemm_phase(PG8_LAS unsigned char* lds, const Gemm g, const Sched& S, const Epi& E) {
;     ...
;             PG8_LDA(At, 1, 1); PG8_STAGE(PG8_SB(1, 0), b3, voffB); PG8_STAGE(PG8_SB(1, 1), b3 + hstep, voffB); PG8_STAGE(PG8_SA(1, 0), a3, voffA);
;             PG8_WAIT_V(8); PG8_WAIT_L(0); PG8_BAR; PG8_MMA(1, 0, At, B0); PG8_MMA(1, 1, At, B1); PG8_BAR; PG8_SCHED;
;     ...
;         if constexpr (ALIGN_EPI) { if (wr == 0) PG8_BAR; }
	s_add_i32 s24, s47, s23
	v_lshl_add_u64 v[170:171], v[170:171], 0, s[14:15]
	s_mov_b32 m0, s24
	ds_read_b128 v[204:207], v161 offset:49152
	ds_read_b128 v[208:211], v161 offset:50176
	ds_read_b128 v[212:215], v161 offset:51200
	ds_read_b128 v[216:219], v161 offset:52224
	ds_read_b128 v[220:223], v161 offset:53248
	ds_read_b128 v[224:227], v161 offset:54272
	ds_read_b128 v[228:231], v161 offset:55296
	ds_read_b128 v[232:235], v161 offset:56320
	global_load_lds_dwordx4 v[170:171], off
	s_add_i32 m0, s24, 0x2000
	s_add_u32 s24, s58, 0x40080
	v_lshl_add_u64 v[170:171], v[236:237], 0, s[14:15]
	s_addc_u32 s25, s59, 0
	s_add_i32 s47, s50, s23
	global_load_lds_dwordx4 v[170:171], off
	v_lshl_add_u64 v[170:171], s[24:25], 0, v[132:133]
	s_mov_b32 m0, s47
	s_nop 0
	global_load_lds_dwordx4 v[170:171], off
	v_lshl_add_u64 v[170:171], s[24:25], 0, v[140:141]
	s_add_i32 m0, s47, 0x2000
	s_nop 0
	global_load_lds_dwordx4 v[170:171], off
	v_lshl_add_u64 v[170:171], v[238:239], 0, s[14:15]
	s_mov_b32 m0, s65
	s_nop 0
	global_load_lds_dwordx4 v[170:171], off
	v_lshl_add_u64 v[170:171], v[240:241], 0, s[14:15]
	s_mov_b32 m0, s66
	s_nop 0
	global_load_lds_dwordx4 v[170:171], off
	s_waitcnt vmcnt(8)
	s_waitcnt lgkmcnt(0)
	s_barrier
	s_setprio 1
	v_mfma_f32_16x16x32_bf16 v[60:63], v[146:149], v[204:207], v[60:63]
	v_mfma_f32_16x16x32_bf16 v[56:59], v[154:157], v[204:207], v[56:59]
	v_mfma_f32_16x16x32_bf16 v[44:47], v[146:149], v[212:215], v[44:47]
	v_mfma_f32_16x16x32_bf16 v[40:43], v[154:157], v[212:215], v[40:43]
	v_mfma_f32_16x16x32_bf16 v[28:31], v[146:149], v[220:223], v[28:31]
	v_mfma_f32_16x16x32_bf16 v[24:27], v[154:157], v[220:223], v[24:27]
	v_mfma_f32_16x16x32_bf16 v[12:15], v[146:149], v[228:231], v[12:15]
	v_mfma_f32_16x16x32_bf16 v[8:11], v[154:157], v[228:231], v[8:11]
	v_mfma_f32_16x16x32_bf16 v[60:63], v[150:153], v[208:211], v[60:63]
	v_mfma_f32_16x16x32_bf16 v[56:59], v[162:165], v[208:211], v[56:59]
	v_mfma_f32_16x16x32_bf16 v[44:47], v[150:153], v[216:219], v[44:47]
	v_mfma_f32_16x16x32_bf16 v[40:43], v[162:165], v[216:219], v[40:43]
	v_mfma_f32_16x16x32_bf16 v[28:31], v[150:153], v[224:227], v[28:31]
	v_mfma_f32_16x16x32_bf16 v[24:27], v[162:165], v[224:227], v[24:27]
	v_mfma_f32_16x16x32_bf16 v[12:15], v[150:153], v[232:235], v[12:15]
	v_mfma_f32_16x16x32_bf16 v[8:11], v[162:165], v[232:235], v[8:11]
	v_mfma_f32_16x16x32_bf16 v[52:55], v[166:169], v[204:207], v[52:55]
	v_mfma_f32_16x16x32_bf16 v[48:51], v[196:199], v[204:207], v[48:51]
	v_mfma_f32_16x16x32_bf16 v[36:39], v[166:169], v[212:215], v[36:39]
	v_mfma_f32_16x16x32_bf16 v[32:35], v[196:199], v[212:215], v[32:35]
	v_mfma_f32_16x16x32_bf16 v[20:23], v[166:169], v[220:223], v[20:23]
	v_mfma_f32_16x16x32_bf16 v[16:19], v[196:199], v[220:223], v[16:19]
	v_mfma_f32_16x16x32_bf16 v[4:7], v[166:169], v[228:231], v[4:7]
	v_mfma_f32_16x16x32_bf16 v[0:3], v[196:199], v[228:231], v[0:3]
	v_mfma_f32_16x16x32_bf16 v[52:55], v[192:195], v[208:211], v[52:55]
	v_mfma_f32_16x16x32_bf16 v[48:51], v[200:203], v[208:211], v[48:51]
	v_mfma_f32_16x16x32_bf16 v[36:39], v[192:195], v[216:219], v[36:39]
	v_mfma_f32_16x16x32_bf16 v[32:35], v[200:203], v[216:219], v[32:35]
	v_mfma_f32_16x16x32_bf16 v[20:23], v[192:195], v[224:227], v[20:23]
	v_mfma_f32_16x16x32_bf16 v[16:19], v[200:203], v[224:227], v[16:19]
	v_mfma_f32_16x16x32_bf16 v[4:7], v[192:195], v[232:235], v[4:7]
	v_mfma_f32_16x16x32_bf16 v[0:3], v[200:203], v[232:235], v[0:3]
	s_setprio 0
	s_barrier
	s_add_i32 s45, s45, 2
	s_add_u32 s56, s56, 0x100
	s_addc_u32 s57, s57, 0
	s_add_u32 s22, s22, 0x100
	s_addc_u32 s33, s33, 0
	s_cmp_gt_u32 s45, 13
	s_cbranch_scc0 .LBB0_554
	s_and_b64 vcc, exec, s[8:9]
	s_cbranch_vccz .LBB0_557
	s_barrier

; #define PG8_STAGE(bufoff, gbase, voff) do { _Pragma("unroll") for (int _i = 0; _i < 2; ++_i) \
;         __builtin_amdgcn_global_load_lds((const unsigned*)((const char*)(gbase) + (voff)[_i]), (PG8_LAS unsigned*)(lds + (bufoff) + ldsw + _i * 8192), 16, 0, 0); } while (0)
; #define PG8_LDA(dst, b, h) do { _Pragma("unroll") for (int m = 0; m < 4; ++m) _Pragma("unroll") for (int k = 0; k < 2; ++k) dst[m][k] = *(const PG8_LAS bf16x8*)(lds + PG8_SA(b, h) + aoff + m * 2048 + k * 1024); } while (0)
; #define PG8_LDB(dst, b, h) do { _Pragma("unroll") for (int n = 0; n < 2; ++n) _Pragma("unroll") for (int k = 0; k < 2; ++k) dst[n][k] = *(const PG8_LAS bf16x8*)(lds + PG8_SB(b, h) + boff + n * 2048 + k * 1024); } while (0)
; #define PG8_WAIT_V(n) asm volatile("s_waitcnt vmcnt(" #n ")" ::: "memory")
; #define PG8_WAIT_L(n) asm volatile("s_waitcnt lgkmcnt(" #n ")" ::: "memory")
; #define PG8_BAR __builtin_amdgcn_s_barrier()
; #define PG8_SCHED __builtin_amdgcn_sched_barrier(0)
; template <class Epi, class Sched, bool ALIGN_EPI = false, bool SP2 = false>
; __device__ __forceinline__ void gemm_phase(PG8_LAS unsigned char* lds, const Gemm g, const Sched& S, const Epi& E) {
;     ...
;         const bool has_next = S.next(ui + 1, nxt);
;         const char* nA = has_next ? (const char*)g.A + (size_t)nxt.pm * tstep : cA; const char* nB = has_next ? (const char*)g.Bt + (size_t)nxt.pn * tstep : cB;
;         for (int t = 0; t < nt; t += 2) {
;             const bool last = (t == nt - 2);
;             const char* a1 = cA + (size_t)(t + 1) * kstep;
;             const char* a2 = last ? nA : cA + (size_t)(t + 2) * kstep; const char* b2 = last ? nB : cB + (size_t)(t + 2) * kstep;
;             const char* a3 = a2 + kstep; const char* b3 = b2 + kstep;
;             if (last && has_next) S.a_ready(nxt);
;             if constexpr (SP2) {
;             PG8_LDB(B0, 0, 0); PG8_LDB(B1, 0, 1); PG8_SCHED; PG8_LDA(At, 0, 0); PG8_STAGE(PG8_SA(1, 1), a1 + hstep, voffA);
;             PG8_WAIT_V(8); PG8_WAIT_L(0); PG8_BAR; PG8_MMA(0, 0, At, B0); PG8_MMA(0, 1, At, B1); PG8_BAR; PG8_SCHED;
;             PG8_LDA(At, 0, 1); PG8_STAGE(PG8_SB(0, 0), b2, voffB); PG8_STAGE(PG8_SB(0, 1), b2 + hstep, voffB); PG8_STAGE(PG8_SA(0, 0), a2, voffA);
;             PG8_WAIT_V(8); PG8_WAIT_L(0); PG8_BAR; PG8_MMA(1, 0, At, B0); PG8_MMA(1, 1, At, B1); PG8_BAR; PG8_SCHED;
.LBB0_698:
	s_add_u32 s48, s48, 0x80
	s_addc_u32 s49, s49, 0
	s_add_u32 s59, s52, 0x100
	s_addc_u32 vcc_lo, s53, 0
	s_mov_b32 s52, 0
	s_add_i32 vcc_hi, s52, 2
	s_add_u32 s24, s48, 0x80
	s_addc_u32 s25, s49, 0
	s_add_i32 s66, 0, 0x10000
	s_cmp_eq_u32 s79, s52
	s_cselect_b32 s53, s39, s25
	s_cselect_b32 s52, s38, s24
	v_add_u32_e32 v132, s66, v147
	s_cselect_b32 s25, s43, vcc_lo
	s_cselect_b32 s24, s42, s59
	s_add_i32 s29, 0, 0x14000
	ds_read_b128 v[156:159], v132
	ds_read_b128 v[162:165], v132 offset:1024
	ds_read_b128 v[166:169], v132 offset:2048
	ds_read_b128 v[192:195], v132 offset:3072
	v_add_u32_e32 v132, s29, v147
	ds_read_b128 v[196:199], v132
	ds_read_b128 v[200:203], v132 offset:1024
	ds_read_b128 v[204:207], v132 offset:2048
	ds_read_b128 v[208:211], v132 offset:3072
	v_lshl_add_u64 v[170:171], s[48:49], 0, v[152:153]
	s_add_i32 m0, s90, 0xc000
	ds_read_b128 v[212:215], v160
	ds_read_b128 v[216:219], v160 offset:1024
	ds_read_b128 v[220:223], v160 offset:2048
	ds_read_b128 v[224:227], v160 offset:3072
	ds_read_b128 v[228:231], v160 offset:4096
	ds_read_b128 v[232:235], v160 offset:5120
	ds_read_b128 v[236:239], v160 offset:6144
	ds_read_b128 v[240:243], v160 offset:7168
	global_load_lds_dwordx4 v[170:171], off
	v_lshl_add_u64 v[170:171], s[48:49], 0, v[154:155]
	s_add_i32 m0, s90, 0xe000
	s_nop 0
	global_load_lds_dwordx4 v[170:171], off
	s_waitcnt vmcnt(8)
	s_waitcnt lgkmcnt(0)
	s_barrier
	s_setprio 1
	v_mfma_f32_16x16x32_bf16 v[124:127], v[156:159], v[212:215], 0
	v_mfma_f32_16x16x32_bf16 v[120:123], v[166:169], v[212:215], 0
	v_mfma_f32_16x16x32_bf16 v[108:111], v[156:159], v[220:223], 0
	v_mfma_f32_16x16x32_bf16 v[104:107], v[166:169], v[220:223], 0
	v_mfma_f32_16x16x32_bf16 v[92:95], v[156:159], v[228:231], 0
	v_mfma_f32_16x16x32_bf16 v[88:91], v[166:169], v[228:231], 0
	v_mfma_f32_16x16x32_bf16 v[76:79], v[156:159], v[236:239], 0
	v_mfma_f32_16x16x32_bf16 v[72:75], v[166:169], v[236:239], 0
	v_mfma_f32_16x16x32_bf16 v[124:127], v[162:165], v[216:219], v[124:127]
	v_mfma_f32_16x16x32_bf16 v[120:123], v[192:195], v[216:219], v[120:123]
	v_mfma_f32_16x16x32_bf16 v[108:111], v[162:165], v[224:227], v[108:111]
	v_mfma_f32_16x16x32_bf16 v[104:107], v[192:195], v[224:227], v[104:107]
	v_mfma_f32_16x16x32_bf16 v[92:95], v[162:165], v[232:235], v[92:95]
	v_mfma_f32_16x16x32_bf16 v[88:91], v[192:195], v[232:235], v[88:91]
	v_mfma_f32_16x16x32_bf16 v[76:79], v[162:165], v[240:243], v[76:79]
	v_mfma_f32_16x16x32_bf16 v[72:75], v[192:195], v[240:243], v[72:75]
	v_mfma_f32_16x16x32_bf16 v[116:119], v[196:199], v[212:215], 0
	v_mfma_f32_16x16x32_bf16 v[112:115], v[204:207], v[212:215], 0
	v_mfma_f32_16x16x32_bf16 v[100:103], v[196:199], v[220:223], 0
	v_mfma_f32_16x16x32_bf16 v[96:99], v[204:207], v[220:223], 0
	v_mfma_f32_16x16x32_bf16 v[84:87], v[196:199], v[228:231], 0
	v_mfma_f32_16x16x32_bf16 v[80:83], v[204:207], v[228:231], 0
	v_mfma_f32_16x16x32_bf16 v[68:71], v[196:199], v[236:239], 0
	v_mfma_f32_16x16x32_bf16 v[64:67], v[204:207], v[236:239], 0
	v_mfma_f32_16x16x32_bf16 v[116:119], v[200:203], v[216:219], v[116:119]
	v_mfma_f32_16x16x32_bf16 v[112:115], v[208:211], v[216:219], v[112:115]
	v_mfma_f32_16x16x32_bf16 v[100:103], v[200:203], v[224:227], v[100:103]
	v_mfma_f32_16x16x32_bf16 v[96:99], v[208:211], v[224:227], v[96:99]
	v_mfma_f32_16x16x32_bf16 v[84:87], v[200:203], v[232:235], v[84:87]
	v_mfma_f32_16x16x32_bf16 v[80:83], v[208:211], v[232:235], v[80:83]
	v_mfma_f32_16x16x32_bf16 v[68:71], v[200:203], v[240:243], v[68:71]
	v_mfma_f32_16x16x32_bf16 v[64:67], v[208:211], v[240:243], v[64:67]
	s_setprio 0
	s_barrier
	s_add_i32 s66, s66, s89
	v_lshl_add_u64 v[170:171], s[24:25], 0, v[130:131]
	s_mov_b32 m0, s66
	ds_read_b128 v[212:215], v160 offset:16384
	ds_read_b128 v[216:219], v160 offset:17408
	ds_read_b128 v[220:223], v160 offset:18432
	ds_read_b128 v[224:227], v160 offset:19456
	ds_read_b128 v[228:231], v160 offset:20480
	ds_read_b128 v[232:235], v160 offset:21504
	ds_read_b128 v[236:239], v160 offset:22528
	ds_read_b128 v[240:243], v160 offset:23552
	global_load_lds_dwordx4 v[170:171], off
	s_add_i32 m0, s66, 0x2000
	v_lshl_add_u64 v[244:245], s[24:25], 0, v[142:143]
	s_add_u32 s24, s24, s10
	s_addc_u32 s25, s25, 0
	s_add_i32 s29, s29, s89
	global_load_lds_dwordx4 v[244:245], off
	v_lshl_add_u64 v[246:247], s[24:25], 0, v[130:131]
	s_mov_b32 m0, s29
	v_lshl_add_u64 v[248:249], s[24:25], 0, v[142:143]
	global_load_lds_dwordx4 v[246:247], off
	s_add_i32 m0, s29, 0x2000
	v_lshl_add_u64 v[250:251], s[52:53], 0, v[128:129]
	global_load_lds_dwordx4 v[248:249], off
	s_mov_b32 m0, s90
	v_lshl_add_u64 v[252:253], s[52:53], 0, v[140:141]
	global_load_lds_dwordx4 v[250:251], off
	s_mov_b32 m0, s91
	s_nop 0
	global_load_lds_dwordx4 v[252:253], off
	s_waitcnt vmcnt(8)
	s_waitcnt lgkmcnt(0)
	s_barrier
; #define PG8_STAGE(bufoff, gbase, voff) do { _Pragma("unroll") for (int _i = 0; _i < 2; ++_i) \
;         __builtin_amdgcn_global_load_lds((const unsigned*)((const char*)(gbase) + (voff)[_i]), (PG8_LAS unsigned*)(lds + (bufoff) + ldsw + _i * 8192), 16, 0, 0); } while (0)
; #define PG8_LDA(dst, b, h) do { _Pragma("unroll") for (int m = 0; m < 4; ++m) _Pragma("unroll") for (int k = 0; k < 2; ++k) dst[m][k] = *(const PG8_LAS bf16x8*)(lds + PG8_SA(b, h) + aoff + m * 2048 + k * 1024); } while (0)
; #define PG8_LDB(dst, b, h) do { _Pragma("unroll") for (int n = 0; n < 2; ++n) _Pragma("unroll") for (int k = 0; k < 2; ++k) dst[n][k] = *(const PG8_LAS bf16x8*)(lds + PG8_SB(b, h) + boff + n * 2048 + k * 1024); } while (0)
; #define PG8_MMA(ai, bj, At, Bt) do { __builtin_amdgcn_s_setprio(1); _Pragma("unroll") for (int m = 0; m < 4; ++m) _Pragma("unroll") for (int n = 0; n < 2; ++n) _Pragma("unroll") for (int k = 0; k < 2; ++k) \
;         acc[ai][bj][m][n] = __builtin_amdgcn_mfma_f32_16x16x32_bf16(Bt[n][k], At[m][k], acc[ai][bj][m][n], 0, 0, 0); __builtin_amdgcn_s_setprio(0); } while (0)
; #define PG8_WAIT_V(n) asm volatile("s_waitcnt vmcnt(" #n ")" ::: "memory")
; #define PG8_WAIT_L(n) asm volatile("s_waitcnt lgkmcnt(" #n ")" ::: "memory")
; #define PG8_BAR __builtin_amdgcn_s_barrier()
; #define PG8_SCHED __builtin_amdgcn_sched_barrier(0)
; template <class Epi, class Sched, bool ALIGN_EPI = false, bool SP2 = false>
; __device__ __forceinline__ void gemm_phase(PG8_LAS unsigned char* lds, const Gemm g, const Sched& S, const Epi& E) {
;     ...
;             PG8_WAIT_V(8); PG8_WAIT_L(0); PG8_BAR; PG8_MMA(1, 0, At, B0); PG8_MMA(1, 1, At, B1); PG8_BAR; PG8_SCHED;
;             PG8_LDB(B0, 1, 0); PG8_LDB(B1, 1, 1); PG8_SCHED; PG8_LDA(At, 1, 0); PG8_STAGE(PG8_SA(0, 1), a2 + hstep, voffA);
;             PG8_WAIT_V(8); PG8_WAIT_L(0); PG8_BAR; PG8_MMA(0, 0, At, B0); PG8_MMA(0, 1, At, B1); PG8_BAR; PG8_SCHED;
	s_setprio 1
	v_mfma_f32_16x16x32_bf16 v[60:63], v[156:159], v[212:215], 0
	v_mfma_f32_16x16x32_bf16 v[56:59], v[166:169], v[212:215], 0
	v_mfma_f32_16x16x32_bf16 v[44:47], v[156:159], v[220:223], 0
	v_mfma_f32_16x16x32_bf16 v[40:43], v[166:169], v[220:223], 0
	v_mfma_f32_16x16x32_bf16 v[28:31], v[156:159], v[228:231], 0
	v_mfma_f32_16x16x32_bf16 v[24:27], v[166:169], v[228:231], 0
	v_mfma_f32_16x16x32_bf16 v[12:15], v[156:159], v[236:239], 0
	v_mfma_f32_16x16x32_bf16 v[8:11], v[166:169], v[236:239], 0
	v_mfma_f32_16x16x32_bf16 v[60:63], v[162:165], v[216:219], v[60:63]
	v_mfma_f32_16x16x32_bf16 v[56:59], v[192:195], v[216:219], v[56:59]
	v_mfma_f32_16x16x32_bf16 v[44:47], v[162:165], v[224:227], v[44:47]
	v_mfma_f32_16x16x32_bf16 v[40:43], v[192:195], v[224:227], v[40:43]
	v_mfma_f32_16x16x32_bf16 v[28:31], v[162:165], v[232:235], v[28:31]
	v_mfma_f32_16x16x32_bf16 v[24:27], v[192:195], v[232:235], v[24:27]
	v_mfma_f32_16x16x32_bf16 v[12:15], v[162:165], v[240:243], v[12:15]
	v_mfma_f32_16x16x32_bf16 v[8:11], v[192:195], v[240:243], v[8:11]
	v_mfma_f32_16x16x32_bf16 v[52:55], v[196:199], v[212:215], 0
	v_mfma_f32_16x16x32_bf16 v[48:51], v[204:207], v[212:215], 0
	v_mfma_f32_16x16x32_bf16 v[36:39], v[196:199], v[220:223], 0
	v_mfma_f32_16x16x32_bf16 v[32:35], v[204:207], v[220:223], 0
	v_mfma_f32_16x16x32_bf16 v[20:23], v[196:199], v[228:231], 0
	v_mfma_f32_16x16x32_bf16 v[16:19], v[204:207], v[228:231], 0
	v_mfma_f32_16x16x32_bf16 v[4:7], v[196:199], v[236:239], 0
	v_mfma_f32_16x16x32_bf16 v[0:3], v[204:207], v[236:239], 0
	v_mfma_f32_16x16x32_bf16 v[52:55], v[200:203], v[216:219], v[52:55]
	v_mfma_f32_16x16x32_bf16 v[48:51], v[208:211], v[216:219], v[48:51]
	v_mfma_f32_16x16x32_bf16 v[36:39], v[200:203], v[224:227], v[36:39]
	v_mfma_f32_16x16x32_bf16 v[32:35], v[208:211], v[224:227], v[32:35]
	v_mfma_f32_16x16x32_bf16 v[20:23], v[200:203], v[232:235], v[20:23]
	v_mfma_f32_16x16x32_bf16 v[16:19], v[208:211], v[232:235], v[16:19]
	v_mfma_f32_16x16x32_bf16 v[4:7], v[200:203], v[240:243], v[4:7]
	v_mfma_f32_16x16x32_bf16 v[0:3], v[208:211], v[240:243], v[0:3]
	s_setprio 0
	s_barrier
	s_add_i32 s29, 0, 0x18000
	v_add_u32_e32 v132, s29, v147
	s_add_i32 s66, 0, 0x1c000
	ds_read_b128 v[156:159], v132
	ds_read_b128 v[162:165], v132 offset:1024
	ds_read_b128 v[166:169], v132 offset:2048
	ds_read_b128 v[192:195], v132 offset:3072
	v_add_u32_e32 v132, s66, v147
	ds_read_b128 v[196:199], v132
	ds_read_b128 v[200:203], v132 offset:1024
	ds_read_b128 v[204:207], v132 offset:2048
	ds_read_b128 v[208:211], v132 offset:3072
	s_add_u32 s24, s52, s10
	s_addc_u32 s25, s53, 0
	s_mov_b32 m0, s92
	v_lshl_add_u64 v[184:185], s[24:25], 0, v[128:129]
	ds_read_b128 v[212:215], v160 offset:32768
	ds_read_b128 v[216:219], v160 offset:33792
	ds_read_b128 v[220:223], v160 offset:34816
	ds_read_b128 v[224:227], v160 offset:35840
	ds_read_b128 v[228:231], v160 offset:36864
	ds_read_b128 v[232:235], v160 offset:37888
	ds_read_b128 v[236:239], v160 offset:38912
	ds_read_b128 v[240:243], v160 offset:39936
	global_load_lds_dwordx4 v[184:185], off
	v_lshl_add_u64 v[184:185], s[24:25], 0, v[140:141]
	s_mov_b32 m0, s93
	s_nop 0
	global_load_lds_dwordx4 v[184:185], off
	s_waitcnt vmcnt(8)
	s_waitcnt lgkmcnt(0)
	s_barrier
	s_setprio 1
	v_mfma_f32_16x16x32_bf16 v[124:127], v[156:159], v[212:215], v[124:127]
	v_mfma_f32_16x16x32_bf16 v[120:123], v[166:169], v[212:215], v[120:123]
	v_mfma_f32_16x16x32_bf16 v[108:111], v[156:159], v[220:223], v[108:111]
	v_mfma_f32_16x16x32_bf16 v[104:107], v[166:169], v[220:223], v[104:107]
	v_mfma_f32_16x16x32_bf16 v[92:95], v[156:159], v[228:231], v[92:95]
	v_mfma_f32_16x16x32_bf16 v[88:91], v[166:169], v[228:231], v[88:91]
	v_mfma_f32_16x16x32_bf16 v[76:79], v[156:159], v[236:239], v[76:79]
	v_mfma_f32_16x16x32_bf16 v[72:75], v[166:169], v[236:239], v[72:75]
	v_mfma_f32_16x16x32_bf16 v[124:127], v[162:165], v[216:219], v[124:127]
	v_mfma_f32_16x16x32_bf16 v[120:123], v[192:195], v[216:219], v[120:123]
	v_mfma_f32_16x16x32_bf16 v[108:111], v[162:165], v[224:227], v[108:111]
	v_mfma_f32_16x16x32_bf16 v[104:107], v[192:195], v[224:227], v[104:107]
	v_mfma_f32_16x16x32_bf16 v[92:95], v[162:165], v[232:235], v[92:95]
	v_mfma_f32_16x16x32_bf16 v[88:91], v[192:195], v[232:235], v[88:91]
	v_mfma_f32_16x16x32_bf16 v[76:79], v[162:165], v[240:243], v[76:79]
	v_mfma_f32_16x16x32_bf16 v[72:75], v[192:195], v[240:243], v[72:75]
	v_mfma_f32_16x16x32_bf16 v[116:119], v[196:199], v[212:215], v[116:119]
	v_mfma_f32_16x16x32_bf16 v[112:115], v[204:207], v[212:215], v[112:115]
	v_mfma_f32_16x16x32_bf16 v[100:103], v[196:199], v[220:223], v[100:103]
	v_mfma_f32_16x16x32_bf16 v[96:99], v[204:207], v[220:223], v[96:99]
	v_mfma_f32_16x16x32_bf16 v[84:87], v[196:199], v[228:231], v[84:87]
	v_mfma_f32_16x16x32_bf16 v[80:83], v[204:207], v[228:231], v[80:83]
	v_mfma_f32_16x16x32_bf16 v[68:71], v[196:199], v[236:239], v[68:71]
	v_mfma_f32_16x16x32_bf16 v[64:67], v[204:207], v[236:239], v[64:67]
	v_mfma_f32_16x16x32_bf16 v[116:119], v[200:203], v[216:219], v[116:119]
	v_mfma_f32_16x16x32_bf16 v[112:115], v[208:211], v[216:219], v[112:115]
	v_mfma_f32_16x16x32_bf16 v[100:103], v[200:203], v[224:227], v[100:103]
	v_mfma_f32_16x16x32_bf16 v[96:99], v[208:211], v[224:227], v[96:99]
	v_mfma_f32_16x16x32_bf16 v[84:87], v[200:203], v[232:235], v[84:87]
	v_mfma_f32_16x16x32_bf16 v[80:83], v[208:211], v[232:235], v[80:83]
	v_mfma_f32_16x16x32_bf16 v[68:71], v[200:203], v[240:243], v[68:71]
	v_mfma_f32_16x16x32_bf16 v[64:67], v[208:211], v[240:243], v[64:67]
	s_setprio 0
	s_barrier
; #define PG8_STAGE(bufoff, gbase, voff) do { _Pragma("unroll") for (int _i = 0; _i < 2; ++_i) \
;         __builtin_amdgcn_global_load_lds((const unsigned*)((const char*)(gbase) + (voff)[_i]), (PG8_LAS unsigned*)(lds + (bufoff) + ldsw + _i * 8192), 16, 0, 0); } while (0)
; #define PG8_LDA(dst, b, h) do { _Pragma("unroll") for (int m = 0; m < 4; ++m) _Pragma("unroll") for (int k = 0; k < 2; ++k) dst[m][k] = *(const PG8_LAS bf16x8*)(lds + PG8_SA(b, h) + aoff + m * 2048 + k * 1024); } while (0)
; #define PG8_LDB(dst, b, h) do { _Pragma("unroll") for (int n = 0; n < 2; ++n) _Pragma("unroll") for (int k = 0; k < 2; ++k) dst[n][k] = *(const PG8_LAS bf16x8*)(lds + PG8_SB(b, h) + boff + n * 2048 + k * 1024); } while (0)
; #define PG8_MMA(ai, bj, At, Bt) do { __builtin_amdgcn_s_setprio(1); _Pragma("unroll") for (int m = 0; m < 4; ++m) _Pragma("unroll") for (int n = 0; n < 2; ++n) _Pragma("unroll") for (int k = 0; k < 2; ++k) \
;         acc[ai][bj][m][n] = __builtin_amdgcn_mfma_f32_16x16x32_bf16(Bt[n][k], At[m][k], acc[ai][bj][m][n], 0, 0, 0); __builtin_amdgcn_s_setprio(0); } while (0)
; #define PG8_WAIT_V(n) asm volatile("s_waitcnt vmcnt(" #n ")" ::: "memory")
; #define PG8_BAR __builtin_amdgcn_s_barrier()
; template <class Epi, class Sched, bool ALIGN_EPI = false, bool SP2 = false>
; __device__ __forceinline__ void gemm_phase(PG8_LAS unsigned char* lds, const Gemm g, const Sched& S, const Epi& E) {
;     ...
;         for (int t = 0; t < nt; t += 2) {
;             const bool last = (t == nt - 2);
;             const char* a1 = cA + (size_t)(t + 1) * kstep;
;             const char* a2 = last ? nA : cA + (size_t)(t + 2) * kstep; const char* b2 = last ? nB : cB + (size_t)(t + 2) * kstep;
;             const char* a3 = a2 + kstep; const char* b3 = b2 + kstep;
;             if (last && has_next) S.a_ready(nxt);
;             if constexpr (SP2) {
;             PG8_LDB(B0, 0, 0); PG8_LDB(B1, 0, 1); PG8_SCHED; PG8_LDA(At, 0, 0); PG8_STAGE(PG8_SA(1, 1), a1 + hstep, voffA);
;             PG8_WAIT_V(8); PG8_WAIT_L(0); PG8_BAR; PG8_MMA(0, 0, At, B0); PG8_MMA(0, 1, At, B1); PG8_BAR; PG8_SCHED;
;     ...
;             PG8_LDA(At, 1, 1); PG8_STAGE(PG8_SB(1, 0), b3, voffB); PG8_STAGE(PG8_SB(1, 1), b3 + hstep, voffB); PG8_STAGE(PG8_SA(1, 0), a3, voffA);
;             PG8_WAIT_V(8); PG8_WAIT_L(0); PG8_BAR; PG8_MMA(1, 0, At, B0); PG8_MMA(1, 1, At, B1); PG8_BAR; PG8_SCHED;
	s_add_i32 s24, s29, s89
	v_lshl_add_u64 v[170:171], v[170:171], 0, s[14:15]
	s_mov_b32 m0, s24
	ds_read_b128 v[212:215], v160 offset:49152
	ds_read_b128 v[216:219], v160 offset:50176
	ds_read_b128 v[220:223], v160 offset:51200
	ds_read_b128 v[224:227], v160 offset:52224
	ds_read_b128 v[228:231], v160 offset:53248
	ds_read_b128 v[232:235], v160 offset:54272
	ds_read_b128 v[236:239], v160 offset:55296
	ds_read_b128 v[240:243], v160 offset:56320
	global_load_lds_dwordx4 v[170:171], off
	v_lshl_add_u64 v[170:171], v[244:245], 0, s[14:15]
	s_add_i32 m0, s24, 0x2000
	s_add_i32 s24, s66, s89
	global_load_lds_dwordx4 v[170:171], off
	v_lshl_add_u64 v[170:171], v[246:247], 0, s[14:15]
	s_mov_b32 m0, s24
	s_nop 0
	global_load_lds_dwordx4 v[170:171], off
	v_lshl_add_u64 v[170:171], v[248:249], 0, s[14:15]
	s_add_i32 m0, s24, 0x2000
	s_nop 0
	global_load_lds_dwordx4 v[170:171], off
	v_lshl_add_u64 v[170:171], v[250:251], 0, s[14:15]
	s_mov_b32 m0, s96
	s_nop 0
	global_load_lds_dwordx4 v[170:171], off
	v_lshl_add_u64 v[170:171], v[252:253], 0, s[14:15]
	s_mov_b32 m0, s97
	s_nop 0
	global_load_lds_dwordx4 v[170:171], off
	s_waitcnt vmcnt(8)
	s_waitcnt lgkmcnt(0)
	s_barrier
	s_setprio 1
	v_mfma_f32_16x16x32_bf16 v[60:63], v[156:159], v[212:215], v[60:63]
	v_mfma_f32_16x16x32_bf16 v[56:59], v[166:169], v[212:215], v[56:59]
	v_mfma_f32_16x16x32_bf16 v[44:47], v[156:159], v[220:223], v[44:47]
	v_mfma_f32_16x16x32_bf16 v[40:43], v[166:169], v[220:223], v[40:43]
	v_mfma_f32_16x16x32_bf16 v[28:31], v[156:159], v[228:231], v[28:31]
	v_mfma_f32_16x16x32_bf16 v[24:27], v[166:169], v[228:231], v[24:27]
	v_mfma_f32_16x16x32_bf16 v[12:15], v[156:159], v[236:239], v[12:15]
	v_mfma_f32_16x16x32_bf16 v[8:11], v[166:169], v[236:239], v[8:11]
	v_mfma_f32_16x16x32_bf16 v[60:63], v[162:165], v[216:219], v[60:63]
	v_mfma_f32_16x16x32_bf16 v[56:59], v[192:195], v[216:219], v[56:59]
	v_mfma_f32_16x16x32_bf16 v[44:47], v[162:165], v[224:227], v[44:47]
	v_mfma_f32_16x16x32_bf16 v[40:43], v[192:195], v[224:227], v[40:43]
	v_mfma_f32_16x16x32_bf16 v[28:31], v[162:165], v[232:235], v[28:31]
	v_mfma_f32_16x16x32_bf16 v[24:27], v[192:195], v[232:235], v[24:27]
	v_mfma_f32_16x16x32_bf16 v[12:15], v[162:165], v[240:243], v[12:15]
	v_mfma_f32_16x16x32_bf16 v[8:11], v[192:195], v[240:243], v[8:11]
	v_mfma_f32_16x16x32_bf16 v[52:55], v[196:199], v[212:215], v[52:55]
	v_mfma_f32_16x16x32_bf16 v[48:51], v[204:207], v[212:215], v[48:51]
	v_mfma_f32_16x16x32_bf16 v[36:39], v[196:199], v[220:223], v[36:39]
	v_mfma_f32_16x16x32_bf16 v[32:35], v[204:207], v[220:223], v[32:35]
	v_mfma_f32_16x16x32_bf16 v[20:23], v[196:199], v[228:231], v[20:23]
	v_mfma_f32_16x16x32_bf16 v[16:19], v[204:207], v[228:231], v[16:19]
	v_mfma_f32_16x16x32_bf16 v[4:7], v[196:199], v[236:239], v[4:7]
	v_mfma_f32_16x16x32_bf16 v[0:3], v[204:207], v[236:239], v[0:3]
	v_mfma_f32_16x16x32_bf16 v[52:55], v[200:203], v[216:219], v[52:55]
	v_mfma_f32_16x16x32_bf16 v[48:51], v[208:211], v[216:219], v[48:51]
	v_mfma_f32_16x16x32_bf16 v[36:39], v[200:203], v[224:227], v[36:39]
	v_mfma_f32_16x16x32_bf16 v[32:35], v[208:211], v[224:227], v[32:35]
	v_mfma_f32_16x16x32_bf16 v[20:23], v[200:203], v[232:235], v[20:23]
	v_mfma_f32_16x16x32_bf16 v[16:19], v[208:211], v[232:235], v[16:19]
	v_mfma_f32_16x16x32_bf16 v[4:7], v[200:203], v[240:243], v[4:7]
	v_mfma_f32_16x16x32_bf16 v[0:3], v[208:211], v[240:243], v[0:3]
	s_setprio 0
	s_barrier
	s_add_u32 s48, s48, 0x100
	s_addc_u32 s49, s49, 0
	s_add_u32 s59, s59, 0x100
	s_addc_u32 vcc_lo, vcc_lo, 0
	s_cmp_ge_u32 vcc_hi, s78
	s_mov_b32 s52, vcc_hi
.LBB0_699:
	s_add_i32 vcc_hi, s52, 2
	s_add_u32 s24, s48, 0x80
	s_addc_u32 s25, s49, 0
	s_add_i32 s66, 0, 0x10000
	s_cmp_eq_u32 s79, s52
	s_cselect_b32 s53, s39, s25
	s_cselect_b32 s52, s38, s24
	v_add_u32_e32 v132, s66, v147
	s_cselect_b32 s25, s43, vcc_lo
	s_cselect_b32 s24, s42, s59
	s_add_i32 s29, 0, 0x14000
	ds_read_b128 v[156:159], v132
	ds_read_b128 v[162:165], v132 offset:1024
	ds_read_b128 v[166:169], v132 offset:2048
	ds_read_b128 v[192:195], v132 offset:3072
	v_add_u32_e32 v132, s29, v147
	ds_read_b128 v[196:199], v132
	ds_read_b128 v[200:203], v132 offset:1024
	ds_read_b128 v[204:207], v132 offset:2048
	ds_read_b128 v[208:211], v132 offset:3072
	v_lshl_add_u64 v[170:171], s[48:49], 0, v[152:153]
	s_add_i32 m0, s90, 0xc000
	ds_read_b128 v[212:215], v160
	ds_read_b128 v[216:219], v160 offset:1024
	ds_read_b128 v[220:223], v160 offset:2048
	ds_read_b128 v[224:227], v160 offset:3072
	ds_read_b128 v[228:231], v160 offset:4096
	ds_read_b128 v[232:235], v160 offset:5120
	ds_read_b128 v[236:239], v160 offset:6144
	ds_read_b128 v[240:243], v160 offset:7168
	global_load_lds_dwordx4 v[170:171], off
	v_lshl_add_u64 v[170:171], s[48:49], 0, v[154:155]
	s_add_i32 m0, s90, 0xe000
	s_nop 0
	global_load_lds_dwordx4 v[170:171], off
	s_waitcnt vmcnt(8)
	s_waitcnt lgkmcnt(0)
	s_barrier
; #define PG8_STAGE(bufoff, gbase, voff) do { _Pragma("unroll") for (int _i = 0; _i < 2; ++_i) \
;         __builtin_amdgcn_global_load_lds((const unsigned*)((const char*)(gbase) + (voff)[_i]), (PG8_LAS unsigned*)(lds + (bufoff) + ldsw + _i * 8192), 16, 0, 0); } while (0)
; #define PG8_LDA(dst, b, h) do { _Pragma("unroll") for (int m = 0; m < 4; ++m) _Pragma("unroll") for (int k = 0; k < 2; ++k) dst[m][k] = *(const PG8_LAS bf16x8*)(lds + PG8_SA(b, h) + aoff + m * 2048 + k * 1024); } while (0)
; #define PG8_MMA(ai, bj, At, Bt) do { __builtin_amdgcn_s_setprio(1); _Pragma("unroll") for (int m = 0; m < 4; ++m) _Pragma("unroll") for (int n = 0; n < 2; ++n) _Pragma("unroll") for (int k = 0; k < 2; ++k) \
;         acc[ai][bj][m][n] = __builtin_amdgcn_mfma_f32_16x16x32_bf16(Bt[n][k], At[m][k], acc[ai][bj][m][n], 0, 0, 0); __builtin_amdgcn_s_setprio(0); } while (0)
; #define PG8_WAIT_V(n) asm volatile("s_waitcnt vmcnt(" #n ")" ::: "memory")
; #define PG8_WAIT_L(n) asm volatile("s_waitcnt lgkmcnt(" #n ")" ::: "memory")
; #define PG8_BAR __builtin_amdgcn_s_barrier()
; #define PG8_SCHED __builtin_amdgcn_sched_barrier(0)
; template <class Epi, class Sched, bool ALIGN_EPI = false, bool SP2 = false>
; __device__ __forceinline__ void gemm_phase(PG8_LAS unsigned char* lds, const Gemm g, const Sched& S, const Epi& E) {
;     ...
;             PG8_WAIT_V(8); PG8_WAIT_L(0); PG8_BAR; PG8_MMA(0, 0, At, B0); PG8_MMA(0, 1, At, B1); PG8_BAR; PG8_SCHED;
;             PG8_LDA(At, 0, 1); PG8_STAGE(PG8_SB(0, 0), b2, voffB); PG8_STAGE(PG8_SB(0, 1), b2 + hstep, voffB); PG8_STAGE(PG8_SA(0, 0), a2, voffA);
;             PG8_WAIT_V(8); PG8_WAIT_L(0); PG8_BAR; PG8_MMA(1, 0, At, B0); PG8_MMA(1, 1, At, B1); PG8_BAR; PG8_SCHED;
	s_setprio 1
	v_mfma_f32_16x16x32_bf16 v[124:127], v[156:159], v[212:215], v[124:127]
	v_mfma_f32_16x16x32_bf16 v[120:123], v[166:169], v[212:215], v[120:123]
	v_mfma_f32_16x16x32_bf16 v[108:111], v[156:159], v[220:223], v[108:111]
	v_mfma_f32_16x16x32_bf16 v[104:107], v[166:169], v[220:223], v[104:107]
	v_mfma_f32_16x16x32_bf16 v[92:95], v[156:159], v[228:231], v[92:95]
	v_mfma_f32_16x16x32_bf16 v[88:91], v[166:169], v[228:231], v[88:91]
	v_mfma_f32_16x16x32_bf16 v[76:79], v[156:159], v[236:239], v[76:79]
	v_mfma_f32_16x16x32_bf16 v[72:75], v[166:169], v[236:239], v[72:75]
	v_mfma_f32_16x16x32_bf16 v[124:127], v[162:165], v[216:219], v[124:127]
	v_mfma_f32_16x16x32_bf16 v[120:123], v[192:195], v[216:219], v[120:123]
	v_mfma_f32_16x16x32_bf16 v[108:111], v[162:165], v[224:227], v[108:111]
	v_mfma_f32_16x16x32_bf16 v[104:107], v[192:195], v[224:227], v[104:107]
	v_mfma_f32_16x16x32_bf16 v[92:95], v[162:165], v[232:235], v[92:95]
	v_mfma_f32_16x16x32_bf16 v[88:91], v[192:195], v[232:235], v[88:91]
	v_mfma_f32_16x16x32_bf16 v[76:79], v[162:165], v[240:243], v[76:79]
	v_mfma_f32_16x16x32_bf16 v[72:75], v[192:195], v[240:243], v[72:75]
	v_mfma_f32_16x16x32_bf16 v[116:119], v[196:199], v[212:215], v[116:119]
	v_mfma_f32_16x16x32_bf16 v[112:115], v[204:207], v[212:215], v[112:115]
	v_mfma_f32_16x16x32_bf16 v[100:103], v[196:199], v[220:223], v[100:103]
	v_mfma_f32_16x16x32_bf16 v[96:99], v[204:207], v[220:223], v[96:99]
	v_mfma_f32_16x16x32_bf16 v[84:87], v[196:199], v[228:231], v[84:87]
	v_mfma_f32_16x16x32_bf16 v[80:83], v[204:207], v[228:231], v[80:83]
	v_mfma_f32_16x16x32_bf16 v[68:71], v[196:199], v[236:239], v[68:71]
	v_mfma_f32_16x16x32_bf16 v[64:67], v[204:207], v[236:239], v[64:67]
	v_mfma_f32_16x16x32_bf16 v[116:119], v[200:203], v[216:219], v[116:119]
	v_mfma_f32_16x16x32_bf16 v[112:115], v[208:211], v[216:219], v[112:115]
	v_mfma_f32_16x16x32_bf16 v[100:103], v[200:203], v[224:227], v[100:103]
	v_mfma_f32_16x16x32_bf16 v[96:99], v[208:211], v[224:227], v[96:99]
	v_mfma_f32_16x16x32_bf16 v[84:87], v[200:203], v[232:235], v[84:87]
	v_mfma_f32_16x16x32_bf16 v[80:83], v[208:211], v[232:235], v[80:83]
	v_mfma_f32_16x16x32_bf16 v[68:71], v[200:203], v[240:243], v[68:71]
	v_mfma_f32_16x16x32_bf16 v[64:67], v[208:211], v[240:243], v[64:67]
	s_setprio 0
	s_barrier
	s_add_i32 s66, s66, s89
	v_lshl_add_u64 v[170:171], s[24:25], 0, v[130:131]
	s_mov_b32 m0, s66
	ds_read_b128 v[212:215], v160 offset:16384
	ds_read_b128 v[216:219], v160 offset:17408
	ds_read_b128 v[220:223], v160 offset:18432
	ds_read_b128 v[224:227], v160 offset:19456
	ds_read_b128 v[228:231], v160 offset:20480
	ds_read_b128 v[232:235], v160 offset:21504
	ds_read_b128 v[236:239], v160 offset:22528
	ds_read_b128 v[240:243], v160 offset:23552
	global_load_lds_dwordx4 v[170:171], off
	s_add_i32 m0, s66, 0x2000
	v_lshl_add_u64 v[244:245], s[24:25], 0, v[142:143]
	s_add_u32 s24, s24, s10
	s_addc_u32 s25, s25, 0
	s_add_i32 s29, s29, s89
	global_load_lds_dwordx4 v[244:245], off
	v_lshl_add_u64 v[246:247], s[24:25], 0, v[130:131]
	s_mov_b32 m0, s29
	v_lshl_add_u64 v[248:249], s[24:25], 0, v[142:143]
	global_load_lds_dwordx4 v[246:247], off
	s_add_i32 m0, s29, 0x2000
	v_lshl_add_u64 v[250:251], s[52:53], 0, v[128:129]
	global_load_lds_dwordx4 v[248:249], off
	s_mov_b32 m0, s90
	v_lshl_add_u64 v[252:253], s[52:53], 0, v[140:141]
	global_load_lds_dwordx4 v[250:251], off
	s_mov_b32 m0, s91
	s_nop 0
	global_load_lds_dwordx4 v[252:253], off
	s_waitcnt vmcnt(8)
	s_waitcnt lgkmcnt(0)
	s_barrier
	s_setprio 1
	v_mfma_f32_16x16x32_bf16 v[60:63], v[156:159], v[212:215], v[60:63]
	v_mfma_f32_16x16x32_bf16 v[56:59], v[166:169], v[212:215], v[56:59]
	v_mfma_f32_16x16x32_bf16 v[44:47], v[156:159], v[220:223], v[44:47]
	v_mfma_f32_16x16x32_bf16 v[40:43], v[166:169], v[220:223], v[40:43]
	v_mfma_f32_16x16x32_bf16 v[28:31], v[156:159], v[228:231], v[28:31]
	v_mfma_f32_16x16x32_bf16 v[24:27], v[166:169], v[228:231], v[24:27]
	v_mfma_f32_16x16x32_bf16 v[12:15], v[156:159], v[236:239], v[12:15]
	v_mfma_f32_16x16x32_bf16 v[8:11], v[166:169], v[236:239], v[8:11]
	v_mfma_f32_16x16x32_bf16 v[60:63], v[162:165], v[216:219], v[60:63]
	v_mfma_f32_16x16x32_bf16 v[56:59], v[192:195], v[216:219], v[56:59]
	v_mfma_f32_16x16x32_bf16 v[44:47], v[162:165], v[224:227], v[44:47]
	v_mfma_f32_16x16x32_bf16 v[40:43], v[192:195], v[224:227], v[40:43]
	v_mfma_f32_16x16x32_bf16 v[28:31], v[162:165], v[232:235], v[28:31]
	v_mfma_f32_16x16x32_bf16 v[24:27], v[192:195], v[232:235], v[24:27]
	v_mfma_f32_16x16x32_bf16 v[12:15], v[162:165], v[240:243], v[12:15]
	v_mfma_f32_16x16x32_bf16 v[8:11], v[192:195], v[240:243], v[8:11]
	v_mfma_f32_16x16x32_bf16 v[52:55], v[196:199], v[212:215], v[52:55]
	v_mfma_f32_16x16x32_bf16 v[48:51], v[204:207], v[212:215], v[48:51]
	v_mfma_f32_16x16x32_bf16 v[36:39], v[196:199], v[220:223], v[36:39]
	v_mfma_f32_16x16x32_bf16 v[32:35], v[204:207], v[220:223], v[32:35]
	v_mfma_f32_16x16x32_bf16 v[20:23], v[196:199], v[228:231], v[20:23]
	v_mfma_f32_16x16x32_bf16 v[16:19], v[204:207], v[228:231], v[16:19]
	v_mfma_f32_16x16x32_bf16 v[4:7], v[196:199], v[236:239], v[4:7]
	v_mfma_f32_16x16x32_bf16 v[0:3], v[204:207], v[236:239], v[0:3]
	v_mfma_f32_16x16x32_bf16 v[52:55], v[200:203], v[216:219], v[52:55]
	v_mfma_f32_16x16x32_bf16 v[48:51], v[208:211], v[216:219], v[48:51]
	v_mfma_f32_16x16x32_bf16 v[36:39], v[200:203], v[224:227], v[36:39]
	v_mfma_f32_16x16x32_bf16 v[32:35], v[208:211], v[224:227], v[32:35]
	v_mfma_f32_16x16x32_bf16 v[20:23], v[200:203], v[232:235], v[20:23]
	v_mfma_f32_16x16x32_bf16 v[16:19], v[208:211], v[232:235], v[16:19]
	v_mfma_f32_16x16x32_bf16 v[4:7], v[200:203], v[240:243], v[4:7]
	v_mfma_f32_16x16x32_bf16 v[0:3], v[208:211], v[240:243], v[0:3]
	s_setprio 0
	s_barrier
; #define PG8_STAGE(bufoff, gbase, voff) do { _Pragma("unroll") for (int _i = 0; _i < 2; ++_i) \
;         __builtin_amdgcn_global_load_lds((const unsigned*)((const char*)(gbase) + (voff)[_i]), (PG8_LAS unsigned*)(lds + (bufoff) + ldsw + _i * 8192), 16, 0, 0); } while (0)
; #define PG8_LDA(dst, b, h) do { _Pragma("unroll") for (int m = 0; m < 4; ++m) _Pragma("unroll") for (int k = 0; k < 2; ++k) dst[m][k] = *(const PG8_LAS bf16x8*)(lds + PG8_SA(b, h) + aoff + m * 2048 + k * 1024); } while (0)
; #define PG8_LDB(dst, b, h) do { _Pragma("unroll") for (int n = 0; n < 2; ++n) _Pragma("unroll") for (int k = 0; k < 2; ++k) dst[n][k] = *(const PG8_LAS bf16x8*)(lds + PG8_SB(b, h) + boff + n * 2048 + k * 1024); } while (0)
; #define PG8_MMA(ai, bj, At, Bt) do { __builtin_amdgcn_s_setprio(1); _Pragma("unroll") for (int m = 0; m < 4; ++m) _Pragma("unroll") for (int n = 0; n < 2; ++n) _Pragma("unroll") for (int k = 0; k < 2; ++k) \
;         acc[ai][bj][m][n] = __builtin_amdgcn_mfma_f32_16x16x32_bf16(Bt[n][k], At[m][k], acc[ai][bj][m][n], 0, 0, 0); __builtin_amdgcn_s_setprio(0); } while (0)
; #define PG8_WAIT_V(n) asm volatile("s_waitcnt vmcnt(" #n ")" ::: "memory")
; #define PG8_WAIT_L(n) asm volatile("s_waitcnt lgkmcnt(" #n ")" ::: "memory")
; #define PG8_BAR __builtin_amdgcn_s_barrier()
; #define PG8_SCHED __builtin_amdgcn_sched_barrier(0)
; template <class Epi, class Sched, bool ALIGN_EPI = false, bool SP2 = false>
; __device__ __forceinline__ void gemm_phase(PG8_LAS unsigned char* lds, const Gemm g, const Sched& S, const Epi& E) {
;     ...
;             PG8_LDB(B0, 1, 0); PG8_LDB(B1, 1, 1); PG8_SCHED; PG8_LDA(At, 1, 0); PG8_STAGE(PG8_SA(0, 1), a2 + hstep, voffA);
;             PG8_WAIT_V(8); PG8_WAIT_L(0); PG8_BAR; PG8_MMA(0, 0, At, B0); PG8_MMA(0, 1, At, B1); PG8_BAR; PG8_SCHED;
	s_add_i32 s29, 0, 0x18000
	v_add_u32_e32 v132, s29, v147
	s_add_i32 s66, 0, 0x1c000
	ds_read_b128 v[156:159], v132
	ds_read_b128 v[162:165], v132 offset:1024
	ds_read_b128 v[166:169], v132 offset:2048
	ds_read_b128 v[192:195], v132 offset:3072
	v_add_u32_e32 v132, s66, v147
	ds_read_b128 v[196:199], v132
	ds_read_b128 v[200:203], v132 offset:1024
	ds_read_b128 v[204:207], v132 offset:2048
	ds_read_b128 v[208:211], v132 offset:3072
	s_add_u32 s24, s52, s10
	s_addc_u32 s25, s53, 0
	s_mov_b32 m0, s92
	v_lshl_add_u64 v[184:185], s[24:25], 0, v[128:129]
	ds_read_b128 v[212:215], v160 offset:32768
	ds_read_b128 v[216:219], v160 offset:33792
	ds_read_b128 v[220:223], v160 offset:34816
	ds_read_b128 v[224:227], v160 offset:35840
	ds_read_b128 v[228:231], v160 offset:36864
	ds_read_b128 v[232:235], v160 offset:37888
	ds_read_b128 v[236:239], v160 offset:38912
	ds_read_b128 v[240:243], v160 offset:39936
	global_load_lds_dwordx4 v[184:185], off
	v_lshl_add_u64 v[184:185], s[24:25], 0, v[140:141]
	s_mov_b32 m0, s93
	s_nop 0
	global_load_lds_dwordx4 v[184:185], off
	s_waitcnt vmcnt(8)
	s_waitcnt lgkmcnt(0)
	s_barrier
	s_setprio 1
	v_mfma_f32_16x16x32_bf16 v[124:127], v[156:159], v[212:215], v[124:127]
	v_mfma_f32_16x16x32_bf16 v[120:123], v[166:169], v[212:215], v[120:123]
	v_mfma_f32_16x16x32_bf16 v[108:111], v[156:159], v[220:223], v[108:111]
	v_mfma_f32_16x16x32_bf16 v[104:107], v[166:169], v[220:223], v[104:107]
	v_mfma_f32_16x16x32_bf16 v[92:95], v[156:159], v[228:231], v[92:95]
	v_mfma_f32_16x16x32_bf16 v[88:91], v[166:169], v[228:231], v[88:91]
	v_mfma_f32_16x16x32_bf16 v[76:79], v[156:159], v[236:239], v[76:79]
	v_mfma_f32_16x16x32_bf16 v[72:75], v[166:169], v[236:239], v[72:75]
	v_mfma_f32_16x16x32_bf16 v[124:127], v[162:165], v[216:219], v[124:127]
	v_mfma_f32_16x16x32_bf16 v[120:123], v[192:195], v[216:219], v[120:123]
	v_mfma_f32_16x16x32_bf16 v[108:111], v[162:165], v[224:227], v[108:111]
	v_mfma_f32_16x16x32_bf16 v[104:107], v[192:195], v[224:227], v[104:107]
	v_mfma_f32_16x16x32_bf16 v[92:95], v[162:165], v[232:235], v[92:95]
	v_mfma_f32_16x16x32_bf16 v[88:91], v[192:195], v[232:235], v[88:91]
	v_mfma_f32_16x16x32_bf16 v[76:79], v[162:165], v[240:243], v[76:79]
	v_mfma_f32_16x16x32_bf16 v[72:75], v[192:195], v[240:243], v[72:75]
	v_mfma_f32_16x16x32_bf16 v[116:119], v[196:199], v[212:215], v[116:119]
	v_mfma_f32_16x16x32_bf16 v[112:115], v[204:207], v[212:215], v[112:115]
	v_mfma_f32_16x16x32_bf16 v[100:103], v[196:199], v[220:223], v[100:103]
	v_mfma_f32_16x16x32_bf16 v[96:99], v[204:207], v[220:223], v[96:99]
	v_mfma_f32_16x16x32_bf16 v[84:87], v[196:199], v[228:231], v[84:87]
	v_mfma_f32_16x16x32_bf16 v[80:83], v[204:207], v[228:231], v[80:83]
	v_mfma_f32_16x16x32_bf16 v[68:71], v[196:199], v[236:239], v[68:71]
	v_mfma_f32_16x16x32_bf16 v[64:67], v[204:207], v[236:239], v[64:67]
	v_mfma_f32_16x16x32_bf16 v[116:119], v[200:203], v[216:219], v[116:119]
	v_mfma_f32_16x16x32_bf16 v[112:115], v[208:211], v[216:219], v[112:115]
	v_mfma_f32_16x16x32_bf16 v[100:103], v[200:203], v[224:227], v[100:103]
	v_mfma_f32_16x16x32_bf16 v[96:99], v[208:211], v[224:227], v[96:99]
	v_mfma_f32_16x16x32_bf16 v[84:87], v[200:203], v[232:235], v[84:87]
	v_mfma_f32_16x16x32_bf16 v[80:83], v[208:211], v[232:235], v[80:83]
	v_mfma_f32_16x16x32_bf16 v[68:71], v[200:203], v[240:243], v[68:71]
	v_mfma_f32_16x16x32_bf16 v[64:67], v[208:211], v[240:243], v[64:67]
	s_setprio 0
	s_barrier
; #define PG8_STAGE(bufoff, gbase, voff) do { _Pragma("unroll") for (int _i = 0; _i < 2; ++_i) \
;         __builtin_amdgcn_global_load_lds((const unsigned*)((const char*)(gbase) + (voff)[_i]), (PG8_LAS unsigned*)(lds + (bufoff) + ldsw + _i * 8192), 16, 0, 0); } while (0)
; #define PG8_LDA(dst, b, h) do { _Pragma("unroll") for (int m = 0; m < 4; ++m) _Pragma("unroll") for (int k = 0; k < 2; ++k) dst[m][k] = *(const PG8_LAS bf16x8*)(lds + PG8_SA(b, h) + aoff + m * 2048 + k * 1024); } while (0)
; #define PG8_MMA(ai, bj, At, Bt) do { __builtin_amdgcn_s_setprio(1); _Pragma("unroll") for (int m = 0; m < 4; ++m) _Pragma("unroll") for (int n = 0; n < 2; ++n) _Pragma("unroll") for (int k = 0; k < 2; ++k) \
;         acc[ai][bj][m][n] = __builtin_amdgcn_mfma_f32_16x16x32_bf16(Bt[n][k], At[m][k], acc[ai][bj][m][n], 0, 0, 0); __builtin_amdgcn_s_setprio(0); } while (0)
; #define PG8_WAIT_V(n) asm volatile("s_waitcnt vmcnt(" #n ")" ::: "memory")
; #define PG8_WAIT_L(n) asm volatile("s_waitcnt lgkmcnt(" #n ")" ::: "memory")
; #define PG8_BAR __builtin_amdgcn_s_barrier()
; #define PG8_SCHED __builtin_amdgcn_sched_barrier(0)
; template <class Epi, class Sched, bool ALIGN_EPI = false, bool SP2 = false>
; __device__ __forceinline__ void gemm_phase(PG8_LAS unsigned char* lds, const Gemm g, const Sched& S, const Epi& E) {
;     ...
;         for (int t = 0; t < nt; t += 2) {
;     ...
;             PG8_LDA(At, 1, 1); PG8_STAGE(PG8_SB(1, 0), b3, voffB); PG8_STAGE(PG8_SB(1, 1), b3 + hstep, voffB); PG8_STAGE(PG8_SA(1, 0), a3, voffA);
;             PG8_WAIT_V(8); PG8_WAIT_L(0); PG8_BAR; PG8_MMA(1, 0, At, B0); PG8_MMA(1, 1, At, B1); PG8_BAR; PG8_SCHED;
	s_add_i32 s24, s29, s89
	v_lshl_add_u64 v[170:171], v[170:171], 0, s[14:15]
	s_mov_b32 m0, s24
	ds_read_b128 v[212:215], v160 offset:49152
	ds_read_b128 v[216:219], v160 offset:50176
	ds_read_b128 v[220:223], v160 offset:51200
	ds_read_b128 v[224:227], v160 offset:52224
	ds_read_b128 v[228:231], v160 offset:53248
	ds_read_b128 v[232:235], v160 offset:54272
	ds_read_b128 v[236:239], v160 offset:55296
	ds_read_b128 v[240:243], v160 offset:56320
	global_load_lds_dwordx4 v[170:171], off
	v_lshl_add_u64 v[170:171], v[244:245], 0, s[14:15]
	s_add_i32 m0, s24, 0x2000
	s_add_i32 s24, s66, s89
	global_load_lds_dwordx4 v[170:171], off
	v_lshl_add_u64 v[170:171], v[246:247], 0, s[14:15]
	s_mov_b32 m0, s24
	s_nop 0
	global_load_lds_dwordx4 v[170:171], off
	v_lshl_add_u64 v[170:171], v[248:249], 0, s[14:15]
	s_add_i32 m0, s24, 0x2000
	s_nop 0
	global_load_lds_dwordx4 v[170:171], off
	v_lshl_add_u64 v[170:171], v[250:251], 0, s[14:15]
	s_mov_b32 m0, s96
	s_nop 0
	global_load_lds_dwordx4 v[170:171], off
	v_lshl_add_u64 v[170:171], v[252:253], 0, s[14:15]
	s_mov_b32 m0, s97
	s_nop 0
	global_load_lds_dwordx4 v[170:171], off
	s_waitcnt vmcnt(8)
	s_waitcnt lgkmcnt(0)
	s_barrier
	s_setprio 1
	v_mfma_f32_16x16x32_bf16 v[60:63], v[156:159], v[212:215], v[60:63]
	v_mfma_f32_16x16x32_bf16 v[56:59], v[166:169], v[212:215], v[56:59]
	v_mfma_f32_16x16x32_bf16 v[44:47], v[156:159], v[220:223], v[44:47]
	v_mfma_f32_16x16x32_bf16 v[40:43], v[166:169], v[220:223], v[40:43]
	v_mfma_f32_16x16x32_bf16 v[28:31], v[156:159], v[228:231], v[28:31]
	v_mfma_f32_16x16x32_bf16 v[24:27], v[166:169], v[228:231], v[24:27]
	v_mfma_f32_16x16x32_bf16 v[12:15], v[156:159], v[236:239], v[12:15]
	v_mfma_f32_16x16x32_bf16 v[8:11], v[166:169], v[236:239], v[8:11]
	v_mfma_f32_16x16x32_bf16 v[60:63], v[162:165], v[216:219], v[60:63]
	v_mfma_f32_16x16x32_bf16 v[56:59], v[192:195], v[216:219], v[56:59]
	v_mfma_f32_16x16x32_bf16 v[44:47], v[162:165], v[224:227], v[44:47]
	v_mfma_f32_16x16x32_bf16 v[40:43], v[192:195], v[224:227], v[40:43]
	v_mfma_f32_16x16x32_bf16 v[28:31], v[162:165], v[232:235], v[28:31]
	v_mfma_f32_16x16x32_bf16 v[24:27], v[192:195], v[232:235], v[24:27]
	v_mfma_f32_16x16x32_bf16 v[12:15], v[162:165], v[240:243], v[12:15]
	v_mfma_f32_16x16x32_bf16 v[8:11], v[192:195], v[240:243], v[8:11]
	v_mfma_f32_16x16x32_bf16 v[52:55], v[196:199], v[212:215], v[52:55]
	v_mfma_f32_16x16x32_bf16 v[48:51], v[204:207], v[212:215], v[48:51]
	v_mfma_f32_16x16x32_bf16 v[36:39], v[196:199], v[220:223], v[36:39]
	v_mfma_f32_16x16x32_bf16 v[32:35], v[204:207], v[220:223], v[32:35]
	v_mfma_f32_16x16x32_bf16 v[20:23], v[196:199], v[228:231], v[20:23]
	v_mfma_f32_16x16x32_bf16 v[16:19], v[204:207], v[228:231], v[16:19]
	v_mfma_f32_16x16x32_bf16 v[4:7], v[196:199], v[236:239], v[4:7]
	v_mfma_f32_16x16x32_bf16 v[0:3], v[204:207], v[236:239], v[0:3]
	v_mfma_f32_16x16x32_bf16 v[52:55], v[200:203], v[216:219], v[52:55]
	v_mfma_f32_16x16x32_bf16 v[48:51], v[208:211], v[216:219], v[48:51]
	v_mfma_f32_16x16x32_bf16 v[36:39], v[200:203], v[224:227], v[36:39]
	v_mfma_f32_16x16x32_bf16 v[32:35], v[208:211], v[224:227], v[32:35]
	v_mfma_f32_16x16x32_bf16 v[20:23], v[200:203], v[232:235], v[20:23]
	v_mfma_f32_16x16x32_bf16 v[16:19], v[208:211], v[232:235], v[16:19]
	v_mfma_f32_16x16x32_bf16 v[4:7], v[200:203], v[240:243], v[4:7]
	v_mfma_f32_16x16x32_bf16 v[0:3], v[208:211], v[240:243], v[0:3]
	s_setprio 0
	s_barrier
	s_add_u32 s48, s48, 0x100
	s_addc_u32 s49, s49, 0
	s_add_u32 s59, s59, 0x100
	s_addc_u32 vcc_lo, vcc_lo, 0
	s_cmp_ge_u32 vcc_hi, s78
	s_mov_b32 s52, vcc_hi
	s_cbranch_scc0 .LBB0_699
	s_and_b64 vcc, exec, s[36:37]
	s_cbranch_vccz .LBB0_702
